# combo6 + all global-memory flat loads issued as global_load (no lgkmcnt coupling)
# baseline (speedup 1.0000x reference)
.LBB0_136:
	v_lshl_or_b32 v144, s92, 8, v230
	v_ashrrev_i32_e32 v145, 31, v144
	v_lshl_add_u64 v[132:133], v[144:145], 2, s[26:27]
	global_load_dwordx4 v[136:139], v[132:133], off offset:16
	global_load_dwordx4 v[140:143], v[132:133], off
	global_load_dwordx4 v[128:131], v[132:133], off offset:528
	s_nop 0
	global_load_dwordx4 v[132:135], v[132:133], off offset:512
	v_lshlrev_b64 v[192:193], 1, v[144:145]
	v_ashrrev_i32_e32 v191, 31, v190
	v_lshl_add_u64 v[194:195], s[62:63], 0, v[192:193]
	v_lshlrev_b64 v[144:145], 10, v[190:191]
	v_lshl_add_u64 v[144:145], v[194:195], 0, v[144:145]
	global_load_dwordx4 v[172:175], v[144:145], off
	global_load_dwordx4 v[168:171], v[144:145], off offset:256
	v_or_b32_e32 v200, 16, v190
	v_ashrrev_i32_e32 v201, 31, v200
	v_lshlrev_b64 v[144:145], 10, v[200:201]
	v_lshl_add_u64 v[144:145], v[194:195], 0, v[144:145]
	global_load_dwordx4 v[164:167], v[144:145], off
	global_load_dwordx4 v[160:163], v[144:145], off offset:256
	v_or_b32_e32 v198, 32, v190
	v_ashrrev_i32_e32 v199, 31, v198
	v_lshlrev_b64 v[144:145], 10, v[198:199]
	v_or_b32_e32 v196, 48, v190
	v_mul_lo_u32 v191, s50, v191
	v_lshl_add_u64 v[144:145], v[194:195], 0, v[144:145]
	v_ashrrev_i32_e32 v197, 31, v196
	global_load_dwordx4 v[156:159], v[144:145], off
	global_load_dwordx4 v[152:155], v[144:145], off offset:256
	v_lshlrev_b64 v[144:145], 10, v[196:197]
	v_lshl_add_u64 v[144:145], v[194:195], 0, v[144:145]
	global_load_dwordx4 v[148:151], v[144:145], off
	s_nop 0
	global_load_dwordx4 v[144:147], v[144:145], off offset:256
	s_waitcnt vmcnt(0)
	v_add_f32_e32 v203, v120, v136
	v_mul_f32_e32 v203, 0xbfb8aa3b, v203
	v_exp_f32_e32 v203, v203
	v_add_f32_e32 v202, v124, v140
	v_mul_f32_e32 v202, 0xbfb8aa3b, v202
	v_exp_f32_e32 v202, v202
	v_add_f32_e32 v203, 1.0, v203
	v_rcp_f32_e32 v232, v203
	s_waitcnt lgkmcnt(0)
	v_and_b32_e32 v235, 0xffff0000, v172
	v_lshlrev_b32_e32 v234, 16, v172
	v_add_f32_e32 v172, v121, v137
	v_mul_f32_e32 v172, 0xbfb8aa3b, v172
	v_add_f32_e32 v203, v125, v141
	v_exp_f32_e32 v172, v172
	v_mul_f32_e32 v203, 0xbfb8aa3b, v203
	v_exp_f32_e32 v203, v203
	v_add_f32_e32 v202, 1.0, v202
	v_add_f32_e32 v172, 1.0, v172
	v_rcp_f32_e32 v233, v172
	v_add_f32_e32 v172, v126, v142
	v_add_f32_e32 v203, 1.0, v203
	v_mul_f32_e32 v172, 0xbfb8aa3b, v172
	v_rcp_f32_e32 v202, v202
	v_rcp_f32_e32 v203, v203
	v_exp_f32_e32 v172, v172
	v_and_b32_e32 v237, 0xffff0000, v173
	v_lshlrev_b32_e32 v236, 16, v173
	v_pk_mul_f32 v[202:203], v[202:203], v[234:235]
	v_and_b32_e32 v235, 0xffff0000, v174
	v_lshlrev_b32_e32 v234, 16, v174
	v_add_f32_e32 v172, 1.0, v172
	v_add_f32_e32 v174, v127, v143
	v_pk_mul_f32 v[232:233], v[232:233], v[234:235]
	v_rcp_f32_e32 v234, v172
	v_add_f32_e32 v172, v122, v138
	v_mul_f32_e32 v174, 0xbfb8aa3b, v174
	v_add_f32_e32 v173, v123, v139
	v_mul_f32_e32 v172, 0xbfb8aa3b, v172
	v_exp_f32_e32 v174, v174
	v_mul_f32_e32 v173, 0xbfb8aa3b, v173
	v_exp_f32_e32 v172, v172
	v_exp_f32_e32 v173, v173
	v_add_f32_e32 v174, 1.0, v174
	v_rcp_f32_e32 v235, v174
	v_add_f32_e32 v172, 1.0, v172
	v_add_f32_e32 v173, 1.0, v173
	v_rcp_f32_e32 v172, v172
	v_rcp_f32_e32 v173, v173
	v_pk_mul_f32 v[234:235], v[234:235], v[236:237]
	v_and_b32_e32 v237, 0xffff0000, v175
	v_lshlrev_b32_e32 v236, 16, v175
	v_pk_mul_f32 v[236:237], v[172:173], v[236:237]
	v_cvt_pk_bf16_f32 v172, v202, v203
	v_cvt_pk_bf16_f32 v174, v232, v233
	v_mul_lo_u32 v232, s51, v190
	v_mad_u64_u32 v[202:203], s[8:9], s50, v190, 0
	v_add3_u32 v203, v203, v191, v232
	v_lshl_add_u64 v[202:203], v[202:203], 1, s[60:61]
	v_cvt_pk_bf16_f32 v173, v234, v235
	v_cvt_pk_bf16_f32 v175, v236, v237
	v_lshl_add_u64 v[202:203], v[202:203], 0, v[192:193]
	flat_store_dwordx4 v[202:203], v[172:175]
	v_and_b32_e32 v233, 0xffff0000, v168
	v_lshlrev_b32_e32 v232, 16, v168
	v_add_f32_e32 v173, v112, v128
	v_mul_f32_e32 v173, 0xbfb8aa3b, v173
	v_exp_f32_e32 v173, v173
	v_add_f32_e32 v168, v113, v129
	v_mul_f32_e32 v168, 0xbfb8aa3b, v168
	v_add_f32_e32 v172, v116, v132
	v_add_f32_e32 v173, 1.0, v173
	v_rcp_f32_e32 v174, v173
	v_add_f32_e32 v173, v117, v133
	v_exp_f32_e32 v168, v168
	v_mul_f32_e32 v172, 0xbfb8aa3b, v172
	v_mul_f32_e32 v173, 0xbfb8aa3b, v173
	v_exp_f32_e32 v172, v172
	v_exp_f32_e32 v173, v173
	v_add_f32_e32 v168, 1.0, v168
	v_rcp_f32_e32 v175, v168
	v_add_f32_e32 v168, v118, v134
	v_add_f32_e32 v172, 1.0, v172
	v_add_f32_e32 v173, 1.0, v173
	v_mul_f32_e32 v168, 0xbfb8aa3b, v168
	v_rcp_f32_e32 v172, v172
	v_rcp_f32_e32 v173, v173
	v_exp_f32_e32 v168, v168
	v_and_b32_e32 v235, 0xffff0000, v169
	v_lshlrev_b32_e32 v234, 16, v169
	v_pk_mul_f32 v[172:173], v[172:173], v[232:233]
	v_and_b32_e32 v233, 0xffff0000, v170
	v_lshlrev_b32_e32 v232, 16, v170
	v_add_f32_e32 v168, 1.0, v168
	v_add_f32_e32 v170, v119, v135
	v_pk_mul_f32 v[174:175], v[174:175], v[232:233]
	v_rcp_f32_e32 v232, v168
	v_add_f32_e32 v168, v114, v130
	v_mul_f32_e32 v170, 0xbfb8aa3b, v170
	v_add_f32_e32 v169, v115, v131
	v_mul_f32_e32 v168, 0xbfb8aa3b, v168
	v_exp_f32_e32 v170, v170
	v_mul_f32_e32 v169, 0xbfb8aa3b, v169
	v_exp_f32_e32 v168, v168
	v_exp_f32_e32 v169, v169
	v_add_f32_e32 v170, 1.0, v170
	v_rcp_f32_e32 v233, v170
	v_add_f32_e32 v168, 1.0, v168
	v_add_f32_e32 v169, 1.0, v169
	v_rcp_f32_e32 v168, v168
	v_rcp_f32_e32 v169, v169
	v_pk_mul_f32 v[232:233], v[232:233], v[234:235]
	v_and_b32_e32 v235, 0xffff0000, v171
	v_lshlrev_b32_e32 v234, 16, v171
	v_pk_mul_f32 v[234:235], v[168:169], v[234:235]
	v_cvt_pk_bf16_f32 v168, v172, v173
	v_cvt_pk_bf16_f32 v169, v232, v233
	v_cvt_pk_bf16_f32 v170, v174, v175
	v_cvt_pk_bf16_f32 v171, v234, v235
	flat_store_dwordx4 v[202:203], v[168:171] offset:256
	v_and_b32_e32 v173, 0xffff0000, v164
	v_lshlrev_b32_e32 v172, 16, v164
	v_add_f32_e32 v169, v104, v136
	v_mul_f32_e32 v169, 0xbfb8aa3b, v169
	v_exp_f32_e32 v169, v169
	v_add_f32_e32 v164, v105, v137
	v_mul_f32_e32 v164, 0xbfb8aa3b, v164
	v_add_f32_e32 v168, v108, v140
	v_add_f32_e32 v169, 1.0, v169
	v_rcp_f32_e32 v170, v169
	v_add_f32_e32 v169, v109, v141
	v_exp_f32_e32 v164, v164
	v_mul_f32_e32 v168, 0xbfb8aa3b, v168
	v_mul_f32_e32 v169, 0xbfb8aa3b, v169
	v_exp_f32_e32 v168, v168
	v_exp_f32_e32 v169, v169
	v_add_f32_e32 v164, 1.0, v164
	v_rcp_f32_e32 v171, v164
	v_add_f32_e32 v164, v110, v142
	v_add_f32_e32 v168, 1.0, v168
	v_add_f32_e32 v169, 1.0, v169
	v_mul_f32_e32 v164, 0xbfb8aa3b, v164
	v_rcp_f32_e32 v168, v168
	v_rcp_f32_e32 v169, v169
	v_exp_f32_e32 v164, v164
	v_and_b32_e32 v175, 0xffff0000, v165
	v_lshlrev_b32_e32 v174, 16, v165
	v_pk_mul_f32 v[168:169], v[168:169], v[172:173]
	v_and_b32_e32 v173, 0xffff0000, v166
	v_lshlrev_b32_e32 v172, 16, v166
	v_add_f32_e32 v164, 1.0, v164
	v_add_f32_e32 v166, v111, v143
	v_pk_mul_f32 v[170:171], v[170:171], v[172:173]
	v_rcp_f32_e32 v172, v164
	v_add_f32_e32 v164, v106, v138
	v_mul_f32_e32 v166, 0xbfb8aa3b, v166
	v_add_f32_e32 v165, v107, v139
	v_mul_f32_e32 v164, 0xbfb8aa3b, v164
	v_exp_f32_e32 v166, v166
	v_mul_f32_e32 v165, 0xbfb8aa3b, v165
	v_exp_f32_e32 v164, v164
	v_exp_f32_e32 v165, v165
	v_add_f32_e32 v166, 1.0, v166
	v_rcp_f32_e32 v173, v166
	v_add_f32_e32 v164, 1.0, v164
	v_add_f32_e32 v165, 1.0, v165
	v_rcp_f32_e32 v164, v164
	v_rcp_f32_e32 v165, v165
	v_pk_mul_f32 v[172:173], v[172:173], v[174:175]
	v_and_b32_e32 v175, 0xffff0000, v167
	v_lshlrev_b32_e32 v174, 16, v167
	v_pk_mul_f32 v[174:175], v[164:165], v[174:175]
	v_cvt_pk_bf16_f32 v164, v168, v169
	v_cvt_pk_bf16_f32 v166, v170, v171
	v_mul_lo_u32 v170, s50, v201
	v_mul_lo_u32 v171, s51, v200
	v_mad_u64_u32 v[168:169], s[8:9], s50, v200, 0
	v_add3_u32 v169, v169, v170, v171
	v_lshl_add_u64 v[168:169], v[168:169], 1, s[60:61]
	v_cvt_pk_bf16_f32 v165, v172, v173
	v_cvt_pk_bf16_f32 v167, v174, v175
	v_lshl_add_u64 v[168:169], v[168:169], 0, v[192:193]
	flat_store_dwordx4 v[168:169], v[164:167]
	v_and_b32_e32 v171, 0xffff0000, v160
	v_lshlrev_b32_e32 v170, 16, v160
	v_add_f32_e32 v165, v96, v128
	v_mul_f32_e32 v165, 0xbfb8aa3b, v165
	v_exp_f32_e32 v165, v165
	v_add_f32_e32 v160, v97, v129
	v_mul_f32_e32 v160, 0xbfb8aa3b, v160
	v_add_f32_e32 v164, v100, v132
	v_add_f32_e32 v165, 1.0, v165
	v_rcp_f32_e32 v166, v165
	v_add_f32_e32 v165, v101, v133
	v_exp_f32_e32 v160, v160
	v_mul_f32_e32 v164, 0xbfb8aa3b, v164
	v_mul_f32_e32 v165, 0xbfb8aa3b, v165
	v_exp_f32_e32 v164, v164
	v_exp_f32_e32 v165, v165
	v_add_f32_e32 v160, 1.0, v160
	v_rcp_f32_e32 v167, v160
	v_add_f32_e32 v160, v102, v134
	v_add_f32_e32 v164, 1.0, v164
	v_add_f32_e32 v165, 1.0, v165
	v_mul_f32_e32 v160, 0xbfb8aa3b, v160
	v_rcp_f32_e32 v164, v164
	v_rcp_f32_e32 v165, v165
	v_exp_f32_e32 v160, v160
	v_and_b32_e32 v173, 0xffff0000, v161
	v_lshlrev_b32_e32 v172, 16, v161
	v_pk_mul_f32 v[164:165], v[164:165], v[170:171]
	v_and_b32_e32 v171, 0xffff0000, v162
	v_lshlrev_b32_e32 v170, 16, v162
	v_add_f32_e32 v160, 1.0, v160
	v_add_f32_e32 v162, v103, v135
	v_pk_mul_f32 v[166:167], v[166:167], v[170:171]
	v_rcp_f32_e32 v170, v160
	v_add_f32_e32 v160, v98, v130
	v_mul_f32_e32 v162, 0xbfb8aa3b, v162
	v_add_f32_e32 v161, v99, v131
	v_mul_f32_e32 v160, 0xbfb8aa3b, v160
	v_exp_f32_e32 v162, v162
	v_mul_f32_e32 v161, 0xbfb8aa3b, v161
	v_exp_f32_e32 v160, v160
	v_exp_f32_e32 v161, v161
	v_add_f32_e32 v162, 1.0, v162
	v_rcp_f32_e32 v171, v162
	v_add_f32_e32 v160, 1.0, v160
	v_add_f32_e32 v161, 1.0, v161
	v_rcp_f32_e32 v160, v160
	v_rcp_f32_e32 v161, v161
	v_pk_mul_f32 v[170:171], v[170:171], v[172:173]
	v_and_b32_e32 v173, 0xffff0000, v163
	v_lshlrev_b32_e32 v172, 16, v163
	v_pk_mul_f32 v[172:173], v[160:161], v[172:173]
	v_cvt_pk_bf16_f32 v160, v164, v165
	v_cvt_pk_bf16_f32 v161, v170, v171
	v_cvt_pk_bf16_f32 v162, v166, v167
	v_cvt_pk_bf16_f32 v163, v172, v173
	flat_store_dwordx4 v[168:169], v[160:163] offset:256
	v_and_b32_e32 v165, 0xffff0000, v156
	v_lshlrev_b32_e32 v164, 16, v156
	v_add_f32_e32 v161, v88, v136
	v_mul_f32_e32 v161, 0xbfb8aa3b, v161
	v_exp_f32_e32 v161, v161
	v_add_f32_e32 v156, v89, v137
	v_mul_f32_e32 v156, 0xbfb8aa3b, v156
	v_add_f32_e32 v160, v92, v140
	v_add_f32_e32 v161, 1.0, v161
	v_rcp_f32_e32 v162, v161
	v_add_f32_e32 v161, v93, v141
	v_exp_f32_e32 v156, v156
	v_mul_f32_e32 v160, 0xbfb8aa3b, v160
	v_mul_f32_e32 v161, 0xbfb8aa3b, v161
	v_exp_f32_e32 v160, v160
	v_exp_f32_e32 v161, v161
	v_add_f32_e32 v156, 1.0, v156
	v_rcp_f32_e32 v163, v156
	v_add_f32_e32 v156, v94, v142
	v_add_f32_e32 v160, 1.0, v160
	v_add_f32_e32 v161, 1.0, v161
	v_mul_f32_e32 v156, 0xbfb8aa3b, v156
	v_rcp_f32_e32 v160, v160
	v_rcp_f32_e32 v161, v161
	v_exp_f32_e32 v156, v156
	v_and_b32_e32 v167, 0xffff0000, v157
	v_lshlrev_b32_e32 v166, 16, v157
	v_pk_mul_f32 v[160:161], v[160:161], v[164:165]
	v_and_b32_e32 v165, 0xffff0000, v158
	v_lshlrev_b32_e32 v164, 16, v158
	v_add_f32_e32 v156, 1.0, v156
	v_add_f32_e32 v158, v95, v143
	v_pk_mul_f32 v[162:163], v[162:163], v[164:165]
	v_rcp_f32_e32 v164, v156
	v_add_f32_e32 v156, v90, v138
	v_mul_f32_e32 v158, 0xbfb8aa3b, v158
	v_add_f32_e32 v157, v91, v139
	v_mul_f32_e32 v156, 0xbfb8aa3b, v156
	v_exp_f32_e32 v158, v158
	v_mul_f32_e32 v157, 0xbfb8aa3b, v157
	v_exp_f32_e32 v156, v156
	v_exp_f32_e32 v157, v157
	v_add_f32_e32 v158, 1.0, v158
	v_rcp_f32_e32 v165, v158
	v_add_f32_e32 v156, 1.0, v156
	v_add_f32_e32 v157, 1.0, v157
	v_rcp_f32_e32 v156, v156
	v_rcp_f32_e32 v157, v157
	v_pk_mul_f32 v[164:165], v[164:165], v[166:167]
	v_and_b32_e32 v167, 0xffff0000, v159
	v_lshlrev_b32_e32 v166, 16, v159
	v_pk_mul_f32 v[166:167], v[156:157], v[166:167]
	v_cvt_pk_bf16_f32 v156, v160, v161
	v_cvt_pk_bf16_f32 v158, v162, v163
	v_mul_lo_u32 v162, s50, v199
	v_mul_lo_u32 v163, s51, v198
	v_mad_u64_u32 v[160:161], s[8:9], s50, v198, 0
	v_add3_u32 v161, v161, v162, v163
	v_lshl_add_u64 v[160:161], v[160:161], 1, s[60:61]
	v_cvt_pk_bf16_f32 v157, v164, v165
	v_cvt_pk_bf16_f32 v159, v166, v167
	v_lshl_add_u64 v[160:161], v[160:161], 0, v[192:193]
	flat_store_dwordx4 v[160:161], v[156:159]
	v_and_b32_e32 v163, 0xffff0000, v152
	v_lshlrev_b32_e32 v162, 16, v152
	v_add_f32_e32 v157, v80, v128
	v_mul_f32_e32 v157, 0xbfb8aa3b, v157
	v_exp_f32_e32 v157, v157
	v_add_f32_e32 v152, v81, v129
	v_mul_f32_e32 v152, 0xbfb8aa3b, v152
	v_add_f32_e32 v156, v84, v132
	v_add_f32_e32 v157, 1.0, v157
	v_rcp_f32_e32 v158, v157
	v_add_f32_e32 v157, v85, v133
	v_exp_f32_e32 v152, v152
	v_mul_f32_e32 v156, 0xbfb8aa3b, v156
	v_mul_f32_e32 v157, 0xbfb8aa3b, v157
	v_exp_f32_e32 v156, v156
	v_exp_f32_e32 v157, v157
	v_add_f32_e32 v152, 1.0, v152
	v_rcp_f32_e32 v159, v152
	v_add_f32_e32 v152, v86, v134
	v_add_f32_e32 v156, 1.0, v156
	v_add_f32_e32 v157, 1.0, v157
	v_mul_f32_e32 v152, 0xbfb8aa3b, v152
	v_rcp_f32_e32 v156, v156
	v_rcp_f32_e32 v157, v157
	v_exp_f32_e32 v152, v152
	v_and_b32_e32 v165, 0xffff0000, v153
	v_lshlrev_b32_e32 v164, 16, v153
	v_pk_mul_f32 v[156:157], v[156:157], v[162:163]
	v_and_b32_e32 v163, 0xffff0000, v154
	v_lshlrev_b32_e32 v162, 16, v154
	v_add_f32_e32 v152, 1.0, v152
	v_add_f32_e32 v154, v87, v135
	v_pk_mul_f32 v[158:159], v[158:159], v[162:163]
	v_rcp_f32_e32 v162, v152
	v_add_f32_e32 v152, v82, v130
	v_mul_f32_e32 v154, 0xbfb8aa3b, v154
	v_add_f32_e32 v153, v83, v131
	v_mul_f32_e32 v152, 0xbfb8aa3b, v152
	v_exp_f32_e32 v154, v154
	v_mul_f32_e32 v153, 0xbfb8aa3b, v153
	v_exp_f32_e32 v152, v152
	v_exp_f32_e32 v153, v153
	v_add_f32_e32 v154, 1.0, v154
	v_rcp_f32_e32 v163, v154
	v_add_f32_e32 v152, 1.0, v152
	v_add_f32_e32 v153, 1.0, v153
	v_rcp_f32_e32 v152, v152
	v_rcp_f32_e32 v153, v153
	v_pk_mul_f32 v[162:163], v[162:163], v[164:165]
	v_and_b32_e32 v165, 0xffff0000, v155
	v_lshlrev_b32_e32 v164, 16, v155
	v_pk_mul_f32 v[164:165], v[152:153], v[164:165]
	v_cvt_pk_bf16_f32 v152, v156, v157
	v_cvt_pk_bf16_f32 v153, v162, v163
	v_cvt_pk_bf16_f32 v154, v158, v159
	v_cvt_pk_bf16_f32 v155, v164, v165
	flat_store_dwordx4 v[160:161], v[152:155] offset:256
	v_and_b32_e32 v157, 0xffff0000, v148
	v_lshlrev_b32_e32 v156, 16, v148
	v_add_f32_e32 v153, v72, v136
	v_mul_f32_e32 v153, 0xbfb8aa3b, v153
	v_exp_f32_e32 v153, v153
	v_add_f32_e32 v148, v73, v137
	v_mul_f32_e32 v148, 0xbfb8aa3b, v148
	v_add_f32_e32 v152, v76, v140
	v_add_f32_e32 v153, 1.0, v153
	v_rcp_f32_e32 v154, v153
	v_add_f32_e32 v153, v77, v141
	v_exp_f32_e32 v148, v148
	v_mul_f32_e32 v152, 0xbfb8aa3b, v152
	v_mul_f32_e32 v153, 0xbfb8aa3b, v153
	v_exp_f32_e32 v152, v152
	v_exp_f32_e32 v153, v153
	v_add_f32_e32 v148, 1.0, v148
	v_rcp_f32_e32 v155, v148
	v_add_f32_e32 v148, v78, v142
	v_add_f32_e32 v152, 1.0, v152
	v_add_f32_e32 v153, 1.0, v153
	v_mul_f32_e32 v148, 0xbfb8aa3b, v148
	v_rcp_f32_e32 v152, v152
	v_rcp_f32_e32 v153, v153
	v_exp_f32_e32 v148, v148
	v_and_b32_e32 v159, 0xffff0000, v149
	v_lshlrev_b32_e32 v158, 16, v149
	v_pk_mul_f32 v[152:153], v[152:153], v[156:157]
	v_and_b32_e32 v157, 0xffff0000, v150
	v_lshlrev_b32_e32 v156, 16, v150
	v_add_f32_e32 v148, 1.0, v148
	v_add_f32_e32 v150, v79, v143
	v_pk_mul_f32 v[154:155], v[154:155], v[156:157]
	v_rcp_f32_e32 v156, v148
	v_add_f32_e32 v148, v74, v138
	v_mul_f32_e32 v150, 0xbfb8aa3b, v150
	v_add_f32_e32 v149, v75, v139
	v_mul_f32_e32 v148, 0xbfb8aa3b, v148
	v_exp_f32_e32 v150, v150
	v_mul_f32_e32 v149, 0xbfb8aa3b, v149
	v_exp_f32_e32 v148, v148
	v_exp_f32_e32 v149, v149
	v_add_f32_e32 v150, 1.0, v150
	v_rcp_f32_e32 v157, v150
	v_add_f32_e32 v148, 1.0, v148
	v_add_f32_e32 v149, 1.0, v149
	v_rcp_f32_e32 v148, v148
	v_rcp_f32_e32 v149, v149
	v_pk_mul_f32 v[156:157], v[156:157], v[158:159]
	v_and_b32_e32 v159, 0xffff0000, v151
	v_lshlrev_b32_e32 v158, 16, v151
	v_pk_mul_f32 v[158:159], v[148:149], v[158:159]
	v_cvt_pk_bf16_f32 v148, v152, v153
	v_cvt_pk_bf16_f32 v150, v154, v155
	v_mul_lo_u32 v154, s50, v197
	v_mul_lo_u32 v155, s51, v196
	v_mad_u64_u32 v[152:153], s[8:9], s50, v196, 0
	v_add3_u32 v153, v153, v154, v155
	v_lshl_add_u64 v[152:153], v[152:153], 1, s[60:61]
	v_cvt_pk_bf16_f32 v149, v156, v157
	v_cvt_pk_bf16_f32 v151, v158, v159
	v_lshl_add_u64 v[152:153], v[152:153], 0, v[192:193]
	flat_store_dwordx4 v[152:153], v[148:151]
	v_and_b32_e32 v155, 0xffff0000, v144
	v_lshlrev_b32_e32 v154, 16, v144
	v_add_f32_e32 v149, v64, v128
	v_mul_f32_e32 v149, 0xbfb8aa3b, v149
	v_exp_f32_e32 v149, v149
	v_add_f32_e32 v144, v65, v129
	v_mul_f32_e32 v144, 0xbfb8aa3b, v144
	v_add_f32_e32 v148, v68, v132
	v_add_f32_e32 v149, 1.0, v149
	v_rcp_f32_e32 v150, v149
	v_add_f32_e32 v149, v69, v133
	v_exp_f32_e32 v144, v144
	v_mul_f32_e32 v148, 0xbfb8aa3b, v148
	v_mul_f32_e32 v149, 0xbfb8aa3b, v149
	v_exp_f32_e32 v148, v148
	v_exp_f32_e32 v149, v149
	v_add_f32_e32 v144, 1.0, v144
	v_rcp_f32_e32 v151, v144
	v_add_f32_e32 v144, v70, v134
	v_add_f32_e32 v148, 1.0, v148
	v_add_f32_e32 v149, 1.0, v149
	v_mul_f32_e32 v144, 0xbfb8aa3b, v144
	v_rcp_f32_e32 v148, v148
	v_rcp_f32_e32 v149, v149
	v_exp_f32_e32 v144, v144
	v_and_b32_e32 v157, 0xffff0000, v145
	v_lshlrev_b32_e32 v156, 16, v145
	v_pk_mul_f32 v[148:149], v[148:149], v[154:155]
	v_and_b32_e32 v155, 0xffff0000, v146
	v_lshlrev_b32_e32 v154, 16, v146
	v_add_f32_e32 v144, 1.0, v144
	v_add_f32_e32 v146, v71, v135
	v_pk_mul_f32 v[150:151], v[150:151], v[154:155]
	v_rcp_f32_e32 v154, v144
	v_add_f32_e32 v144, v66, v130
	v_mul_f32_e32 v146, 0xbfb8aa3b, v146
	v_add_f32_e32 v145, v67, v131
	v_mul_f32_e32 v144, 0xbfb8aa3b, v144
	v_exp_f32_e32 v146, v146
	v_mul_f32_e32 v145, 0xbfb8aa3b, v145
	v_exp_f32_e32 v144, v144
	v_exp_f32_e32 v145, v145
	v_add_f32_e32 v146, 1.0, v146
	v_rcp_f32_e32 v155, v146
	v_add_f32_e32 v144, 1.0, v144
	v_add_f32_e32 v145, 1.0, v145
	v_rcp_f32_e32 v144, v144
	v_rcp_f32_e32 v145, v145
	v_pk_mul_f32 v[154:155], v[154:155], v[156:157]
	v_and_b32_e32 v157, 0xffff0000, v147
	v_lshlrev_b32_e32 v156, 16, v147
	v_pk_mul_f32 v[156:157], v[144:145], v[156:157]
	v_add_u32_e32 v198, 0x80, v190
	v_cvt_pk_bf16_f32 v144, v148, v149
	v_cvt_pk_bf16_f32 v145, v154, v155
	v_cvt_pk_bf16_f32 v146, v150, v151
	v_cvt_pk_bf16_f32 v147, v156, v157
	v_ashrrev_i32_e32 v199, 31, v198
	flat_store_dwordx4 v[152:153], v[144:147] offset:256
	v_add_u32_e32 v196, 0x90, v190
	v_add_f32_e32 v191, v60, v140
	v_lshlrev_b64 v[144:145], 10, v[198:199]
	v_lshl_add_u64 v[144:145], v[194:195], 0, v[144:145]
	global_load_dwordx4 v[200:203], v[144:145], off
	global_load_dwordx4 v[168:171], v[144:145], off offset:256
	v_ashrrev_i32_e32 v197, 31, v196
	v_mul_f32_e32 v191, 0xbfb8aa3b, v191
	v_lshlrev_b64 v[144:145], 10, v[196:197]
	v_add_u32_e32 v174, 0xa0, v190
	v_exp_f32_e32 v191, v191
	v_lshl_add_u64 v[144:145], v[194:195], 0, v[144:145]
	v_ashrrev_i32_e32 v175, 31, v174
	global_load_dwordx4 v[164:167], v[144:145], off
	global_load_dwordx4 v[160:163], v[144:145], off offset:256
	v_lshlrev_b64 v[144:145], 10, v[174:175]
	v_add_u32_e32 v172, 0xb0, v190
	v_lshl_add_u64 v[144:145], v[194:195], 0, v[144:145]
	v_ashrrev_i32_e32 v173, 31, v172
	global_load_dwordx4 v[156:159], v[144:145], off
	global_load_dwordx4 v[152:155], v[144:145], off offset:256
	v_lshlrev_b64 v[144:145], 10, v[172:173]
	v_add_f32_e32 v191, 1.0, v191
	v_lshl_add_u64 v[144:145], v[194:195], 0, v[144:145]
	v_rcp_f32_e32 v194, v191
	v_add_f32_e32 v191, v56, v136
	v_mul_f32_e32 v191, 0xbfb8aa3b, v191
	v_exp_f32_e32 v191, v191
	global_load_dwordx4 v[148:151], v[144:145], off
	s_nop 0
	global_load_dwordx4 v[144:147], v[144:145], off offset:256
	v_add_f32_e32 v191, 1.0, v191
	v_rcp_f32_e32 v232, v191
	v_add_f32_e32 v191, v61, v141
	v_mul_f32_e32 v191, 0xbfb8aa3b, v191
	v_exp_f32_e32 v191, v191
	s_waitcnt vmcnt(0) lgkmcnt(0)
	v_and_b32_e32 v235, 0xffff0000, v200
	v_add_f32_e32 v191, 1.0, v191
	v_rcp_f32_e32 v195, v191
	v_add_f32_e32 v191, v57, v137
	v_mul_f32_e32 v191, 0xbfb8aa3b, v191
	v_exp_f32_e32 v191, v191
	v_lshlrev_b32_e32 v234, 16, v200
	v_pk_mul_f32 v[194:195], v[194:195], v[234:235]
	v_and_b32_e32 v235, 0xffff0000, v202
	v_add_f32_e32 v191, 1.0, v191
	v_rcp_f32_e32 v233, v191
	v_add_f32_e32 v191, v62, v142
	v_mul_f32_e32 v191, 0xbfb8aa3b, v191
	v_exp_f32_e32 v191, v191
	v_lshlrev_b32_e32 v234, 16, v202
	v_pk_mul_f32 v[232:233], v[232:233], v[234:235]
	v_and_b32_e32 v237, 0xffff0000, v201
	v_add_f32_e32 v191, 1.0, v191
	v_rcp_f32_e32 v234, v191
	v_add_f32_e32 v191, v58, v138
	v_mul_f32_e32 v191, 0xbfb8aa3b, v191
	v_exp_f32_e32 v191, v191
	v_lshlrev_b32_e32 v236, 16, v201
	v_cvt_pk_bf16_f32 v202, v232, v233
	v_and_b32_e32 v233, 0xffff0000, v169
	v_add_f32_e32 v191, 1.0, v191
	v_rcp_f32_e32 v200, v191
	v_add_f32_e32 v191, v63, v143
	v_mul_f32_e32 v191, 0xbfb8aa3b, v191
	v_exp_f32_e32 v191, v191
	v_lshlrev_b32_e32 v232, 16, v169
	v_add_f32_e32 v169, v51, v131
	v_mul_f32_e32 v169, 0xbfb8aa3b, v169
	v_add_f32_e32 v191, 1.0, v191
	v_rcp_f32_e32 v235, v191
	v_add_f32_e32 v191, v59, v139
	v_mul_f32_e32 v191, 0xbfb8aa3b, v191
	v_exp_f32_e32 v191, v191
	v_pk_mul_f32 v[234:235], v[234:235], v[236:237]
	v_and_b32_e32 v237, 0xffff0000, v203
	v_lshlrev_b32_e32 v236, 16, v203
	v_add_f32_e32 v191, 1.0, v191
	v_rcp_f32_e32 v201, v191
	v_mul_lo_u32 v191, s50, v199
	v_mul_lo_u32 v199, s51, v198
	v_exp_f32_e32 v169, v169
	v_pk_mul_f32 v[236:237], v[200:201], v[236:237]
	v_cvt_pk_bf16_f32 v200, v194, v195
	v_mad_u64_u32 v[194:195], s[8:9], s50, v198, 0
	v_add3_u32 v195, v195, v191, v199
	v_add_f32_e32 v191, v52, v132
	v_mul_f32_e32 v191, 0xbfb8aa3b, v191
	v_exp_f32_e32 v191, v191
	v_lshl_add_u64 v[194:195], v[194:195], 1, s[60:61]
	v_cvt_pk_bf16_f32 v201, v234, v235
	v_cvt_pk_bf16_f32 v203, v236, v237
	v_add_f32_e32 v191, 1.0, v191
	v_rcp_f32_e32 v198, v191
	v_add_f32_e32 v191, v48, v128
	v_mul_f32_e32 v191, 0xbfb8aa3b, v191
	v_exp_f32_e32 v191, v191
	v_lshl_add_u64 v[194:195], v[194:195], 0, v[192:193]
	flat_store_dwordx4 v[194:195], v[200:203]
	v_add_f32_e32 v169, 1.0, v169
	v_add_f32_e32 v191, 1.0, v191
	v_and_b32_e32 v203, 0xffff0000, v168
	v_lshlrev_b32_e32 v202, 16, v168
	v_add_f32_e32 v168, v49, v129
	v_mul_f32_e32 v168, 0xbfb8aa3b, v168
	v_rcp_f32_e32 v200, v191
	v_add_f32_e32 v191, v53, v133
	v_exp_f32_e32 v168, v168
	v_mul_f32_e32 v191, 0xbfb8aa3b, v191
	v_exp_f32_e32 v191, v191
	v_rcp_f32_e32 v169, v169
	v_add_f32_e32 v168, 1.0, v168
	v_rcp_f32_e32 v201, v168
	v_add_f32_e32 v168, v54, v134
	v_add_f32_e32 v191, 1.0, v191
	v_mul_f32_e32 v168, 0xbfb8aa3b, v168
	v_rcp_f32_e32 v199, v191
	v_exp_f32_e32 v168, v168
	v_pk_mul_f32 v[198:199], v[198:199], v[202:203]
	v_and_b32_e32 v203, 0xffff0000, v170
	v_lshlrev_b32_e32 v202, 16, v170
	v_add_f32_e32 v168, 1.0, v168
	v_add_f32_e32 v170, v55, v135
	v_pk_mul_f32 v[200:201], v[200:201], v[202:203]
	v_rcp_f32_e32 v202, v168
	v_add_f32_e32 v168, v50, v130
	v_mul_f32_e32 v170, 0xbfb8aa3b, v170
	v_mul_f32_e32 v168, 0xbfb8aa3b, v168
	v_exp_f32_e32 v170, v170
	v_exp_f32_e32 v168, v168
	v_add_f32_e32 v170, 1.0, v170
	v_add_f32_e32 v168, 1.0, v168
	v_rcp_f32_e32 v203, v170
	v_rcp_f32_e32 v168, v168
	v_cvt_pk_bf16_f32 v170, v200, v201
	v_pk_mul_f32 v[202:203], v[202:203], v[232:233]
	v_and_b32_e32 v233, 0xffff0000, v171
	v_lshlrev_b32_e32 v232, 16, v171
	v_pk_mul_f32 v[232:233], v[168:169], v[232:233]
	v_cvt_pk_bf16_f32 v168, v198, v199
	v_cvt_pk_bf16_f32 v169, v202, v203
	v_cvt_pk_bf16_f32 v171, v232, v233
	flat_store_dwordx4 v[194:195], v[168:171] offset:256
	v_and_b32_e32 v195, 0xffff0000, v164
	v_lshlrev_b32_e32 v194, 16, v164
	v_add_f32_e32 v169, v40, v136
	v_mul_f32_e32 v169, 0xbfb8aa3b, v169
	v_exp_f32_e32 v169, v169
	v_add_f32_e32 v164, v41, v137
	v_mul_f32_e32 v164, 0xbfb8aa3b, v164
	v_add_f32_e32 v168, v44, v140
	v_add_f32_e32 v169, 1.0, v169
	v_rcp_f32_e32 v170, v169
	v_add_f32_e32 v169, v45, v141
	v_exp_f32_e32 v164, v164
	v_mul_f32_e32 v168, 0xbfb8aa3b, v168
	v_mul_f32_e32 v169, 0xbfb8aa3b, v169
	v_exp_f32_e32 v168, v168
	v_exp_f32_e32 v169, v169
	v_add_f32_e32 v164, 1.0, v164
	v_rcp_f32_e32 v171, v164
	v_add_f32_e32 v164, v46, v142
	v_add_f32_e32 v168, 1.0, v168
	v_add_f32_e32 v169, 1.0, v169
	v_mul_f32_e32 v164, 0xbfb8aa3b, v164
	v_rcp_f32_e32 v168, v168
	v_rcp_f32_e32 v169, v169
	v_exp_f32_e32 v164, v164
	v_and_b32_e32 v199, 0xffff0000, v165
	v_lshlrev_b32_e32 v198, 16, v165
	v_pk_mul_f32 v[168:169], v[168:169], v[194:195]
	v_and_b32_e32 v195, 0xffff0000, v166
	v_lshlrev_b32_e32 v194, 16, v166
	v_add_f32_e32 v164, 1.0, v164
	v_add_f32_e32 v166, v47, v143
	v_pk_mul_f32 v[170:171], v[170:171], v[194:195]
	v_rcp_f32_e32 v194, v164
	v_add_f32_e32 v164, v42, v138
	v_mul_f32_e32 v166, 0xbfb8aa3b, v166
	v_add_f32_e32 v165, v43, v139
	v_mul_f32_e32 v164, 0xbfb8aa3b, v164
	v_exp_f32_e32 v166, v166
	v_mul_f32_e32 v165, 0xbfb8aa3b, v165
	v_exp_f32_e32 v164, v164
	v_exp_f32_e32 v165, v165
	v_add_f32_e32 v166, 1.0, v166
	v_rcp_f32_e32 v195, v166
	v_add_f32_e32 v164, 1.0, v164
	v_add_f32_e32 v165, 1.0, v165
	v_rcp_f32_e32 v164, v164
	v_rcp_f32_e32 v165, v165
	v_pk_mul_f32 v[194:195], v[194:195], v[198:199]
	v_and_b32_e32 v199, 0xffff0000, v167
	v_lshlrev_b32_e32 v198, 16, v167
	v_pk_mul_f32 v[198:199], v[164:165], v[198:199]
	v_cvt_pk_bf16_f32 v164, v168, v169
	v_cvt_pk_bf16_f32 v166, v170, v171
	v_mul_lo_u32 v170, s50, v197
	v_mul_lo_u32 v171, s51, v196
	v_mad_u64_u32 v[168:169], s[8:9], s50, v196, 0
	v_add3_u32 v169, v169, v170, v171
	v_lshl_add_u64 v[168:169], v[168:169], 1, s[60:61]
	v_cvt_pk_bf16_f32 v165, v194, v195
	v_cvt_pk_bf16_f32 v167, v198, v199
	v_lshl_add_u64 v[168:169], v[168:169], 0, v[192:193]
	flat_store_dwordx4 v[168:169], v[164:167]
	v_and_b32_e32 v171, 0xffff0000, v160
	v_lshlrev_b32_e32 v170, 16, v160
	v_add_f32_e32 v165, v32, v128
	v_mul_f32_e32 v165, 0xbfb8aa3b, v165
	v_exp_f32_e32 v165, v165
	v_add_f32_e32 v160, v33, v129
	v_mul_f32_e32 v160, 0xbfb8aa3b, v160
	v_add_f32_e32 v164, v36, v132
	v_add_f32_e32 v165, 1.0, v165
	v_rcp_f32_e32 v166, v165
	v_add_f32_e32 v165, v37, v133
	v_exp_f32_e32 v160, v160
	v_mul_f32_e32 v164, 0xbfb8aa3b, v164
	v_mul_f32_e32 v165, 0xbfb8aa3b, v165
	v_exp_f32_e32 v164, v164
	v_exp_f32_e32 v165, v165
	v_add_f32_e32 v160, 1.0, v160
	v_rcp_f32_e32 v167, v160
	v_add_f32_e32 v160, v38, v134
	v_add_f32_e32 v164, 1.0, v164
	v_add_f32_e32 v165, 1.0, v165
	v_mul_f32_e32 v160, 0xbfb8aa3b, v160
	v_rcp_f32_e32 v164, v164
	v_rcp_f32_e32 v165, v165
	v_exp_f32_e32 v160, v160
	v_and_b32_e32 v195, 0xffff0000, v161
	v_lshlrev_b32_e32 v194, 16, v161
	v_pk_mul_f32 v[164:165], v[164:165], v[170:171]
	v_and_b32_e32 v171, 0xffff0000, v162
	v_lshlrev_b32_e32 v170, 16, v162
	v_add_f32_e32 v160, 1.0, v160
	v_add_f32_e32 v162, v39, v135
	v_pk_mul_f32 v[166:167], v[166:167], v[170:171]
	v_rcp_f32_e32 v170, v160
	v_add_f32_e32 v160, v34, v130
	v_mul_f32_e32 v162, 0xbfb8aa3b, v162
	v_add_f32_e32 v161, v35, v131
	v_mul_f32_e32 v160, 0xbfb8aa3b, v160
	v_exp_f32_e32 v162, v162
	v_mul_f32_e32 v161, 0xbfb8aa3b, v161
	v_exp_f32_e32 v160, v160
	v_exp_f32_e32 v161, v161
	v_add_f32_e32 v162, 1.0, v162
	v_rcp_f32_e32 v171, v162
	v_add_f32_e32 v160, 1.0, v160
	v_add_f32_e32 v161, 1.0, v161
	v_rcp_f32_e32 v160, v160
	v_rcp_f32_e32 v161, v161
	v_pk_mul_f32 v[170:171], v[170:171], v[194:195]
	v_and_b32_e32 v195, 0xffff0000, v163
	v_lshlrev_b32_e32 v194, 16, v163
	v_pk_mul_f32 v[194:195], v[160:161], v[194:195]
	v_cvt_pk_bf16_f32 v160, v164, v165
	v_cvt_pk_bf16_f32 v161, v170, v171
	v_cvt_pk_bf16_f32 v162, v166, v167
	v_cvt_pk_bf16_f32 v163, v194, v195
	flat_store_dwordx4 v[168:169], v[160:163] offset:256
	v_and_b32_e32 v165, 0xffff0000, v156
	v_lshlrev_b32_e32 v164, 16, v156
	v_add_f32_e32 v161, v24, v136
	v_mul_f32_e32 v161, 0xbfb8aa3b, v161
	v_exp_f32_e32 v161, v161
	v_add_f32_e32 v156, v25, v137
	v_mul_f32_e32 v156, 0xbfb8aa3b, v156
	v_add_f32_e32 v160, v28, v140
	v_add_f32_e32 v161, 1.0, v161
	v_rcp_f32_e32 v162, v161
	v_add_f32_e32 v161, v29, v141
	v_exp_f32_e32 v156, v156
	v_mul_f32_e32 v160, 0xbfb8aa3b, v160
	v_mul_f32_e32 v161, 0xbfb8aa3b, v161
	v_exp_f32_e32 v160, v160
	v_exp_f32_e32 v161, v161
	v_add_f32_e32 v156, 1.0, v156
	v_rcp_f32_e32 v163, v156
	v_add_f32_e32 v156, v30, v142
	v_add_f32_e32 v160, 1.0, v160
	v_add_f32_e32 v161, 1.0, v161
	v_mul_f32_e32 v156, 0xbfb8aa3b, v156
	v_rcp_f32_e32 v160, v160
	v_rcp_f32_e32 v161, v161
	v_exp_f32_e32 v156, v156
	v_and_b32_e32 v167, 0xffff0000, v157
	v_lshlrev_b32_e32 v166, 16, v157
	v_pk_mul_f32 v[160:161], v[160:161], v[164:165]
	v_and_b32_e32 v165, 0xffff0000, v158
	v_lshlrev_b32_e32 v164, 16, v158
	v_add_f32_e32 v156, 1.0, v156
	v_add_f32_e32 v158, v31, v143
	v_pk_mul_f32 v[162:163], v[162:163], v[164:165]
	v_rcp_f32_e32 v164, v156
	v_add_f32_e32 v156, v26, v138
	v_mul_f32_e32 v158, 0xbfb8aa3b, v158
	v_add_f32_e32 v157, v27, v139
	v_mul_f32_e32 v156, 0xbfb8aa3b, v156
	v_exp_f32_e32 v158, v158
	v_mul_f32_e32 v157, 0xbfb8aa3b, v157
	v_exp_f32_e32 v156, v156
	v_exp_f32_e32 v157, v157
	v_add_f32_e32 v158, 1.0, v158
	v_rcp_f32_e32 v165, v158
	v_add_f32_e32 v156, 1.0, v156
	v_add_f32_e32 v157, 1.0, v157
	v_rcp_f32_e32 v156, v156
	v_rcp_f32_e32 v157, v157
	v_pk_mul_f32 v[164:165], v[164:165], v[166:167]
	v_and_b32_e32 v167, 0xffff0000, v159
	v_lshlrev_b32_e32 v166, 16, v159
	v_pk_mul_f32 v[166:167], v[156:157], v[166:167]
	v_cvt_pk_bf16_f32 v156, v160, v161
	v_cvt_pk_bf16_f32 v158, v162, v163
	v_mul_lo_u32 v162, s50, v175
	v_mul_lo_u32 v163, s51, v174
	v_mad_u64_u32 v[160:161], s[8:9], s50, v174, 0
	v_add3_u32 v161, v161, v162, v163
	v_lshl_add_u64 v[160:161], v[160:161], 1, s[60:61]
	v_cvt_pk_bf16_f32 v157, v164, v165
	v_cvt_pk_bf16_f32 v159, v166, v167
	v_lshl_add_u64 v[160:161], v[160:161], 0, v[192:193]
	flat_store_dwordx4 v[160:161], v[156:159]
	v_and_b32_e32 v163, 0xffff0000, v152
	v_lshlrev_b32_e32 v162, 16, v152
	v_add_f32_e32 v157, v16, v128
	v_mul_f32_e32 v157, 0xbfb8aa3b, v157
	v_exp_f32_e32 v157, v157
	v_add_f32_e32 v152, v17, v129
	v_mul_f32_e32 v152, 0xbfb8aa3b, v152
	v_add_f32_e32 v156, v20, v132
	v_add_f32_e32 v157, 1.0, v157
	v_rcp_f32_e32 v158, v157
	v_add_f32_e32 v157, v21, v133
	v_exp_f32_e32 v152, v152
	v_mul_f32_e32 v156, 0xbfb8aa3b, v156
	v_mul_f32_e32 v157, 0xbfb8aa3b, v157
	v_exp_f32_e32 v156, v156
	v_exp_f32_e32 v157, v157
	v_add_f32_e32 v152, 1.0, v152
	v_rcp_f32_e32 v159, v152
	v_add_f32_e32 v152, v22, v134
	v_add_f32_e32 v156, 1.0, v156
	v_add_f32_e32 v157, 1.0, v157
	v_mul_f32_e32 v152, 0xbfb8aa3b, v152
	v_rcp_f32_e32 v156, v156
	v_rcp_f32_e32 v157, v157
	v_exp_f32_e32 v152, v152
	v_and_b32_e32 v165, 0xffff0000, v153
	v_lshlrev_b32_e32 v164, 16, v153
	v_pk_mul_f32 v[156:157], v[156:157], v[162:163]
	v_and_b32_e32 v163, 0xffff0000, v154
	v_lshlrev_b32_e32 v162, 16, v154
	v_add_f32_e32 v152, 1.0, v152
	v_add_f32_e32 v154, v23, v135
	v_pk_mul_f32 v[158:159], v[158:159], v[162:163]
	v_rcp_f32_e32 v162, v152
	v_add_f32_e32 v152, v18, v130
	v_mul_f32_e32 v154, 0xbfb8aa3b, v154
	v_add_f32_e32 v153, v19, v131
	v_mul_f32_e32 v152, 0xbfb8aa3b, v152
	v_exp_f32_e32 v154, v154
	v_mul_f32_e32 v153, 0xbfb8aa3b, v153
	v_exp_f32_e32 v152, v152
	v_exp_f32_e32 v153, v153
	v_add_f32_e32 v140, v12, v140
	v_add_f32_e32 v141, v13, v141
	v_mul_f32_e32 v140, 0xbfb8aa3b, v140
	v_add_f32_e32 v136, v8, v136
	v_mul_f32_e32 v141, 0xbfb8aa3b, v141
	v_add_f32_e32 v137, v9, v137
	v_add_f32_e32 v154, 1.0, v154
	v_exp_f32_e32 v140, v140
	v_mul_f32_e32 v136, 0xbfb8aa3b, v136
	v_exp_f32_e32 v141, v141
	v_mul_f32_e32 v137, 0xbfb8aa3b, v137
	v_add_f32_e32 v152, 1.0, v152
	v_rcp_f32_e32 v163, v154
	v_add_f32_e32 v153, 1.0, v153
	v_exp_f32_e32 v136, v136
	v_exp_f32_e32 v137, v137
	v_rcp_f32_e32 v152, v152
	v_rcp_f32_e32 v153, v153
	v_add_f32_e32 v140, 1.0, v140
	v_add_f32_e32 v141, 1.0, v141
	v_pk_mul_f32 v[162:163], v[162:163], v[164:165]
	v_and_b32_e32 v165, 0xffff0000, v155
	v_lshlrev_b32_e32 v164, 16, v155
	v_rcp_f32_e32 v140, v140
	v_add_f32_e32 v136, 1.0, v136
	v_rcp_f32_e32 v141, v141
	v_add_f32_e32 v137, 1.0, v137
	v_pk_mul_f32 v[164:165], v[152:153], v[164:165]
	v_rcp_f32_e32 v136, v136
	v_rcp_f32_e32 v137, v137
	v_cvt_pk_bf16_f32 v152, v156, v157
	v_cvt_pk_bf16_f32 v153, v162, v163
	v_cvt_pk_bf16_f32 v154, v158, v159
	v_cvt_pk_bf16_f32 v155, v164, v165
	flat_store_dwordx4 v[160:161], v[152:155] offset:256
	v_add_f32_e32 v132, v4, v132
	v_add_f32_e32 v133, v5, v133
	v_and_b32_e32 v153, 0xffff0000, v148
	v_lshlrev_b32_e32 v152, 16, v148
	v_pk_mul_f32 v[140:141], v[140:141], v[152:153]
	v_and_b32_e32 v153, 0xffff0000, v150
	v_lshlrev_b32_e32 v152, 16, v150
	v_pk_mul_f32 v[152:153], v[136:137], v[152:153]
	v_add_f32_e32 v137, v10, v138
	v_mul_f32_e32 v137, 0xbfb8aa3b, v137
	v_exp_f32_e32 v137, v137
	v_add_f32_e32 v136, v14, v142
	v_mul_f32_e32 v136, 0xbfb8aa3b, v136
	v_exp_f32_e32 v136, v136
	v_add_f32_e32 v137, 1.0, v137
	v_rcp_f32_e32 v138, v137
	v_add_f32_e32 v137, v15, v143
	v_mul_f32_e32 v137, 0xbfb8aa3b, v137
	v_exp_f32_e32 v137, v137
	v_add_f32_e32 v136, 1.0, v136
	v_rcp_f32_e32 v136, v136
	v_and_b32_e32 v143, 0xffff0000, v149
	v_add_f32_e32 v137, 1.0, v137
	v_rcp_f32_e32 v137, v137
	v_lshlrev_b32_e32 v142, 16, v149
	v_mul_f32_e32 v132, 0xbfb8aa3b, v132
	v_add_f32_e32 v128, v0, v128
	v_pk_mul_f32 v[142:143], v[136:137], v[142:143]
	v_add_f32_e32 v136, v11, v139
	v_mul_f32_e32 v136, 0xbfb8aa3b, v136
	v_exp_f32_e32 v136, v136
	v_mul_f32_e32 v133, 0xbfb8aa3b, v133
	v_add_f32_e32 v129, v1, v129
	v_exp_f32_e32 v132, v132
	v_add_f32_e32 v136, 1.0, v136
	v_rcp_f32_e32 v139, v136
	v_mul_f32_e32 v128, 0xbfb8aa3b, v128
	v_exp_f32_e32 v133, v133
	v_mul_f32_e32 v129, 0xbfb8aa3b, v129
	v_exp_f32_e32 v128, v128
	v_exp_f32_e32 v129, v129
	v_and_b32_e32 v137, 0xffff0000, v151
	v_lshlrev_b32_e32 v136, 16, v151
	v_pk_mul_f32 v[148:149], v[138:139], v[136:137]
	v_cvt_pk_bf16_f32 v136, v140, v141
	v_cvt_pk_bf16_f32 v137, v142, v143
	v_mul_lo_u32 v142, s50, v173
	v_mul_lo_u32 v143, s51, v172
	v_mad_u64_u32 v[140:141], s[8:9], s50, v172, 0
	v_add_f32_e32 v132, 1.0, v132
	v_add_f32_e32 v133, 1.0, v133
	v_add3_u32 v141, v141, v142, v143
	v_rcp_f32_e32 v132, v132
	v_add_f32_e32 v128, 1.0, v128
	v_rcp_f32_e32 v133, v133
	v_add_f32_e32 v129, 1.0, v129
	v_lshl_add_u64 v[140:141], v[140:141], 1, s[60:61]
	v_rcp_f32_e32 v128, v128
	v_rcp_f32_e32 v129, v129
	v_cvt_pk_bf16_f32 v138, v152, v153
	v_cvt_pk_bf16_f32 v139, v148, v149
	v_lshl_add_u64 v[140:141], v[140:141], 0, v[192:193]
	flat_store_dwordx4 v[140:141], v[136:139]
	s_nop 1
	v_and_b32_e32 v137, 0xffff0000, v144
	v_lshlrev_b32_e32 v136, 16, v144
	v_pk_mul_f32 v[132:133], v[132:133], v[136:137]
	v_and_b32_e32 v137, 0xffff0000, v146
	v_lshlrev_b32_e32 v136, 16, v146
	v_pk_mul_f32 v[136:137], v[128:129], v[136:137]
	v_add_f32_e32 v129, v2, v130
	v_mul_f32_e32 v129, 0xbfb8aa3b, v129
	v_exp_f32_e32 v129, v129
	v_add_f32_e32 v128, v6, v134
	v_mul_f32_e32 v128, 0xbfb8aa3b, v128
	v_exp_f32_e32 v128, v128
	v_add_f32_e32 v129, 1.0, v129
	v_rcp_f32_e32 v130, v129
	v_add_f32_e32 v129, v7, v135
	v_mul_f32_e32 v129, 0xbfb8aa3b, v129
	v_exp_f32_e32 v129, v129
	v_add_f32_e32 v128, 1.0, v128
	v_rcp_f32_e32 v128, v128
	v_and_b32_e32 v135, 0xffff0000, v145
	v_add_f32_e32 v129, 1.0, v129
	v_rcp_f32_e32 v129, v129
	v_lshlrev_b32_e32 v134, 16, v145
	v_pk_mul_f32 v[134:135], v[128:129], v[134:135]
	v_add_f32_e32 v128, v3, v131
	v_mul_f32_e32 v128, 0xbfb8aa3b, v128
	v_exp_f32_e32 v128, v128
	v_and_b32_e32 v129, 0xffff0000, v147
	v_add_f32_e32 v128, 1.0, v128
	v_rcp_f32_e32 v131, v128
	v_lshlrev_b32_e32 v128, 16, v147
	v_pk_mul_f32 v[138:139], v[130:131], v[128:129]
	v_cvt_pk_bf16_f32 v128, v132, v133
	v_cvt_pk_bf16_f32 v129, v134, v135
	v_cvt_pk_bf16_f32 v130, v136, v137
	v_cvt_pk_bf16_f32 v131, v138, v139
	flat_store_dwordx4 v[140:141], v[128:131] offset:256
	s_cbranch_execz .LBB0_140
	s_branch .LBB0_141

.LBB0_140:
	v_lshl_or_b32 v128, s92, 8, v230
	v_ashrrev_i32_e32 v129, 31, v128
	v_lshlrev_b64 v[128:129], 1, v[128:129]
	v_lshl_add_u64 v[154:155], s[62:63], 0, v[128:129]
	v_lshl_add_u64 v[152:153], s[60:61], 0, v[128:129]
	v_ashrrev_i32_e32 v128, 31, v190
	v_mul_lo_u32 v130, s51, v190
	v_mul_lo_u32 v134, s50, v128
	v_mad_u64_u32 v[128:129], s[8:9], s50, v190, 0
	v_add3_u32 v129, v129, v134, v130
	v_lshlrev_b64 v[170:171], 1, v[128:129]
	v_lshl_add_u64 v[128:129], v[154:155], 0, v[170:171]
	global_load_dwordx4 v[162:165], v[128:129], off
	global_load_dwordx4 v[166:169], v[128:129], off offset:256
	v_or_b32_e32 v128, 16, v190
	v_mul_lo_u32 v130, s51, v128
	v_mad_u64_u32 v[128:129], s[8:9], s50, v128, 0
	v_add3_u32 v129, v129, v134, v130
	v_lshlrev_b64 v[160:161], 1, v[128:129]
	v_lshl_add_u64 v[128:129], v[154:155], 0, v[160:161]
	global_load_dwordx4 v[148:151], v[128:129], off
	global_load_dwordx4 v[144:147], v[128:129], off offset:256
	v_or_b32_e32 v128, 32, v190
	v_mul_lo_u32 v130, s51, v128
	v_mad_u64_u32 v[128:129], s[8:9], s50, v128, 0
	v_add3_u32 v129, v129, v134, v130
	v_lshlrev_b64 v[156:157], 1, v[128:129]
	v_lshl_add_u64 v[128:129], v[154:155], 0, v[156:157]
	global_load_dwordx4 v[136:139], v[128:129], off
	s_nop 0
	global_load_dwordx4 v[128:131], v[128:129], off offset:256
	v_or_b32_e32 v132, 48, v190
	v_mul_lo_u32 v135, s51, v132
	v_mad_u64_u32 v[132:133], s[8:9], s50, v132, 0
	v_add3_u32 v133, v133, v134, v135
	v_lshlrev_b64 v[158:159], 1, v[132:133]
	v_lshl_add_u64 v[132:133], v[154:155], 0, v[158:159]
	global_load_dwordx4 v[140:143], v[132:133], off
	s_nop 0
	global_load_dwordx4 v[132:135], v[132:133], off offset:256
	v_lshl_add_u64 v[170:171], v[152:153], 0, v[170:171]
	v_lshl_add_u64 v[160:161], v[152:153], 0, v[160:161]
	s_waitcnt vmcnt(0) lgkmcnt(0)
	v_and_b32_e32 v173, 0xffff0000, v162
	v_lshlrev_b32_e32 v172, 16, v162
	v_and_b32_e32 v175, 0xffff0000, v164
	v_lshlrev_b32_e32 v174, 16, v164
	v_and_b32_e32 v193, 0xffff0000, v163
	v_lshlrev_b32_e32 v192, 16, v163
	v_and_b32_e32 v163, 0xffff0000, v165
	v_lshlrev_b32_e32 v162, 16, v165
	v_pk_fma_f32 v[172:173], v[172:173], s[34:35], v[124:125] op_sel_hi:[1,0,1]
	v_pk_fma_f32 v[174:175], v[174:175], s[34:35], v[120:121] op_sel_hi:[1,0,1]
	v_pk_fma_f32 v[192:193], v[192:193], s[34:35], v[126:127] op_sel_hi:[1,0,1]
	v_pk_fma_f32 v[194:195], v[162:163], s[34:35], v[122:123] op_sel_hi:[1,0,1]
	v_cvt_pk_bf16_f32 v162, v172, v173
	v_cvt_pk_bf16_f32 v163, v192, v193
	v_cvt_pk_bf16_f32 v164, v174, v175
	v_cvt_pk_bf16_f32 v165, v194, v195
	v_and_b32_e32 v173, 0xffff0000, v167
	v_lshlrev_b32_e32 v172, 16, v167
	flat_store_dwordx4 v[170:171], v[162:165]
	s_nop 1
	v_and_b32_e32 v163, 0xffff0000, v166
	v_lshlrev_b32_e32 v162, 16, v166
	v_and_b32_e32 v165, 0xffff0000, v168
	v_lshlrev_b32_e32 v164, 16, v168
	v_pk_fma_f32 v[166:167], v[172:173], s[34:35], v[118:119] op_sel_hi:[1,0,1]
	v_and_b32_e32 v173, 0xffff0000, v169
	v_lshlrev_b32_e32 v172, 16, v169
	v_pk_fma_f32 v[162:163], v[162:163], s[34:35], v[116:117] op_sel_hi:[1,0,1]
	v_pk_fma_f32 v[164:165], v[164:165], s[34:35], v[112:113] op_sel_hi:[1,0,1]
	v_pk_fma_f32 v[168:169], v[172:173], s[34:35], v[114:115] op_sel_hi:[1,0,1]
	v_cvt_pk_bf16_f32 v162, v162, v163
	v_cvt_pk_bf16_f32 v163, v166, v167
	v_cvt_pk_bf16_f32 v164, v164, v165
	v_cvt_pk_bf16_f32 v165, v168, v169
	flat_store_dwordx4 v[170:171], v[162:165] offset:256
	v_and_b32_e32 v167, 0xffff0000, v149
	v_lshlrev_b32_e32 v166, 16, v149
	v_and_b32_e32 v163, 0xffff0000, v148
	v_lshlrev_b32_e32 v162, 16, v148
	v_and_b32_e32 v165, 0xffff0000, v150
	v_lshlrev_b32_e32 v164, 16, v150
	v_and_b32_e32 v149, 0xffff0000, v151
	v_lshlrev_b32_e32 v148, 16, v151
	v_pk_fma_f32 v[162:163], v[162:163], s[34:35], v[108:109] op_sel_hi:[1,0,1]
	v_pk_fma_f32 v[164:165], v[164:165], s[34:35], v[104:105] op_sel_hi:[1,0,1]
	v_pk_fma_f32 v[166:167], v[166:167], s[34:35], v[110:111] op_sel_hi:[1,0,1]
	v_pk_fma_f32 v[168:169], v[148:149], s[34:35], v[106:107] op_sel_hi:[1,0,1]
	v_cvt_pk_bf16_f32 v148, v162, v163
	v_cvt_pk_bf16_f32 v149, v166, v167
	v_cvt_pk_bf16_f32 v150, v164, v165
	v_cvt_pk_bf16_f32 v151, v168, v169
	flat_store_dwordx4 v[160:161], v[148:151]
	v_and_b32_e32 v163, 0xffff0000, v145
	v_lshlrev_b32_e32 v162, 16, v145
	v_and_b32_e32 v149, 0xffff0000, v144
	v_lshlrev_b32_e32 v148, 16, v144
	v_and_b32_e32 v151, 0xffff0000, v146
	v_lshlrev_b32_e32 v150, 16, v146
	v_and_b32_e32 v145, 0xffff0000, v147
	v_lshlrev_b32_e32 v144, 16, v147
	v_pk_fma_f32 v[148:149], v[148:149], s[34:35], v[100:101] op_sel_hi:[1,0,1]
	v_pk_fma_f32 v[150:151], v[150:151], s[34:35], v[96:97] op_sel_hi:[1,0,1]
	v_pk_fma_f32 v[162:163], v[162:163], s[34:35], v[102:103] op_sel_hi:[1,0,1]
	v_pk_fma_f32 v[164:165], v[144:145], s[34:35], v[98:99] op_sel_hi:[1,0,1]
	v_cvt_pk_bf16_f32 v144, v148, v149
	v_cvt_pk_bf16_f32 v145, v162, v163
	v_cvt_pk_bf16_f32 v146, v150, v151
	v_cvt_pk_bf16_f32 v147, v164, v165
	flat_store_dwordx4 v[160:161], v[144:147] offset:256
	v_and_b32_e32 v149, 0xffff0000, v138
	v_lshlrev_b32_e32 v148, 16, v138
	v_and_b32_e32 v147, 0xffff0000, v136
	v_lshlrev_b32_e32 v146, 16, v136
	v_and_b32_e32 v151, 0xffff0000, v137
	v_lshlrev_b32_e32 v150, 16, v137
	v_and_b32_e32 v137, 0xffff0000, v139
	v_lshlrev_b32_e32 v136, 16, v139
	v_lshl_add_u64 v[144:145], v[152:153], 0, v[156:157]
	v_pk_fma_f32 v[146:147], v[146:147], s[34:35], v[92:93] op_sel_hi:[1,0,1]
	v_pk_fma_f32 v[148:149], v[148:149], s[34:35], v[88:89] op_sel_hi:[1,0,1]
	v_pk_fma_f32 v[150:151], v[150:151], s[34:35], v[94:95] op_sel_hi:[1,0,1]
	v_pk_fma_f32 v[156:157], v[136:137], s[34:35], v[90:91] op_sel_hi:[1,0,1]
	v_cvt_pk_bf16_f32 v136, v146, v147
	v_cvt_pk_bf16_f32 v137, v150, v151
	v_cvt_pk_bf16_f32 v138, v148, v149
	v_cvt_pk_bf16_f32 v139, v156, v157
	flat_store_dwordx4 v[144:145], v[136:139]
	v_and_b32_e32 v147, 0xffff0000, v129
	v_lshlrev_b32_e32 v146, 16, v129
	v_and_b32_e32 v137, 0xffff0000, v128
	v_lshlrev_b32_e32 v136, 16, v128
	v_and_b32_e32 v139, 0xffff0000, v130
	v_lshlrev_b32_e32 v138, 16, v130
	v_and_b32_e32 v129, 0xffff0000, v131
	v_lshlrev_b32_e32 v128, 16, v131
	v_pk_fma_f32 v[136:137], v[136:137], s[34:35], v[84:85] op_sel_hi:[1,0,1]
	v_pk_fma_f32 v[138:139], v[138:139], s[34:35], v[80:81] op_sel_hi:[1,0,1]
	v_pk_fma_f32 v[146:147], v[146:147], s[34:35], v[86:87] op_sel_hi:[1,0,1]
	v_pk_fma_f32 v[148:149], v[128:129], s[34:35], v[82:83] op_sel_hi:[1,0,1]
	v_cvt_pk_bf16_f32 v128, v136, v137
	v_cvt_pk_bf16_f32 v129, v146, v147
	v_cvt_pk_bf16_f32 v130, v138, v139
	v_cvt_pk_bf16_f32 v131, v148, v149
	flat_store_dwordx4 v[144:145], v[128:131] offset:256
	v_and_b32_e32 v139, 0xffff0000, v141
	v_lshlrev_b32_e32 v138, 16, v141
	v_and_b32_e32 v129, 0xffff0000, v140
	v_lshlrev_b32_e32 v128, 16, v140
	v_and_b32_e32 v131, 0xffff0000, v142
	v_lshlrev_b32_e32 v130, 16, v142
	v_and_b32_e32 v141, 0xffff0000, v143
	v_lshlrev_b32_e32 v140, 16, v143
	v_pk_fma_f32 v[128:129], v[128:129], s[34:35], v[76:77] op_sel_hi:[1,0,1]
	v_pk_fma_f32 v[130:131], v[130:131], s[34:35], v[72:73] op_sel_hi:[1,0,1]
	v_pk_fma_f32 v[138:139], v[138:139], s[34:35], v[78:79] op_sel_hi:[1,0,1]
	v_pk_fma_f32 v[140:141], v[140:141], s[34:35], v[74:75] op_sel_hi:[1,0,1]
	v_lshl_add_u64 v[136:137], v[152:153], 0, v[158:159]
	v_cvt_pk_bf16_f32 v128, v128, v129
	v_cvt_pk_bf16_f32 v129, v138, v139
	v_cvt_pk_bf16_f32 v130, v130, v131
	v_cvt_pk_bf16_f32 v131, v140, v141
	v_and_b32_e32 v139, 0xffff0000, v133
	v_lshlrev_b32_e32 v138, 16, v133
	flat_store_dwordx4 v[136:137], v[128:131]
	s_nop 1
	v_and_b32_e32 v129, 0xffff0000, v132
	v_lshlrev_b32_e32 v128, 16, v132
	v_and_b32_e32 v131, 0xffff0000, v134
	v_lshlrev_b32_e32 v130, 16, v134
	v_pk_fma_f32 v[132:133], v[138:139], s[34:35], v[70:71] op_sel_hi:[1,0,1]
	v_and_b32_e32 v139, 0xffff0000, v135
	v_lshlrev_b32_e32 v138, 16, v135
	v_pk_fma_f32 v[128:129], v[128:129], s[34:35], v[68:69] op_sel_hi:[1,0,1]
	v_pk_fma_f32 v[130:131], v[130:131], s[34:35], v[64:65] op_sel_hi:[1,0,1]
	v_pk_fma_f32 v[134:135], v[138:139], s[34:35], v[66:67] op_sel_hi:[1,0,1]
	v_cvt_pk_bf16_f32 v128, v128, v129
	v_cvt_pk_bf16_f32 v129, v132, v133
	v_cvt_pk_bf16_f32 v130, v130, v131
	v_cvt_pk_bf16_f32 v131, v134, v135
	flat_store_dwordx4 v[136:137], v[128:131] offset:256
	s_nop 1
	v_add_u32_e32 v128, 0x80, v190
	v_ashrrev_i32_e32 v129, 31, v128
	v_mul_lo_u32 v130, s50, v129
	v_mul_lo_u32 v131, s51, v128
	v_mad_u64_u32 v[128:129], s[8:9], s50, v128, 0
	v_add3_u32 v129, v129, v130, v131
	v_lshlrev_b64 v[164:165], 1, v[128:129]
	v_lshl_add_u64 v[128:129], v[154:155], 0, v[164:165]
	global_load_dwordx4 v[132:135], v[128:129], off
	global_load_dwordx4 v[136:139], v[128:129], off offset:256
	v_add_u32_e32 v128, 0x90, v190
	v_ashrrev_i32_e32 v129, 31, v128
	v_mul_lo_u32 v130, s50, v129
	v_mul_lo_u32 v131, s51, v128
	v_mad_u64_u32 v[128:129], s[8:9], s50, v128, 0
	v_add3_u32 v129, v129, v130, v131
	v_lshlrev_b64 v[166:167], 1, v[128:129]
	v_lshl_add_u64 v[128:129], v[154:155], 0, v[166:167]
	global_load_dwordx4 v[140:143], v[128:129], off
	global_load_dwordx4 v[144:147], v[128:129], off offset:256
	v_add_u32_e32 v128, 0xa0, v190
	v_ashrrev_i32_e32 v129, 31, v128
	v_mul_lo_u32 v130, s50, v129
	v_mul_lo_u32 v131, s51, v128
	v_mad_u64_u32 v[128:129], s[8:9], s50, v128, 0
	v_add3_u32 v129, v129, v130, v131
	v_lshlrev_b64 v[168:169], 1, v[128:129]
	v_lshl_add_u64 v[128:129], v[154:155], 0, v[168:169]
	global_load_dwordx4 v[148:151], v[128:129], off
	global_load_dwordx4 v[156:159], v[128:129], off offset:256
	v_add_u32_e32 v128, 0xb0, v190
	v_ashrrev_i32_e32 v129, 31, v128
	v_mul_lo_u32 v130, s50, v129
	v_mul_lo_u32 v131, s51, v128
	v_mad_u64_u32 v[128:129], s[8:9], s50, v128, 0
	v_add3_u32 v129, v129, v130, v131
	v_lshlrev_b64 v[170:171], 1, v[128:129]
	v_lshl_add_u64 v[128:129], v[154:155], 0, v[170:171]
	global_load_dwordx4 v[160:163], v[128:129], off
	s_nop 0
	global_load_dwordx4 v[128:131], v[128:129], off offset:256
	v_lshl_add_u64 v[154:155], v[152:153], 0, v[164:165]
	s_waitcnt vmcnt(0) lgkmcnt(0)
	v_and_b32_e32 v165, 0xffff0000, v132
	v_lshlrev_b32_e32 v164, 16, v132
	v_and_b32_e32 v173, 0xffff0000, v134
	v_lshlrev_b32_e32 v172, 16, v134
	v_and_b32_e32 v175, 0xffff0000, v133
	v_lshlrev_b32_e32 v174, 16, v133
	v_and_b32_e32 v133, 0xffff0000, v135
	v_lshlrev_b32_e32 v132, 16, v135
	v_pk_fma_f32 v[164:165], v[164:165], s[34:35], v[60:61] op_sel_hi:[1,0,1]
	v_pk_fma_f32 v[172:173], v[172:173], s[34:35], v[56:57] op_sel_hi:[1,0,1]
	v_pk_fma_f32 v[174:175], v[174:175], s[34:35], v[62:63] op_sel_hi:[1,0,1]
	v_pk_fma_f32 v[192:193], v[132:133], s[34:35], v[58:59] op_sel_hi:[1,0,1]
	v_cvt_pk_bf16_f32 v132, v164, v165
	v_cvt_pk_bf16_f32 v133, v174, v175
	v_cvt_pk_bf16_f32 v134, v172, v173
	v_cvt_pk_bf16_f32 v135, v192, v193
	v_and_b32_e32 v165, 0xffff0000, v137
	v_lshlrev_b32_e32 v164, 16, v137
	flat_store_dwordx4 v[154:155], v[132:135]
	s_nop 1
	v_and_b32_e32 v133, 0xffff0000, v136
	v_lshlrev_b32_e32 v132, 16, v136
	v_and_b32_e32 v135, 0xffff0000, v138
	v_lshlrev_b32_e32 v134, 16, v138
	v_pk_fma_f32 v[136:137], v[164:165], s[34:35], v[54:55] op_sel_hi:[1,0,1]
	v_and_b32_e32 v165, 0xffff0000, v139
	v_lshlrev_b32_e32 v164, 16, v139
	v_pk_fma_f32 v[132:133], v[132:133], s[34:35], v[52:53] op_sel_hi:[1,0,1]
	v_pk_fma_f32 v[134:135], v[134:135], s[34:35], v[48:49] op_sel_hi:[1,0,1]
	v_pk_fma_f32 v[138:139], v[164:165], s[34:35], v[50:51] op_sel_hi:[1,0,1]
	v_cvt_pk_bf16_f32 v132, v132, v133
	v_cvt_pk_bf16_f32 v133, v136, v137
	v_cvt_pk_bf16_f32 v134, v134, v135
	v_cvt_pk_bf16_f32 v135, v138, v139
	flat_store_dwordx4 v[154:155], v[132:135] offset:256
	v_and_b32_e32 v139, 0xffff0000, v141
	v_lshlrev_b32_e32 v138, 16, v141
	v_and_b32_e32 v133, 0xffff0000, v140
	v_lshlrev_b32_e32 v132, 16, v140
	v_and_b32_e32 v135, 0xffff0000, v142
	v_lshlrev_b32_e32 v134, 16, v142
	v_and_b32_e32 v141, 0xffff0000, v143
	v_lshlrev_b32_e32 v140, 16, v143
	v_pk_fma_f32 v[132:133], v[132:133], s[34:35], v[44:45] op_sel_hi:[1,0,1]
	v_pk_fma_f32 v[134:135], v[134:135], s[34:35], v[40:41] op_sel_hi:[1,0,1]
	v_pk_fma_f32 v[138:139], v[138:139], s[34:35], v[46:47] op_sel_hi:[1,0,1]
	v_pk_fma_f32 v[140:141], v[140:141], s[34:35], v[42:43] op_sel_hi:[1,0,1]
	v_lshl_add_u64 v[136:137], v[152:153], 0, v[166:167]
	v_cvt_pk_bf16_f32 v132, v132, v133
	v_cvt_pk_bf16_f32 v133, v138, v139
	v_cvt_pk_bf16_f32 v134, v134, v135
	v_cvt_pk_bf16_f32 v135, v140, v141
	flat_store_dwordx4 v[136:137], v[132:135]
	v_and_b32_e32 v139, 0xffff0000, v145
	v_lshlrev_b32_e32 v138, 16, v145
	v_and_b32_e32 v133, 0xffff0000, v144
	v_lshlrev_b32_e32 v132, 16, v144
	v_and_b32_e32 v135, 0xffff0000, v146
	v_lshlrev_b32_e32 v134, 16, v146
	v_and_b32_e32 v141, 0xffff0000, v147
	v_lshlrev_b32_e32 v140, 16, v147
	v_pk_fma_f32 v[132:133], v[132:133], s[34:35], v[36:37] op_sel_hi:[1,0,1]
	v_pk_fma_f32 v[134:135], v[134:135], s[34:35], v[32:33] op_sel_hi:[1,0,1]
	v_pk_fma_f32 v[138:139], v[138:139], s[34:35], v[38:39] op_sel_hi:[1,0,1]
	v_pk_fma_f32 v[140:141], v[140:141], s[34:35], v[34:35] op_sel_hi:[1,0,1]
	v_cvt_pk_bf16_f32 v132, v132, v133
	v_cvt_pk_bf16_f32 v133, v138, v139
	v_cvt_pk_bf16_f32 v134, v134, v135
	v_cvt_pk_bf16_f32 v135, v140, v141
	flat_store_dwordx4 v[136:137], v[132:135] offset:256
	v_and_b32_e32 v139, 0xffff0000, v149
	v_lshlrev_b32_e32 v138, 16, v149
	v_and_b32_e32 v133, 0xffff0000, v148
	v_lshlrev_b32_e32 v132, 16, v148
	v_and_b32_e32 v135, 0xffff0000, v150
	v_lshlrev_b32_e32 v134, 16, v150
	v_and_b32_e32 v141, 0xffff0000, v151
	v_lshlrev_b32_e32 v140, 16, v151
	v_pk_fma_f32 v[132:133], v[132:133], s[34:35], v[28:29] op_sel_hi:[1,0,1]
	v_pk_fma_f32 v[134:135], v[134:135], s[34:35], v[24:25] op_sel_hi:[1,0,1]
	v_pk_fma_f32 v[138:139], v[138:139], s[34:35], v[30:31] op_sel_hi:[1,0,1]
	v_pk_fma_f32 v[140:141], v[140:141], s[34:35], v[26:27] op_sel_hi:[1,0,1]
	v_lshl_add_u64 v[136:137], v[152:153], 0, v[168:169]
	v_cvt_pk_bf16_f32 v132, v132, v133
	v_cvt_pk_bf16_f32 v133, v138, v139
	v_cvt_pk_bf16_f32 v134, v134, v135
	v_cvt_pk_bf16_f32 v135, v140, v141
	flat_store_dwordx4 v[136:137], v[132:135]
	v_and_b32_e32 v139, 0xffff0000, v157
	v_lshlrev_b32_e32 v138, 16, v157
	v_and_b32_e32 v133, 0xffff0000, v156
	v_lshlrev_b32_e32 v132, 16, v156
	v_and_b32_e32 v135, 0xffff0000, v158
	v_lshlrev_b32_e32 v134, 16, v158
	v_and_b32_e32 v141, 0xffff0000, v159
	v_lshlrev_b32_e32 v140, 16, v159
	v_pk_fma_f32 v[132:133], v[132:133], s[34:35], v[20:21] op_sel_hi:[1,0,1]
	v_pk_fma_f32 v[134:135], v[134:135], s[34:35], v[16:17] op_sel_hi:[1,0,1]
	v_pk_fma_f32 v[138:139], v[138:139], s[34:35], v[22:23] op_sel_hi:[1,0,1]
	v_pk_fma_f32 v[140:141], v[140:141], s[34:35], v[18:19] op_sel_hi:[1,0,1]
	v_cvt_pk_bf16_f32 v132, v132, v133
	v_cvt_pk_bf16_f32 v133, v138, v139
	v_cvt_pk_bf16_f32 v134, v134, v135
	v_cvt_pk_bf16_f32 v135, v140, v141
	flat_store_dwordx4 v[136:137], v[132:135] offset:256
	v_and_b32_e32 v139, 0xffff0000, v161
	v_lshlrev_b32_e32 v138, 16, v161
	v_and_b32_e32 v133, 0xffff0000, v160
	v_lshlrev_b32_e32 v132, 16, v160
	v_and_b32_e32 v135, 0xffff0000, v162
	v_lshlrev_b32_e32 v134, 16, v162
	v_and_b32_e32 v141, 0xffff0000, v163
	v_lshlrev_b32_e32 v140, 16, v163
	v_pk_fma_f32 v[132:133], v[132:133], s[34:35], v[12:13] op_sel_hi:[1,0,1]
	v_pk_fma_f32 v[134:135], v[134:135], s[34:35], v[8:9] op_sel_hi:[1,0,1]
	v_pk_fma_f32 v[138:139], v[138:139], s[34:35], v[14:15] op_sel_hi:[1,0,1]
	v_pk_fma_f32 v[140:141], v[140:141], s[34:35], v[10:11] op_sel_hi:[1,0,1]
	v_lshl_add_u64 v[136:137], v[152:153], 0, v[170:171]
	v_cvt_pk_bf16_f32 v132, v132, v133
	v_cvt_pk_bf16_f32 v133, v138, v139
	v_cvt_pk_bf16_f32 v134, v134, v135
	v_cvt_pk_bf16_f32 v135, v140, v141
	flat_store_dwordx4 v[136:137], v[132:135]
	v_and_b32_e32 v139, 0xffff0000, v129
	v_lshlrev_b32_e32 v138, 16, v129
	v_and_b32_e32 v133, 0xffff0000, v128
	v_lshlrev_b32_e32 v132, 16, v128
	v_and_b32_e32 v135, 0xffff0000, v130
	v_lshlrev_b32_e32 v134, 16, v130
	v_and_b32_e32 v129, 0xffff0000, v131
	v_lshlrev_b32_e32 v128, 16, v131
	v_pk_fma_f32 v[132:133], v[132:133], s[34:35], v[4:5] op_sel_hi:[1,0,1]
	v_pk_fma_f32 v[134:135], v[134:135], s[34:35], v[0:1] op_sel_hi:[1,0,1]
	v_pk_fma_f32 v[138:139], v[138:139], s[34:35], v[6:7] op_sel_hi:[1,0,1]
	v_pk_fma_f32 v[140:141], v[128:129], s[34:35], v[2:3] op_sel_hi:[1,0,1]
	v_cvt_pk_bf16_f32 v128, v132, v133
	v_cvt_pk_bf16_f32 v129, v138, v139
	v_cvt_pk_bf16_f32 v130, v134, v135
	v_cvt_pk_bf16_f32 v131, v140, v141
	flat_store_dwordx4 v[136:137], v[128:131] offset:256

.LBB0_206:
	v_mul_f32_e32 v78, 0x3fb8aa3b, v91
	v_rndne_f32_e32 v79, v78
	s_mov_b32 s6, 0x3fb8aa3b
	v_sub_f32_e32 v80, v78, v79
	v_fma_f32 v78, v91, s6, -v78
	v_fmac_f32_e32 v78, 0x32a5705f, v91
	v_add_f32_e32 v78, v80, v78
	v_exp_f32_e32 v78, v78
	v_cvt_i32_f32_e32 v79, v79
	s_mov_b32 s6, 0xc2ce8ed0
	v_cmp_ngt_f32_e32 vcc, s6, v91
	s_mov_b32 s6, 0x42b17218
	v_ldexp_f32 v78, v78, v79
	s_waitcnt vmcnt(0)
	v_xor_b32_e32 v11, 0x80000000, v11
	v_xor_b32_e32 v10, 0x80000000, v10
	s_waitcnt vmcnt(1)
	v_xor_b32_e32 v15, 0x80000000, v15
	v_xor_b32_e32 v14, 0x80000000, v14
	v_cndmask_b32_e32 v78, 0, v78, vcc
	v_cmp_nlt_f32_e32 vcc, s6, v91
	v_cvt_pk_bf16_f32 v10, v10, v11
	v_xor_b32_e32 v11, 0x80000000, v12
	v_xor_b32_e32 v12, 0x80000000, v13
	v_cvt_pk_bf16_f32 v14, v14, v15
	v_xor_b32_e32 v15, 0x80000000, v16
	v_xor_b32_e32 v16, 0x80000000, v17
	s_ashr_i32 s9, s8, 31
	s_lshl_b32 s6, s12, 6
	v_cvt_pk_bf16_f32 v11, v11, v12
	s_waitcnt vmcnt(0)
	v_xor_b32_e32 v12, 0x80000000, v19
	v_xor_b32_e32 v13, 0x80000000, v18
	v_cvt_pk_bf16_f32 v15, v15, v16
	v_lshl_add_u64 v[16:17], v[66:67], 0, s[10:11]
	s_lshl_b64 s[8:9], s[8:9], 11
	s_ashr_i32 s10, s6, 31
	v_cvt_pk_bf16_f32 v6, v6, v7
	v_cvt_pk_bf16_f32 v7, v8, v9
	v_xor_b32_e32 v8, 0x80000000, v23
	v_xor_b32_e32 v9, 0x80000000, v22
	v_cvt_pk_bf16_f32 v12, v13, v12
	v_xor_b32_e32 v13, 0x80000000, v20
	v_xor_b32_e32 v18, 0x80000000, v21
	s_add_u32 s8, s8, s6
	v_cvt_pk_bf16_f32 v8, v9, v8
	v_xor_b32_e32 v9, 0x80000000, v24
	v_cvt_pk_bf16_f32 v13, v13, v18
	global_load_dword v24, v[16:17], off
	v_or_b32_e32 v18, s8, v128
	v_mov_b64_e32 v[16:17], s[26:27]
	s_movk_i32 s6, 0x1e00
	s_addc_u32 s9, s9, s10
	v_mad_u64_u32 v[16:17], s[10:11], v18, s6, v[16:17]
	v_mad_i32_i24 v17, s9, v210, v17
	s_lshl_b32 s6, s38, 5
	v_xor_b32_e32 v22, 0x80000000, v25
	v_lshl_add_u64 v[20:21], v[16:17], 0, s[6:7]
	v_cvt_pk_bf16_f32 v9, v9, v22
	global_load_dwordx4 v[16:19], v[20:21], off
	s_nop 0
	global_load_dwordx4 v[20:23], v[20:21], off offset:16
	v_cndmask_b32_e32 v79, v209, v78, vcc
	v_mul_f32_e32 v81, v79, v82
	v_fma_f32 v80, v79, v83, -1.0
	v_mov_b32_e32 v82, v5
	v_mul_f32_e32 v78, v79, v83
	v_pk_mul_f32 v[84:85], v[4:5], v[4:5]
	v_pk_mul_f32 v[82:83], v[82:83], v[80:81] op_sel:[0,1] op_sel_hi:[0,0]
	v_pk_fma_f32 v[92:93], v[4:5], v[80:81], v[82:83]
	v_pk_fma_f32 v[4:5], v[4:5], v[80:81], v[82:83] op_sel_hi:[0,1,1] neg_lo:[0,0,1] neg_hi:[0,0,1]
	v_pk_add_f32 v[82:83], v[84:85], v[84:85] op_sel:[0,1] op_sel_hi:[0,1]
	v_div_scale_f32 v4, s[14:15], v83, v83, v5
	v_rcp_f32_e32 v79, v4
	s_mov_b32 s10, s21
	v_fma_f32 v80, -v4, v79, 1.0
	v_fmac_f32_e32 v79, v80, v79
	v_div_scale_f32 v80, vcc, v5, v83, v5
	v_mul_f32_e32 v84, v80, v79
	v_fma_f32 v85, -v4, v84, v80
	v_fmac_f32_e32 v84, v85, v79
	v_fma_f32 v4, -v4, v84, v80
	v_div_fmas_f32 v4, v4, v79, v84
	v_div_fixup_f32 v5, v4, v83, v5
	v_div_scale_f32 v4, s[14:15], v82, v82, v92
	v_rcp_f32_e32 v79, v4
	s_nop 0
	v_fma_f32 v80, -v4, v79, 1.0
	v_fmac_f32_e32 v79, v80, v79
	v_div_scale_f32 v80, vcc, v92, v82, v92
	v_mul_f32_e32 v83, v80, v79
	v_fma_f32 v84, -v4, v83, v80
	v_fmac_f32_e32 v83, v84, v79
	v_fma_f32 v4, -v4, v83, v80
	v_div_fmas_f32 v4, v4, v79, v83
	v_div_fixup_f32 v4, v4, v82, v92
	v_pk_mul_f32 v[84:85], v[4:5], v[62:63] op_sel:[1,0] op_sel_hi:[0,0]
	v_pk_fma_f32 v[82:83], v[4:5], v[58:59], v[84:85] neg_lo:[0,0,1] neg_hi:[0,0,1]
	v_pk_fma_f32 v[84:85], v[4:5], v[58:59], v[84:85] op_sel_hi:[1,0,1]
	v_mov_b32_e32 v80, v61
	v_mov_b32_e32 v83, v85
	v_pk_mul_f32 v[84:85], v[4:5], v[62:63] op_sel:[1,1] op_sel_hi:[0,1]
	v_pk_fma_f32 v[62:63], v[4:5], v[58:59], v[84:85] op_sel:[0,1,0] neg_lo:[0,0,1] neg_hi:[0,0,1]
	v_pk_fma_f32 v[58:59], v[4:5], v[58:59], v[84:85] op_sel:[0,1,0]
	v_pk_mul_f32 v[84:85], v[4:5], v[64:65] op_sel:[1,0] op_sel_hi:[0,0]
	v_mov_b32_e32 v63, v59
	v_pk_fma_f32 v[58:59], v[4:5], v[60:61], v[84:85] neg_lo:[0,0,1] neg_hi:[0,0,1]
	v_pk_fma_f32 v[84:85], v[4:5], v[60:61], v[84:85] op_sel_hi:[1,0,1]
	v_mov_b32_e32 v60, v65
	v_pk_mul_f32 v[64:65], v[4:5], v[60:61] op_sel:[1,0] op_sel_hi:[0,0]
	v_mov_b32_e32 v59, v85
	v_pk_fma_f32 v[60:61], v[4:5], v[80:81], v[64:65] op_sel_hi:[1,0,1] neg_lo:[0,0,1] neg_hi:[0,0,1]
	v_pk_fma_f32 v[64:65], v[4:5], v[80:81], v[64:65] op_sel_hi:[1,0,1]
	v_pk_mul_f32 v[84:85], v[4:5], v[54:55] op_sel:[1,0] op_sel_hi:[0,0]
	v_mov_b32_e32 v61, v65
	v_pk_fma_f32 v[64:65], v[4:5], v[50:51], v[84:85] neg_lo:[0,0,1] neg_hi:[0,0,1]
	v_pk_fma_f32 v[84:85], v[4:5], v[50:51], v[84:85] op_sel_hi:[1,0,1]
	v_mov_b32_e32 v50, v55
	v_pk_mul_f32 v[54:55], v[4:5], v[50:51] op_sel:[1,0] op_sel_hi:[0,0]
	v_mov_b32_e32 v80, v51
	v_mov_b32_e32 v65, v85
	v_pk_fma_f32 v[50:51], v[4:5], v[80:81], v[54:55] op_sel_hi:[1,0,1] neg_lo:[0,0,1] neg_hi:[0,0,1]
	v_pk_fma_f32 v[54:55], v[4:5], v[80:81], v[54:55] op_sel_hi:[1,0,1]
	v_pk_mul_f32 v[84:85], v[4:5], v[56:57] op_sel:[1,0] op_sel_hi:[0,0]
	v_mov_b32_e32 v51, v55
	v_pk_fma_f32 v[54:55], v[4:5], v[52:53], v[84:85] neg_lo:[0,0,1] neg_hi:[0,0,1]
	v_pk_fma_f32 v[84:85], v[4:5], v[52:53], v[84:85] op_sel_hi:[1,0,1]
	v_mov_b32_e32 v52, v57
	v_pk_mul_f32 v[56:57], v[4:5], v[52:53] op_sel:[1,0] op_sel_hi:[0,0]
	v_mov_b32_e32 v80, v53
	v_mov_b32_e32 v55, v85
	v_pk_fma_f32 v[52:53], v[4:5], v[80:81], v[56:57] op_sel_hi:[1,0,1] neg_lo:[0,0,1] neg_hi:[0,0,1]
	v_pk_fma_f32 v[56:57], v[4:5], v[80:81], v[56:57] op_sel_hi:[1,0,1]
	v_pk_mul_f32 v[84:85], v[4:5], v[46:47] op_sel:[1,0] op_sel_hi:[0,0]
	v_mov_b32_e32 v53, v57
	v_pk_fma_f32 v[56:57], v[4:5], v[42:43], v[84:85] neg_lo:[0,0,1] neg_hi:[0,0,1]
	v_pk_fma_f32 v[84:85], v[4:5], v[42:43], v[84:85] op_sel_hi:[1,0,1]
	v_mov_b32_e32 v42, v47
	v_pk_mul_f32 v[46:47], v[4:5], v[42:43] op_sel:[1,0] op_sel_hi:[0,0]
	v_mov_b32_e32 v80, v43
	v_mov_b32_e32 v57, v85
	v_pk_fma_f32 v[42:43], v[4:5], v[80:81], v[46:47] op_sel_hi:[1,0,1] neg_lo:[0,0,1] neg_hi:[0,0,1]
	v_pk_fma_f32 v[46:47], v[4:5], v[80:81], v[46:47] op_sel_hi:[1,0,1]
	v_pk_mul_f32 v[84:85], v[4:5], v[48:49] op_sel:[1,0] op_sel_hi:[0,0]
	v_mov_b32_e32 v43, v47
	v_pk_fma_f32 v[46:47], v[4:5], v[44:45], v[84:85] neg_lo:[0,0,1] neg_hi:[0,0,1]
	v_pk_fma_f32 v[84:85], v[4:5], v[44:45], v[84:85] op_sel_hi:[1,0,1]
	v_mov_b32_e32 v44, v49
	v_pk_mul_f32 v[48:49], v[4:5], v[44:45] op_sel:[1,0] op_sel_hi:[0,0]
	v_mov_b32_e32 v80, v45
	v_mov_b32_e32 v47, v85
	v_pk_fma_f32 v[44:45], v[4:5], v[80:81], v[48:49] op_sel_hi:[1,0,1] neg_lo:[0,0,1] neg_hi:[0,0,1]
	v_pk_fma_f32 v[48:49], v[4:5], v[80:81], v[48:49] op_sel_hi:[1,0,1]
	v_pk_mul_f32 v[84:85], v[4:5], v[34:35] op_sel:[1,0] op_sel_hi:[0,0]
	v_mov_b32_e32 v45, v49
	v_pk_fma_f32 v[48:49], v[4:5], v[0:1], v[84:85] neg_lo:[0,0,1] neg_hi:[0,0,1]
	v_pk_fma_f32 v[84:85], v[4:5], v[0:1], v[84:85] op_sel_hi:[1,0,1]
	v_mov_b32_e32 v0, v35
	v_mov_b32_e32 v49, v85
	v_pk_mul_f32 v[84:85], v[4:5], v[0:1] op_sel:[1,0] op_sel_hi:[0,0]
	v_mov_b32_e32 v0, v1
	v_pk_fma_f32 v[34:35], v[4:5], v[0:1], v[84:85] op_sel_hi:[1,0,1] neg_lo:[0,0,1] neg_hi:[0,0,1]
	v_pk_fma_f32 v[0:1], v[4:5], v[0:1], v[84:85] op_sel_hi:[1,0,1]
	v_mov_b32_e32 v79, v78
	v_mov_b32_e32 v35, v1
	v_pk_mul_f32 v[0:1], v[4:5], v[36:37] op_sel:[1,0] op_sel_hi:[0,0]
	v_pk_fma_f32 v[84:85], v[4:5], v[2:3], v[0:1] neg_lo:[0,0,1] neg_hi:[0,0,1]
	v_pk_fma_f32 v[0:1], v[4:5], v[2:3], v[0:1] op_sel_hi:[1,0,1]
	v_mov_b32_e32 v2, v3
	v_mov_b32_e32 v0, v37
	v_mov_b32_e32 v85, v1
	v_pk_mul_f32 v[0:1], v[4:5], v[0:1] op_sel:[1,0] op_sel_hi:[0,0]
	v_pk_fma_f32 v[36:37], v[4:5], v[2:3], v[0:1] op_sel_hi:[1,0,1] neg_lo:[0,0,1] neg_hi:[0,0,1]
	v_pk_fma_f32 v[0:1], v[4:5], v[2:3], v[0:1] op_sel_hi:[1,0,1]
	v_cvt_pk_bf16_f32 v2, v26, v27
	v_mov_b32_e32 v37, v1
	v_cvt_pk_bf16_f32 v0, v38, v39
	v_cvt_pk_bf16_f32 v1, v40, v41
	v_cvt_pk_bf16_f32 v3, v28, v29
	v_cvt_pk_bf16_f32 v4, v30, v31
	v_cvt_pk_bf16_f32 v5, v32, v33
	s_waitcnt vmcnt(0) lgkmcnt(0)
	v_and_b32_e32 v29, 0xffff0000, v17
	v_and_b32_e32 v27, 0xffff0000, v16
	v_lshlrev_b32_e32 v28, 16, v17
	v_lshlrev_b32_e32 v26, 16, v16
	v_and_b32_e32 v33, 0xffff0000, v19
	v_and_b32_e32 v31, 0xffff0000, v18
	v_lshlrev_b32_e32 v32, 16, v19
	v_lshlrev_b32_e32 v30, 16, v18
	v_and_b32_e32 v19, 0xffff0000, v21
	v_and_b32_e32 v17, 0xffff0000, v20
	v_lshlrev_b32_e32 v18, 16, v21
	v_lshlrev_b32_e32 v16, 16, v20
	v_lshl_add_u64 v[20:21], v[68:69], 0, s[6:7]
	v_mov_b32_e32 v80, v81
	s_mov_b32 s6, 0
	v_and_b32_e32 v41, 0xffff0000, v23
	v_and_b32_e32 v39, 0xffff0000, v22
	v_lshlrev_b32_e32 v40, 16, v23
	v_lshlrev_b32_e32 v38, 16, v22
	ds_write_b128 v89, v[26:29] offset:34816
	ds_write_b128 v89, v[30:33] offset:34832
	ds_write_b128 v89, v[16:19] offset:34848
	ds_write_b128 v89, v[38:41] offset:34864

.LBB0_216:
	s_and_b32 s9, s6, 0xffe0
	v_or_b32_e32 v3, s9, v2
	v_lshlrev_b32_e32 v176, 3, v3
	v_lshl_add_u64 v[4:5], s[90:91], 0, v[176:177]
	global_load_dwordx4 v[4:7], v[4:5], off
	s_nop 0
	global_load_dword v3, v[0:1], off
	global_load_dword v13, v[0:1], off offset:64
	global_load_dword v16, v[0:1], off offset:512
	global_load_dword v17, v[0:1], off offset:576
	global_load_dword v18, v[0:1], off offset:1536
	global_load_dword v19, v[0:1], off offset:1600
	v_add_co_u32_e32 v8, vcc, 0x1000, v0
	s_add_i32 s8, s8, s36
	s_nop 0
	v_addc_co_u32_e32 v9, vcc, 0, v1, vcc
	global_load_dword v20, v[8:9], off
	global_load_dword v21, v[8:9], off offset:64
	global_load_dword v22, v[8:9], off offset:512
	global_load_dword v23, v[8:9], off offset:576
	global_load_dword v24, v[8:9], off offset:1024
	global_load_dword v25, v[8:9], off offset:1088
	global_load_dword v26, v[8:9], off offset:1536
	global_load_dword v27, v[8:9], off offset:1600
	s_add_i32 s6, s6, s10
	s_cmpk_gt_i32 s8, 0x3fff
	s_waitcnt vmcnt(0) lgkmcnt(0)
	v_mov_b32_e32 v15, v6
	v_mov_b32_e32 v6, v5
	v_lshlrev_b32_e32 v12, 16, v13
	v_and_b32_e32 v13, 0xffff0000, v13
	v_lshlrev_b32_e32 v10, 16, v3
	v_and_b32_e32 v11, 0xffff0000, v3
	v_mov_b32_e32 v14, v4
	v_pk_mul_f32 v[4:5], v[6:7], v[12:13]
	s_nop 0
	v_pk_fma_f32 v[4:5], v[14:15], v[10:11], v[4:5] neg_lo:[0,0,1] neg_hi:[0,0,1]
	s_nop 0
	v_cvt_pk_bf16_f32 v3, v4, v5
	v_pk_mul_f32 v[4:5], v[6:7], v[10:11]
	v_lshlrev_b32_e32 v10, 16, v17
	v_pk_fma_f32 v[4:5], v[14:15], v[12:13], v[4:5]
	v_and_b32_e32 v11, 0xffff0000, v17
	flat_store_dword v[0:1], v3
	v_cvt_pk_bf16_f32 v3, v4, v5
	v_lshlrev_b32_e32 v4, 16, v16
	v_and_b32_e32 v5, 0xffff0000, v16
	v_pk_mul_f32 v[12:13], v[6:7], v[10:11]
	flat_store_dword v[0:1], v3 offset:64
	v_pk_fma_f32 v[12:13], v[14:15], v[4:5], v[12:13] neg_lo:[0,0,1] neg_hi:[0,0,1]
	v_pk_mul_f32 v[4:5], v[6:7], v[4:5]
	v_cvt_pk_bf16_f32 v3, v12, v13
	v_pk_fma_f32 v[4:5], v[14:15], v[10:11], v[4:5]
	v_lshlrev_b32_e32 v10, 16, v19
	v_and_b32_e32 v11, 0xffff0000, v19
	flat_store_dword v[0:1], v3 offset:512
	v_cvt_pk_bf16_f32 v3, v4, v5
	v_lshlrev_b32_e32 v4, 16, v18
	v_and_b32_e32 v5, 0xffff0000, v18
	v_pk_mul_f32 v[12:13], v[6:7], v[10:11]
	flat_store_dword v[0:1], v3 offset:576
	v_pk_fma_f32 v[12:13], v[14:15], v[4:5], v[12:13] neg_lo:[0,0,1] neg_hi:[0,0,1]
	v_pk_mul_f32 v[4:5], v[6:7], v[4:5]
	v_cvt_pk_bf16_f32 v3, v12, v13
	v_pk_fma_f32 v[4:5], v[14:15], v[10:11], v[4:5]
	v_lshlrev_b32_e32 v10, 16, v21
	v_and_b32_e32 v11, 0xffff0000, v21
	flat_store_dword v[0:1], v3 offset:1536
	v_cvt_pk_bf16_f32 v3, v4, v5
	v_lshlrev_b32_e32 v4, 16, v20
	v_and_b32_e32 v5, 0xffff0000, v20
	v_pk_mul_f32 v[12:13], v[6:7], v[10:11]
	flat_store_dword v[0:1], v3 offset:1600
	v_pk_fma_f32 v[12:13], v[14:15], v[4:5], v[12:13] neg_lo:[0,0,1] neg_hi:[0,0,1]
	v_pk_mul_f32 v[4:5], v[6:7], v[4:5]
	v_cvt_pk_bf16_f32 v3, v12, v13
	v_pk_fma_f32 v[4:5], v[14:15], v[10:11], v[4:5]
	v_lshlrev_b32_e32 v10, 16, v23
	v_and_b32_e32 v11, 0xffff0000, v23
	flat_store_dword v[8:9], v3
	v_cvt_pk_bf16_f32 v3, v4, v5
	v_lshlrev_b32_e32 v4, 16, v22
	v_and_b32_e32 v5, 0xffff0000, v22
	v_pk_mul_f32 v[12:13], v[6:7], v[10:11]
	flat_store_dword v[8:9], v3 offset:64
	v_pk_fma_f32 v[12:13], v[14:15], v[4:5], v[12:13] neg_lo:[0,0,1] neg_hi:[0,0,1]
	v_pk_mul_f32 v[4:5], v[6:7], v[4:5]
	v_cvt_pk_bf16_f32 v3, v12, v13
	v_pk_fma_f32 v[4:5], v[14:15], v[10:11], v[4:5]
	v_lshlrev_b32_e32 v10, 16, v25
	v_and_b32_e32 v11, 0xffff0000, v25
	flat_store_dword v[8:9], v3 offset:512
	v_cvt_pk_bf16_f32 v3, v4, v5
	v_lshlrev_b32_e32 v4, 16, v24
	v_and_b32_e32 v5, 0xffff0000, v24
	v_pk_mul_f32 v[12:13], v[6:7], v[10:11]
	flat_store_dword v[8:9], v3 offset:576
	v_pk_fma_f32 v[12:13], v[14:15], v[4:5], v[12:13] neg_lo:[0,0,1] neg_hi:[0,0,1]
	v_pk_mul_f32 v[4:5], v[6:7], v[4:5]
	v_cvt_pk_bf16_f32 v3, v12, v13
	v_pk_fma_f32 v[4:5], v[14:15], v[10:11], v[4:5]
	v_lshlrev_b32_e32 v10, 16, v27
	v_and_b32_e32 v11, 0xffff0000, v27
	flat_store_dword v[8:9], v3 offset:1024
	v_cvt_pk_bf16_f32 v3, v4, v5
	v_lshlrev_b32_e32 v4, 16, v26
	v_and_b32_e32 v5, 0xffff0000, v26
	v_pk_mul_f32 v[12:13], v[6:7], v[10:11]
	flat_store_dword v[8:9], v3 offset:1088
	v_pk_fma_f32 v[12:13], v[14:15], v[4:5], v[12:13] neg_lo:[0,0,1] neg_hi:[0,0,1]
	v_pk_mul_f32 v[4:5], v[6:7], v[4:5]
	v_cvt_pk_bf16_f32 v3, v12, v13
	v_pk_fma_f32 v[4:5], v[14:15], v[10:11], v[4:5]
	flat_store_dword v[8:9], v3 offset:1536
	v_cvt_pk_bf16_f32 v3, v4, v5
	v_lshl_add_u64 v[0:1], v[0:1], 0, s[12:13]
	flat_store_dword v[8:9], v3 offset:1600
	s_cbranch_scc0 .LBB0_216

.LBB0_219:
	s_mul_hi_i32 s6, s14, 0x81020409
	s_add_i32 s6, s6, s14
	s_lshr_b32 s8, s6, 31
	s_ashr_i32 s6, s6, 10
	s_add_i32 s8, s6, s8
	s_mul_i32 s6, s8, 0xfffff810
	s_ashr_i32 s9, s8, 31
	s_add_i32 s16, s14, s6
	s_lshl_b64 s[18:19], s[8:9], 13
	s_lshl_b64 s[20:21], s[8:9], 23
	s_bfe_i32 s9, s16, 0x100001
	s_mulk_i32 s9, 0x8103
	s_lshr_b32 s6, s16, 1
	s_lshr_b32 s9, s9, 16
	s_add_i32 s9, s9, s6
	s_sext_i32_i16 s15, s9
	s_bfe_u32 s9, s9, 0x1000f
	s_ashr_i32 s15, s15, 6
	s_add_i32 s9, s15, s9
	s_mul_i32 s15, s9, 0x7f
	s_ashr_i32 s17, s16, 31
	s_sub_i32 s6, s6, s15
	s_add_u32 s15, s10, s20
	v_lshl_add_u64 v[30:31], v[2:3], 0, s[18:19]
	s_addc_u32 s18, s11, s21
	s_lshl_b64 s[16:17], s[16:17], 12
	s_sext_i32_i16 s6, s6
	s_add_u32 s16, s15, s16
	s_addc_u32 s17, s18, s17
	s_lshl_b32 s15, s9, 11
	s_lshl_b32 s6, s6, 4
	s_add_i32 s15, s15, s6
	s_lshl_b32 s8, s8, 7
	v_or_b32_e32 v1, s15, v0
	s_ashr_i32 s9, s8, 31
	v_mul_hi_i32_i24_e32 v23, 0x1e00, v1
	v_mul_i32_i24_e32 v22, 0x1e00, v1
	s_and_b32 s18, s12, 64
	s_lshl_b64 s[8:9], s[8:9], 1
	v_lshl_add_u64 v[22:23], s[26:27], 0, v[22:23]
	s_lshl_b32 s6, s18, 1
	v_lshl_add_u64 v[22:23], v[22:23], 0, s[8:9]
	v_lshlrev_b32_e32 v18, 2, v4
	v_mov_b32_e32 v19, v177
	v_lshl_add_u64 v[22:23], v[22:23], 0, s[6:7]
	v_lshl_add_u64 v[26:27], v[30:31], 0, v[18:19]
	v_lshl_add_u64 v[22:23], v[22:23], 0, v[176:177]
	global_load_dwordx4 v[18:21], v[26:27], off
	s_nop 0
	global_load_dwordx4 v[22:25], v[22:23], off offset:2048
	s_nop 0
	global_load_dwordx4 v[26:29], v[26:27], off offset:16
	v_or_b32_e32 v1, s15, v6
	v_mul_hi_i32_i24_e32 v39, 0x1e00, v1
	v_mul_i32_i24_e32 v38, 0x1e00, v1
	v_lshl_add_u64 v[38:39], s[26:27], 0, v[38:39]
	v_lshlrev_b32_e32 v32, 1, v4
	v_mov_b32_e32 v33, v177
	v_lshl_add_u64 v[36:37], s[16:17], 0, v[176:177]
	v_lshl_add_u64 v[38:39], v[38:39], 0, s[8:9]
	v_lshl_add_u64 v[32:33], v[36:37], 0, v[32:33]
	v_lshl_add_u64 v[38:39], v[38:39], 0, s[6:7]
	v_lshlrev_b32_e32 v34, 2, v8
	v_mov_b32_e32 v35, v177
	v_lshl_add_u64 v[38:39], v[38:39], 0, v[176:177]
	v_lshl_add_u64 v[34:35], v[30:31], 0, v[34:35]
	v_add_u32_e32 v1, s15, v10
	s_add_i32 s14, s14, s36
	s_add_i32 s12, s12, s13
	s_cmpk_gt_i32 s14, 0xfdf
	s_waitcnt vmcnt(0) lgkmcnt(0)
	v_and_b32_e32 v41, 0xffff0000, v22
	v_lshlrev_b32_e32 v40, 16, v22
	v_and_b32_e32 v43, 0xffff0000, v23
	v_lshlrev_b32_e32 v42, 16, v23
	v_and_b32_e32 v23, 0xffff0000, v24
	v_lshlrev_b32_e32 v22, 16, v24
	v_and_b32_e32 v45, 0xffff0000, v25
	v_lshlrev_b32_e32 v44, 16, v25
	v_pk_add_f32 v[18:19], v[18:19], v[40:41]
	v_pk_add_f32 v[20:21], v[20:21], v[42:43]
	v_pk_add_f32 v[22:23], v[26:27], v[22:23]
	v_pk_add_f32 v[24:25], v[28:29], v[44:45]
	v_cvt_pk_bf16_f32 v18, v18, v19
	v_cvt_pk_bf16_f32 v19, v20, v21
	v_cvt_pk_bf16_f32 v20, v22, v23
	v_cvt_pk_bf16_f32 v21, v24, v25
	flat_store_dwordx4 v[32:33], v[18:21]
	global_load_dwordx4 v[18:21], v[38:39], off offset:2048
	s_nop 0
	global_load_dwordx4 v[22:25], v[34:35], off
	global_load_dwordx4 v[26:29], v[34:35], off offset:16
	v_mul_hi_i32_i24_e32 v39, 0x1e00, v1
	v_mul_i32_i24_e32 v38, 0x1e00, v1
	v_lshl_add_u64 v[38:39], s[26:27], 0, v[38:39]
	v_lshlrev_b32_e32 v32, 1, v8
	v_mov_b32_e32 v33, v177
	v_lshl_add_u64 v[38:39], v[38:39], 0, s[8:9]
	v_lshl_add_u64 v[32:33], v[36:37], 0, v[32:33]
	v_lshl_add_u64 v[38:39], v[38:39], 0, s[6:7]
	v_lshlrev_b32_e32 v34, 2, v12
	v_mov_b32_e32 v35, v177
	v_lshl_add_u64 v[38:39], v[38:39], 0, v[176:177]
	v_lshl_add_u64 v[34:35], v[30:31], 0, v[34:35]
	v_add_u32_e32 v1, s15, v14
	s_waitcnt vmcnt(0) lgkmcnt(0)
	v_and_b32_e32 v41, 0xffff0000, v18
	v_lshlrev_b32_e32 v40, 16, v18
	v_and_b32_e32 v43, 0xffff0000, v19
	v_lshlrev_b32_e32 v42, 16, v19
	v_and_b32_e32 v19, 0xffff0000, v20
	v_lshlrev_b32_e32 v18, 16, v20
	v_and_b32_e32 v45, 0xffff0000, v21
	v_lshlrev_b32_e32 v44, 16, v21
	v_pk_add_f32 v[20:21], v[22:23], v[40:41]
	v_pk_add_f32 v[22:23], v[24:25], v[42:43]
	v_pk_add_f32 v[24:25], v[26:27], v[18:19]
	v_pk_add_f32 v[26:27], v[28:29], v[44:45]
	v_cvt_pk_bf16_f32 v18, v20, v21
	v_cvt_pk_bf16_f32 v19, v22, v23
	v_cvt_pk_bf16_f32 v20, v24, v25
	v_cvt_pk_bf16_f32 v21, v26, v27
	flat_store_dwordx4 v[32:33], v[18:21]
	global_load_dwordx4 v[18:21], v[38:39], off offset:2048
	s_nop 0
	global_load_dwordx4 v[22:25], v[34:35], off
	global_load_dwordx4 v[26:29], v[34:35], off offset:16
	v_lshlrev_b32_e32 v34, 2, v16
	v_mov_b32_e32 v35, v177
	v_lshl_add_u64 v[30:31], v[30:31], 0, v[34:35]
	v_mul_hi_i32_i24_e32 v35, 0x1e00, v1
	v_mul_i32_i24_e32 v34, 0x1e00, v1
	v_lshl_add_u64 v[34:35], s[26:27], 0, v[34:35]
	v_lshlrev_b32_e32 v32, 1, v12
	v_mov_b32_e32 v33, v177
	v_lshl_add_u64 v[34:35], v[34:35], 0, s[8:9]
	v_lshl_add_u64 v[32:33], v[36:37], 0, v[32:33]
	v_lshl_add_u64 v[34:35], v[34:35], 0, s[6:7]
	v_lshl_add_u64 v[34:35], v[34:35], 0, v[176:177]
	s_waitcnt vmcnt(0) lgkmcnt(0)
	v_and_b32_e32 v39, 0xffff0000, v18
	v_lshlrev_b32_e32 v38, 16, v18
	v_and_b32_e32 v41, 0xffff0000, v19
	v_lshlrev_b32_e32 v40, 16, v19
	v_and_b32_e32 v19, 0xffff0000, v20
	v_lshlrev_b32_e32 v18, 16, v20
	v_and_b32_e32 v43, 0xffff0000, v21
	v_lshlrev_b32_e32 v42, 16, v21
	v_pk_add_f32 v[20:21], v[22:23], v[38:39]
	v_pk_add_f32 v[22:23], v[24:25], v[40:41]
	v_pk_add_f32 v[24:25], v[26:27], v[18:19]
	v_pk_add_f32 v[26:27], v[28:29], v[42:43]
	v_cvt_pk_bf16_f32 v18, v20, v21
	v_cvt_pk_bf16_f32 v19, v22, v23
	v_cvt_pk_bf16_f32 v20, v24, v25
	v_cvt_pk_bf16_f32 v21, v26, v27
	flat_store_dwordx4 v[32:33], v[18:21]
	global_load_dwordx4 v[18:21], v[34:35], off offset:2048
	s_nop 0
	global_load_dwordx4 v[22:25], v[30:31], off
	global_load_dwordx4 v[26:29], v[30:31], off offset:16
	v_lshlrev_b32_e32 v30, 1, v16
	v_mov_b32_e32 v31, v177
	v_lshl_add_u64 v[30:31], v[36:37], 0, v[30:31]
	s_waitcnt vmcnt(0) lgkmcnt(0)
	v_and_b32_e32 v33, 0xffff0000, v18
	v_lshlrev_b32_e32 v32, 16, v18
	v_and_b32_e32 v35, 0xffff0000, v19
	v_lshlrev_b32_e32 v34, 16, v19
	v_and_b32_e32 v19, 0xffff0000, v20
	v_lshlrev_b32_e32 v18, 16, v20
	v_and_b32_e32 v37, 0xffff0000, v21
	v_lshlrev_b32_e32 v36, 16, v21
	v_pk_add_f32 v[20:21], v[22:23], v[32:33]
	v_pk_add_f32 v[22:23], v[24:25], v[34:35]
	v_pk_add_f32 v[24:25], v[26:27], v[18:19]
	v_pk_add_f32 v[26:27], v[28:29], v[36:37]
	v_cvt_pk_bf16_f32 v18, v20, v21
	v_cvt_pk_bf16_f32 v19, v22, v23
	v_cvt_pk_bf16_f32 v20, v24, v25
	v_cvt_pk_bf16_f32 v21, v26, v27
	flat_store_dwordx4 v[30:31], v[18:21]
	s_cbranch_scc0 .LBB0_219

.LBB0_232:
	s_or_b64 exec, exec, s[8:9]
	v_max_f32_e32 v0, v0, v0
	v_min_f32_e32 v0, 0xb8d1b717, v0
	v_mul_f32_e32 v6, v0, v6
	v_mul_f32_e32 v7, 0x3fb8aa3b, v6
	s_mov_b32 s6, 0x3fb8aa3b
	v_fma_f32 v12, v6, s6, -v7
	v_rndne_f32_e32 v13, v7
	v_fmac_f32_e32 v12, 0x32a5705f, v6
	v_sub_f32_e32 v7, v7, v13
	v_add_f32_e32 v7, v7, v12
	v_exp_f32_e32 v7, v7
	v_cvt_i32_f32_e32 v12, v13
	s_mov_b32 s6, 0xc2ce8ed0
	v_cmp_ngt_f32_e32 vcc, s6, v6
	s_mov_b32 s6, 0x42b17218
	v_ldexp_f32 v7, v7, v12
	v_readlane_b32 s52, v249, 33
	v_cndmask_b32_e32 v7, 0, v7, vcc
	v_cmp_nlt_f32_e32 vcc, s6, v6
	v_lshlrev_b64 v[2:3], 6, v[2:3]
	v_readlane_b32 s53, v249, 34
	v_cndmask_b32_e32 v13, v209, v7, vcc
	v_readlane_b32 s54, v249, 35
	v_readlane_b32 s55, v249, 36
	v_lshl_add_u64 v[18:19], s[52:53], 0, v[2:3]
	v_mul_f32_e32 v12, v13, v5
	v_mul_f32_e32 v15, v13, v4
	v_fma_f32 v14, v13, v5, -1.0
	v_lshl_add_u64 v[20:21], s[54:55], 0, v[2:3]
	global_load_dwordx4 v[2:5], v[18:19], off offset:48
	global_load_dwordx4 v[38:41], v[18:19], off offset:32
	global_load_dwordx4 v[30:33], v[18:19], off offset:16
	global_load_dwordx4 v[22:25], v[18:19], off
	global_load_dwordx4 v[46:49], v[20:21], off offset:48
	global_load_dwordx4 v[42:45], v[20:21], off offset:32
	global_load_dwordx4 v[34:37], v[20:21], off offset:16
	global_load_dwordx4 v[26:29], v[20:21], off
	v_mov_b32_e32 v18, v1
	v_pk_mul_f32 v[6:7], v[0:1], v[0:1]
	v_pk_mul_f32 v[18:19], v[18:19], v[14:15] op_sel:[0,1] op_sel_hi:[0,0]
	v_pk_fma_f32 v[20:21], v[0:1], v[14:15], v[18:19]
	v_pk_fma_f32 v[0:1], v[0:1], v[14:15], v[18:19] op_sel_hi:[0,1,1] neg_lo:[0,0,1] neg_hi:[0,0,1]
	v_pk_add_f32 v[6:7], v[6:7], v[6:7] op_sel:[0,1] op_sel_hi:[0,1]
	v_div_scale_f32 v0, s[10:11], v7, v7, v1
	v_rcp_f32_e32 v13, v0
	s_ashr_i32 s8, s0, 10
	s_lshl_b32 s9, s0, 6
	s_ashr_i32 s6, s8, 31
	v_fma_f32 v14, -v0, v13, 1.0
	v_fmac_f32_e32 v13, v14, v13
	v_div_scale_f32 v14, vcc, v1, v7, v1
	v_mul_f32_e32 v17, v14, v13
	v_fma_f32 v18, -v0, v17, v14
	v_fmac_f32_e32 v17, v18, v13
	v_fma_f32 v0, -v0, v17, v14
	v_div_fmas_f32 v0, v0, v13, v17
	v_div_fixup_f32 v1, v0, v7, v1
	v_div_scale_f32 v0, s[10:11], v6, v6, v20
	v_rcp_f32_e32 v7, v0
	s_lshl_b32 s8, s8, 11
	s_and_b32 s9, s9, 0x7c0
	s_or_b32 s8, s8, s9
	v_fma_f32 v13, -v0, v7, 1.0
	v_fmac_f32_e32 v7, v13, v7
	v_div_scale_f32 v13, vcc, v20, v6, v20
	v_mul_f32_e32 v14, v13, v7
	v_fma_f32 v17, -v0, v14, v13
	v_fmac_f32_e32 v14, v17, v7
	v_fma_f32 v0, -v0, v14, v13
	v_div_fmas_f32 v0, v0, v7, v14
	v_div_fixup_f32 v0, v0, v6, v20
	v_mov_b32_e32 v16, 0
	v_mov_b32_e32 v13, v12
	v_mov_b32_e32 v17, v16
	v_readlane_b32 s56, v249, 37
	v_readlane_b32 s57, v249, 38
	v_readlane_b32 s58, v249, 39
	v_readlane_b32 s59, v249, 40
	v_readlane_b32 s60, v249, 41
	v_readlane_b32 s61, v249, 42
	v_readlane_b32 s62, v249, 43
	v_readlane_b32 s63, v249, 44
	v_readlane_b32 s64, v249, 45
	v_readlane_b32 s65, v249, 46
	v_readlane_b32 s66, v249, 47
	v_readlane_b32 s67, v249, 48
	s_waitcnt vmcnt(0)
	v_mov_b32_e32 v14, v25
	v_pk_mul_f32 v[6:7], v[0:1], v[26:27] op_sel:[1,0] op_sel_hi:[0,0]
	v_pk_fma_f32 v[18:19], v[0:1], v[22:23], v[6:7] neg_lo:[0,0,1] neg_hi:[0,0,1]
	v_pk_fma_f32 v[6:7], v[0:1], v[22:23], v[6:7] op_sel_hi:[1,0,1]
	s_nop 0
	v_mov_b32_e32 v19, v7
	v_pk_mul_f32 v[6:7], v[0:1], v[26:27] op_sel:[1,1] op_sel_hi:[0,1]
	v_pk_fma_f32 v[20:21], v[0:1], v[22:23], v[6:7] op_sel:[0,1,0] neg_lo:[0,0,1] neg_hi:[0,0,1]
	v_pk_fma_f32 v[6:7], v[0:1], v[22:23], v[6:7] op_sel:[0,1,0]
	s_nop 0
	v_mov_b32_e32 v21, v7
	v_pk_mul_f32 v[6:7], v[0:1], v[28:29] op_sel:[1,0] op_sel_hi:[0,0]
	v_pk_fma_f32 v[22:23], v[0:1], v[24:25], v[6:7] neg_lo:[0,0,1] neg_hi:[0,0,1]
	v_pk_fma_f32 v[6:7], v[0:1], v[24:25], v[6:7] op_sel_hi:[1,0,1]
	s_nop 0
	v_mov_b32_e32 v6, v29
	v_mov_b32_e32 v23, v7
	v_pk_mul_f32 v[6:7], v[0:1], v[6:7] op_sel:[1,0] op_sel_hi:[0,0]
	v_pk_fma_f32 v[24:25], v[0:1], v[14:15], v[6:7] op_sel_hi:[1,0,1] neg_lo:[0,0,1] neg_hi:[0,0,1]
	v_pk_fma_f32 v[6:7], v[0:1], v[14:15], v[6:7] op_sel_hi:[1,0,1]
	v_mov_b32_e32 v14, v33
	v_mov_b32_e32 v25, v7
	v_pk_mul_f32 v[6:7], v[0:1], v[34:35] op_sel:[1,0] op_sel_hi:[0,0]
	v_pk_fma_f32 v[26:27], v[0:1], v[30:31], v[6:7] neg_lo:[0,0,1] neg_hi:[0,0,1]
	v_pk_fma_f32 v[6:7], v[0:1], v[30:31], v[6:7] op_sel_hi:[1,0,1]
	s_nop 0
	v_mov_b32_e32 v27, v7
	v_pk_mul_f32 v[6:7], v[0:1], v[34:35] op_sel:[1,1] op_sel_hi:[0,1]
	v_pk_fma_f32 v[28:29], v[0:1], v[30:31], v[6:7] op_sel:[0,1,0] neg_lo:[0,0,1] neg_hi:[0,0,1]
	v_pk_fma_f32 v[6:7], v[0:1], v[30:31], v[6:7] op_sel:[0,1,0]
	s_nop 0
	v_mov_b32_e32 v29, v7
	v_pk_mul_f32 v[6:7], v[0:1], v[36:37] op_sel:[1,0] op_sel_hi:[0,0]
	v_pk_fma_f32 v[30:31], v[0:1], v[32:33], v[6:7] neg_lo:[0,0,1] neg_hi:[0,0,1]
	v_pk_fma_f32 v[6:7], v[0:1], v[32:33], v[6:7] op_sel_hi:[1,0,1]
	s_nop 0
	v_mov_b32_e32 v6, v37
	v_mov_b32_e32 v31, v7
	v_pk_mul_f32 v[6:7], v[0:1], v[6:7] op_sel:[1,0] op_sel_hi:[0,0]
	v_pk_fma_f32 v[32:33], v[0:1], v[14:15], v[6:7] op_sel_hi:[1,0,1] neg_lo:[0,0,1] neg_hi:[0,0,1]
	v_pk_fma_f32 v[6:7], v[0:1], v[14:15], v[6:7] op_sel_hi:[1,0,1]
	v_mov_b32_e32 v14, v41
	v_mov_b32_e32 v33, v7
	v_pk_mul_f32 v[6:7], v[0:1], v[42:43] op_sel:[1,0] op_sel_hi:[0,0]
	v_pk_fma_f32 v[34:35], v[0:1], v[38:39], v[6:7] neg_lo:[0,0,1] neg_hi:[0,0,1]
	v_pk_fma_f32 v[6:7], v[0:1], v[38:39], v[6:7] op_sel_hi:[1,0,1]
	s_nop 0
	v_mov_b32_e32 v35, v7
	v_pk_mul_f32 v[6:7], v[0:1], v[42:43] op_sel:[1,1] op_sel_hi:[0,1]
	v_pk_fma_f32 v[36:37], v[0:1], v[38:39], v[6:7] op_sel:[0,1,0] neg_lo:[0,0,1] neg_hi:[0,0,1]
	v_pk_fma_f32 v[6:7], v[0:1], v[38:39], v[6:7] op_sel:[0,1,0]
	s_nop 0
	v_mov_b32_e32 v37, v7
	v_pk_mul_f32 v[6:7], v[0:1], v[44:45] op_sel:[1,0] op_sel_hi:[0,0]
	v_pk_fma_f32 v[38:39], v[0:1], v[40:41], v[6:7] neg_lo:[0,0,1] neg_hi:[0,0,1]
	v_pk_fma_f32 v[6:7], v[0:1], v[40:41], v[6:7] op_sel_hi:[1,0,1]
	s_nop 0
	v_mov_b32_e32 v6, v45
	v_mov_b32_e32 v39, v7
	v_pk_mul_f32 v[6:7], v[0:1], v[6:7] op_sel:[1,0] op_sel_hi:[0,0]
	v_pk_fma_f32 v[40:41], v[0:1], v[14:15], v[6:7] op_sel_hi:[1,0,1] neg_lo:[0,0,1] neg_hi:[0,0,1]
	v_pk_fma_f32 v[6:7], v[0:1], v[14:15], v[6:7] op_sel_hi:[1,0,1]
	v_mov_b32_e32 v14, v15
	v_mov_b32_e32 v41, v7
	v_pk_mul_f32 v[6:7], v[0:1], v[46:47] op_sel:[1,0] op_sel_hi:[0,0]
	v_pk_fma_f32 v[42:43], v[0:1], v[2:3], v[6:7] neg_lo:[0,0,1] neg_hi:[0,0,1]
	v_pk_fma_f32 v[6:7], v[0:1], v[2:3], v[6:7] op_sel_hi:[1,0,1]
	s_nop 0
	v_mov_b32_e32 v43, v7
	v_pk_mul_f32 v[6:7], v[0:1], v[46:47] op_sel:[1,1] op_sel_hi:[0,1]
	v_pk_fma_f32 v[44:45], v[0:1], v[2:3], v[6:7] op_sel:[0,1,0] neg_lo:[0,0,1] neg_hi:[0,0,1]
	v_pk_fma_f32 v[2:3], v[0:1], v[2:3], v[6:7] op_sel:[0,1,0]
	s_nop 0
	v_mov_b32_e32 v45, v3
	v_pk_mul_f32 v[2:3], v[0:1], v[48:49] op_sel:[1,0] op_sel_hi:[0,0]
	v_pk_fma_f32 v[46:47], v[0:1], v[4:5], v[2:3] neg_lo:[0,0,1] neg_hi:[0,0,1]
	v_pk_fma_f32 v[2:3], v[0:1], v[4:5], v[2:3] op_sel_hi:[1,0,1]
	v_mov_b32_e32 v4, v5
	v_mov_b32_e32 v2, v49
	v_mov_b32_e32 v47, v3
	v_pk_mul_f32 v[2:3], v[0:1], v[2:3] op_sel:[1,0] op_sel_hi:[0,0]
	v_pk_fma_f32 v[48:49], v[0:1], v[4:5], v[2:3] op_sel_hi:[1,0,1] neg_lo:[0,0,1] neg_hi:[0,0,1]
	v_pk_fma_f32 v[0:1], v[0:1], v[4:5], v[2:3] op_sel_hi:[1,0,1]
	v_or_b32_e32 v2, s8, v128
	v_mov_b32_e32 v49, v1
	v_mov_b64_e32 v[0:1], s[26:27]
	s_movk_i32 s8, 0x1e00
	v_mad_u64_u32 v[0:1], s[8:9], v2, s8, v[0:1]
	v_mad_i32_i24 v1, s6, v210, v1
	s_lshl_b32 s6, s1, 5
	v_lshl_add_u64 v[0:1], v[0:1], 0, s[6:7]
	global_load_dwordx4 v[4:7], v[0:1], off
	s_nop 0
	global_load_dwordx4 v[0:3], v[0:1], off offset:16
	s_mov_b32 s1, 0
	s_waitcnt vmcnt(0) lgkmcnt(0)
	v_and_b32_e32 v55, 0xffff0000, v5
	v_and_b32_e32 v53, 0xffff0000, v4
	v_lshlrev_b32_e32 v54, 16, v5
	v_lshlrev_b32_e32 v52, 16, v4
	v_and_b32_e32 v59, 0xffff0000, v7
	v_and_b32_e32 v57, 0xffff0000, v6
	v_lshlrev_b32_e32 v58, 16, v7
	v_lshlrev_b32_e32 v56, 16, v6
	v_and_b32_e32 v7, 0xffff0000, v1
	v_and_b32_e32 v5, 0xffff0000, v0
	v_lshlrev_b32_e32 v6, 16, v1
	v_lshlrev_b32_e32 v4, 16, v0
	v_and_b32_e32 v63, 0xffff0000, v3
	v_and_b32_e32 v61, 0xffff0000, v2
	v_lshlrev_b32_e32 v62, 16, v3
	v_lshlrev_b32_e32 v60, 16, v2
	ds_write_b128 v50, v[52:55]
	ds_write_b128 v50, v[56:59] offset:16
	ds_write_b128 v50, v[4:7] offset:32
	ds_write_b128 v50, v[60:63] offset:48

.LBB0_250:
	s_add_i32 s18, s16, s12
	s_lshl_b32 s6, s18, 7
	v_lshl_add_u64 v[0:1], v[92:93], 0, s[6:7]
	global_load_dwordx4 v[48:51], v[0:1], off offset:1024
	global_load_dwordx4 v[52:55], v[0:1], off offset:1056
	global_load_dwordx4 v[56:59], v[0:1], off offset:1088
	global_load_dwordx4 v[60:63], v[0:1], off offset:1120
	s_lshl_b32 s17, s18, 6
	v_mov_b32_e32 v18, 0
	v_mov_b32_e32 v0, 0xff800000
	v_mov_b64_e32 v[16:17], v[90:91]
	v_mov_b32_e32 v19, v106
	s_mov_b32 s6, 0
.LBB0_251:
	v_mov_b32_e32 v20, v0
	global_load_dwordx4 v[0:3], v[16:17], off
	global_load_dwordx4 v[22:25], v[16:17], off offset:32
	global_load_dwordx4 v[26:29], v[16:17], off offset:64
	global_load_dwordx4 v[30:33], v[16:17], off offset:96
	v_add_u32_e32 v21, 0xfffffe50, v19
	v_cmp_le_u32_e64 s[44:45], v21, v108
	v_lshl_add_u64 v[16:17], v[16:17], 0, s[24:25]
	s_waitcnt vmcnt(0) lgkmcnt(0)
	v_mfma_f32_32x32x16_bf16 v[0:15], v[0:3], v[48:51], 0
	v_mfma_f32_32x32x16_bf16 v[0:15], v[22:25], v[52:55], v[0:15]
	v_add_u32_e32 v22, s6, v103
	v_cmp_gt_u32_e32 vcc, s75, v22
	s_and_b64 vcc, vcc, s[44:45]
	v_add_u32_e32 v23, 1, v22
	s_add_i32 s6, s6, 32
	v_mfma_f32_32x32x16_bf16 v[0:15], v[26:29], v[56:59], v[0:15]
	v_mfma_f32_32x32x16_bf16 v[0:15], v[30:33], v[60:63], v[0:15]
	s_nop 11
	v_mul_f32_e32 v0, 0x3e38aa3b, v0
	v_cndmask_b32_e32 v21, v212, v0, vcc
	v_cmp_gt_u32_e32 vcc, s75, v23
	v_add_u32_e32 v23, 0xfffffe60, v19
	v_cmp_le_u32_e64 s[44:45], v23, v108
	s_and_b64 vcc, vcc, s[44:45]
	v_mul_f32_e32 v1, 0x3e38aa3b, v1
	v_add_u32_e32 v23, 2, v22
	v_cndmask_b32_e32 v1, v212, v1, vcc
	v_cmp_gt_u32_e32 vcc, s75, v23
	v_add_u32_e32 v23, 0xfffffe70, v19
	v_cmp_le_u32_e64 s[44:45], v23, v108
	s_and_b64 vcc, vcc, s[44:45]
	v_mul_f32_e32 v2, 0x3e38aa3b, v2
	v_add_u32_e32 v23, 3, v22
	v_cndmask_b32_e32 v2, v212, v2, vcc
	v_cmp_gt_u32_e32 vcc, s75, v23
	v_add_u32_e32 v23, 0xfffffe80, v19
	v_cmp_le_u32_e64 s[44:45], v23, v108
	s_and_b64 vcc, vcc, s[44:45]
	v_mul_f32_e32 v3, 0x3e38aa3b, v3
	v_add_u32_e32 v23, 8, v22
	v_cndmask_b32_e32 v3, v212, v3, vcc
	v_cmp_gt_u32_e32 vcc, s75, v23
	v_add_u32_e32 v23, 0xfffffed0, v19
	v_cmp_le_u32_e64 s[44:45], v23, v108
	s_and_b64 vcc, vcc, s[44:45]
	v_mul_f32_e32 v4, 0x3e38aa3b, v4
	v_add_u32_e32 v23, 9, v22
	v_cndmask_b32_e32 v4, v212, v4, vcc
	v_cmp_gt_u32_e32 vcc, s75, v23
	v_add_u32_e32 v23, 0xfffffee0, v19
	v_cmp_le_u32_e64 s[44:45], v23, v108
	s_and_b64 vcc, vcc, s[44:45]
	v_mul_f32_e32 v5, 0x3e38aa3b, v5
	v_add_u32_e32 v23, 10, v22
	v_cndmask_b32_e32 v5, v212, v5, vcc
	v_cmp_gt_u32_e32 vcc, s75, v23
	v_add_u32_e32 v23, 0xfffffef0, v19
	v_cmp_le_u32_e64 s[44:45], v23, v108
	s_and_b64 vcc, vcc, s[44:45]
	v_mul_f32_e32 v6, 0x3e38aa3b, v6
	v_add_u32_e32 v23, 11, v22
	v_cndmask_b32_e32 v6, v212, v6, vcc
	v_cmp_gt_u32_e32 vcc, s75, v23
	v_add_u32_e32 v23, 0xffffff00, v19
	v_cmp_le_u32_e64 s[44:45], v23, v108
	s_and_b64 vcc, vcc, s[44:45]
	v_mul_f32_e32 v7, 0x3e38aa3b, v7
	v_add_u32_e32 v23, 16, v22
	v_cndmask_b32_e32 v7, v212, v7, vcc
	v_cmp_gt_u32_e32 vcc, s75, v23
	v_add_u32_e32 v23, 0xffffff50, v19
	v_cmp_le_u32_e64 s[44:45], v23, v108
	s_and_b64 vcc, vcc, s[44:45]
	v_mul_f32_e32 v8, 0x3e38aa3b, v8
	v_add_u32_e32 v23, 17, v22
	v_cndmask_b32_e32 v8, v212, v8, vcc
	v_cmp_gt_u32_e32 vcc, s75, v23
	v_add_u32_e32 v23, 0xffffff60, v19
	v_cmp_le_u32_e64 s[44:45], v23, v108
	s_and_b64 vcc, vcc, s[44:45]
	v_mul_f32_e32 v9, 0x3e38aa3b, v9
	v_add_u32_e32 v23, 18, v22
	v_cndmask_b32_e32 v9, v212, v9, vcc
	v_cmp_gt_u32_e32 vcc, s75, v23
	v_add_u32_e32 v23, 0xffffff70, v19
	v_cmp_le_u32_e64 s[44:45], v23, v108
	s_and_b64 vcc, vcc, s[44:45]
	v_mul_f32_e32 v10, 0x3e38aa3b, v10
	v_add_u32_e32 v23, 19, v22
	v_cndmask_b32_e32 v10, v212, v10, vcc
	v_cmp_gt_u32_e32 vcc, s75, v23
	v_add_u32_e32 v23, 0xffffff80, v19
	v_cmp_le_u32_e64 s[44:45], v23, v108
	s_and_b64 vcc, vcc, s[44:45]
	v_mul_f32_e32 v11, 0x3e38aa3b, v11
	v_add_u32_e32 v23, 24, v22
	v_cndmask_b32_e32 v11, v212, v11, vcc
	v_cmp_gt_u32_e32 vcc, s75, v23
	v_subrev_u32_e32 v23, 48, v19
	v_cmp_le_u32_e64 s[44:45], v23, v108
	s_and_b64 vcc, vcc, s[44:45]
	v_mul_f32_e32 v12, 0x3e38aa3b, v12
	v_add_u32_e32 v23, 25, v22
	v_cndmask_b32_e32 v12, v212, v12, vcc
	v_cmp_gt_u32_e32 vcc, s75, v23
	v_subrev_u32_e32 v23, 32, v19
	v_max_f32_e32 v0, 0xff800000, v21
	v_cmp_le_u32_e64 s[44:45], v23, v108
	v_max3_f32 v0, v0, v1, v2
	s_and_b64 vcc, vcc, s[44:45]
	v_mul_f32_e32 v13, 0x3e38aa3b, v13
	v_add_u32_e32 v23, 26, v22
	v_max3_f32 v0, v0, v3, v4
	v_cndmask_b32_e32 v13, v212, v13, vcc
	v_cmp_gt_u32_e32 vcc, s75, v23
	v_add_u32_e32 v23, -16, v19
	v_max3_f32 v0, v0, v5, v6
	v_cmp_le_u32_e64 s[44:45], v23, v108
	v_max3_f32 v0, v0, v7, v8
	s_and_b64 vcc, vcc, s[44:45]
	v_mul_f32_e32 v14, 0x3e38aa3b, v14
	v_add_u32_e32 v22, 27, v22
	v_max3_f32 v0, v0, v9, v10
	v_cndmask_b32_e32 v14, v212, v14, vcc
	v_cmp_gt_u32_e32 vcc, s75, v22
	v_cmp_le_u32_e64 s[44:45], v19, v108
	v_max3_f32 v0, v0, v11, v12
	s_and_b64 vcc, vcc, s[44:45]
	v_mul_f32_e32 v15, 0x3e38aa3b, v15
	v_max3_f32 v0, v0, v13, v14
	v_cndmask_b32_e32 v15, v212, v15, vcc
	v_max3_f32 v0, v20, v0, v15
	v_cmp_neq_f32_e32 vcc, s29, v0
	v_add_u32_e32 v19, 0x200, v19
	s_cmp_eq_u32 s15, s6
	v_cndmask_b32_e32 v22, 0, v0, vcc
	v_sub_f32_e32 v21, v21, v22
	v_exp_f32_e32 v21, v21
	v_sub_f32_e32 v1, v1, v22
	v_exp_f32_e32 v1, v1
	v_sub_f32_e32 v2, v2, v22
	v_exp_f32_e32 v2, v2
	v_add_f32_e32 v21, 0, v21
	v_add_f32_e32 v1, v1, v21
	v_add_f32_e32 v1, v2, v1
	v_sub_f32_e32 v2, v3, v22
	v_exp_f32_e32 v2, v2
	v_mov_b32_e32 v3, v18
	v_add_f32_e32 v1, v2, v1
	v_sub_f32_e32 v2, v4, v22
	v_exp_f32_e32 v2, v2
	s_nop 0
	v_add_f32_e32 v1, v2, v1
	v_sub_f32_e32 v2, v5, v22
	v_exp_f32_e32 v2, v2
	s_nop 0
	v_add_f32_e32 v1, v2, v1
	v_sub_f32_e32 v2, v6, v22
	v_exp_f32_e32 v2, v2
	s_nop 0
	v_add_f32_e32 v1, v2, v1
	v_sub_f32_e32 v2, v7, v22
	v_exp_f32_e32 v2, v2
	s_nop 0
	v_add_f32_e32 v1, v2, v1
	v_sub_f32_e32 v2, v8, v22
	v_exp_f32_e32 v2, v2
	s_nop 0
	v_add_f32_e32 v1, v2, v1
	v_sub_f32_e32 v2, v9, v22
	v_exp_f32_e32 v2, v2
	s_nop 0
	v_add_f32_e32 v1, v2, v1
	v_sub_f32_e32 v2, v10, v22
	v_exp_f32_e32 v2, v2
	s_nop 0
	v_add_f32_e32 v1, v2, v1
	v_sub_f32_e32 v2, v11, v22
	v_exp_f32_e32 v2, v2
	s_nop 0
	v_add_f32_e32 v1, v2, v1
	v_sub_f32_e32 v2, v12, v22
	v_exp_f32_e32 v2, v2
	s_nop 0
	v_add_f32_e32 v1, v2, v1
	v_sub_f32_e32 v2, v13, v22
	v_exp_f32_e32 v2, v2
	s_nop 0
	v_add_f32_e32 v1, v2, v1
	v_sub_f32_e32 v2, v14, v22
	v_exp_f32_e32 v2, v2
	s_nop 0
	v_add_f32_e32 v1, v2, v1
	v_sub_f32_e32 v2, v15, v22
	v_exp_f32_e32 v2, v2
	s_nop 0
	v_add_f32_e32 v1, v2, v1
	v_sub_f32_e32 v2, v20, v22
	v_exp_f32_e32 v2, v2
	v_mov_b32_e32 v18, v1
	v_fmac_f32_e32 v18, v3, v2
	s_cbranch_scc0 .LBB0_251
	ds_bpermute_b32 v1, v105, v0
	v_max_f32_e32 v3, v0, v0
	ds_bpermute_b32 v2, v105, v18
	s_waitcnt lgkmcnt(1)
	v_max_f32_e32 v4, v1, v1
	v_max_f32_e32 v3, v3, v4
	v_cmp_neq_f32_e32 vcc, s29, v3
	s_nop 1
	v_cndmask_b32_e32 v89, 0, v3, vcc
	v_sub_f32_e32 v1, v1, v89
	v_sub_f32_e32 v0, v0, v89
	v_exp_f32_e32 v1, v1
	v_exp_f32_e32 v3, v0
	v_mov_b32_e32 v0, 0
	s_waitcnt lgkmcnt(0)
	v_mul_f32_e32 v1, v1, v2
	v_fmac_f32_e32 v1, v18, v3
	v_max_f32_e32 v1, 0xda24260, v1
	v_div_scale_f32 v2, s[20:21], v1, v1, 1.0
	v_rcp_f32_e32 v3, v2
	v_div_scale_f32 v4, vcc, 1.0, v1, 1.0
	s_mov_b32 s6, 0
	v_fma_f32 v5, -v2, v3, 1.0
	v_fmac_f32_e32 v3, v5, v3
	v_mul_f32_e32 v5, v4, v3
	v_fma_f32 v6, -v2, v5, v4
	v_fmac_f32_e32 v5, v6, v3
	v_fma_f32 v2, -v2, v5, v4
	v_div_fmas_f32 v2, v2, v3, v5
	v_div_fixup_f32 v109, v2, v1, 1.0
	v_mov_b64_e32 v[98:99], v[86:87]
	v_mov_b64_e32 v[100:101], v[84:85]
	v_mov_b32_e32 v110, v106
	v_mov_b32_e32 v1, v0
	v_mov_b32_e32 v2, v0
	v_mov_b32_e32 v3, v0
	v_mov_b32_e32 v4, v0
	v_mov_b32_e32 v5, v0
	v_mov_b32_e32 v6, v0
	v_mov_b32_e32 v7, v0
	v_mov_b32_e32 v8, v0
	v_mov_b32_e32 v9, v0
	v_mov_b32_e32 v10, v0
	v_mov_b32_e32 v11, v0
	v_mov_b32_e32 v12, v0
	v_mov_b32_e32 v13, v0
	v_mov_b32_e32 v14, v0
	v_mov_b32_e32 v15, v0
	v_mov_b32_e32 v16, v0
	v_mov_b32_e32 v17, v0
	v_mov_b32_e32 v18, v0
	v_mov_b32_e32 v19, v0
	v_mov_b32_e32 v20, v0
	v_mov_b32_e32 v21, v0
	v_mov_b32_e32 v22, v0
	v_mov_b32_e32 v23, v0
	v_mov_b32_e32 v24, v0
	v_mov_b32_e32 v25, v0
	v_mov_b32_e32 v26, v0
	v_mov_b32_e32 v27, v0
	v_mov_b32_e32 v28, v0
	v_mov_b32_e32 v29, v0
	v_mov_b32_e32 v30, v0
	v_mov_b32_e32 v31, v0
.LBB0_253:
	v_lshl_add_u64 v[32:33], v[100:101], 0, s[8:9]
	s_mov_b32 s19, 0x1e800000
	v_add_co_u32_e32 v36, vcc, s19, v32
	s_mov_b32 s19, 0x1e840000
	s_nop 0
	v_addc_co_u32_e32 v37, vcc, 0, v33, vcc
	global_load_dwordx4 v[32:35], v[36:37], off
	global_load_dwordx4 v[112:115], v[36:37], off offset:32
	global_load_dwordx4 v[116:119], v[36:37], off offset:64
	global_load_dwordx4 v[120:123], v[36:37], off offset:96
	v_lshl_add_u64 v[36:37], v[98:99], 0, s[8:9]
	v_add_co_u32_e32 v38, vcc, s19, v36
	s_mov_b32 s19, 0x1e842000
	s_nop 0
	v_addc_co_u32_e32 v39, vcc, 0, v37, vcc
	v_add_co_u32_e32 v36, vcc, s19, v36
	global_load_dwordx2 v[76:77], v[38:39], off
	global_load_dwordx2 v[78:79], v[38:39], off offset:16
	global_load_dwordx2 v[72:73], v[38:39], off offset:32
	global_load_dwordx2 v[74:75], v[38:39], off offset:48
	v_addc_co_u32_e32 v37, vcc, 0, v37, vcc
	global_load_dwordx2 v[68:69], v[36:37], off
	global_load_dwordx2 v[70:71], v[36:37], off offset:16
	global_load_dwordx2 v[64:65], v[36:37], off offset:32
	global_load_dwordx2 v[66:67], v[36:37], off offset:48
	v_add_u32_e32 v111, s6, v103
	v_cmp_gt_u32_e32 vcc, s75, v111
	s_waitcnt vmcnt(0) lgkmcnt(0)
	v_mfma_f32_32x32x16_bf16 v[32:47], v[32:35], v[48:51], 0
	v_mfma_f32_32x32x16_bf16 v[32:47], v[112:115], v[52:55], v[32:47]
	v_add_u32_e32 v112, 0xfffffe50, v110
	v_cmp_le_u32_e64 s[44:45], v112, v108
	s_and_b64 vcc, vcc, s[44:45]
	v_add_u32_e32 v112, 1, v111
	v_mfma_f32_32x32x16_bf16 v[32:47], v[116:119], v[56:59], v[32:47]
	v_mfma_f32_32x32x16_bf16 v[32:47], v[120:123], v[60:63], v[32:47]
	s_nop 11
	v_fma_f32 v32, v32, s28, -v89
	v_exp_f32_e32 v32, v32
	v_fma_f32 v33, v33, s28, -v89
	v_exp_f32_e32 v33, v33
	v_fma_f32 v34, v34, s28, -v89
	v_mul_f32_e32 v32, v109, v32
	v_cndmask_b32_e32 v32, 0, v32, vcc
	v_cmp_gt_u32_e32 vcc, s75, v112
	v_add_u32_e32 v112, 0xfffffe60, v110
	v_cmp_le_u32_e64 s[44:45], v112, v108
	v_exp_f32_e32 v34, v34
	s_and_b64 vcc, vcc, s[44:45]
	v_mul_f32_e32 v33, v109, v33
	v_add_u32_e32 v112, 2, v111
	v_cndmask_b32_e32 v33, 0, v33, vcc
	v_cmp_gt_u32_e32 vcc, s75, v112
	v_add_u32_e32 v112, 0xfffffe70, v110
	v_fma_f32 v35, v35, s28, -v89
	v_cmp_le_u32_e64 s[44:45], v112, v108
	v_exp_f32_e32 v35, v35
	s_and_b64 vcc, vcc, s[44:45]
	v_mul_f32_e32 v34, v109, v34
	v_add_u32_e32 v112, 3, v111
	v_cndmask_b32_e32 v34, 0, v34, vcc
	v_cmp_gt_u32_e32 vcc, s75, v112
	v_add_u32_e32 v112, 0xfffffe80, v110
	v_fma_f32 v36, v36, s28, -v89
	v_cmp_le_u32_e64 s[44:45], v112, v108
	v_exp_f32_e32 v36, v36
	s_and_b64 vcc, vcc, s[44:45]
	v_mul_f32_e32 v35, v109, v35
	v_add_u32_e32 v112, 8, v111
	v_cndmask_b32_e32 v35, 0, v35, vcc
	v_cmp_gt_u32_e32 vcc, s75, v112
	v_add_u32_e32 v112, 0xfffffed0, v110
	v_fma_f32 v37, v37, s28, -v89
	v_cmp_le_u32_e64 s[44:45], v112, v108
	v_exp_f32_e32 v37, v37
	s_and_b64 vcc, vcc, s[44:45]
	v_mul_f32_e32 v36, v109, v36
	v_add_u32_e32 v112, 9, v111
	v_cndmask_b32_e32 v36, 0, v36, vcc
	v_cmp_gt_u32_e32 vcc, s75, v112
	v_add_u32_e32 v112, 0xfffffee0, v110
	v_fma_f32 v38, v38, s28, -v89
	v_cmp_le_u32_e64 s[44:45], v112, v108
	v_exp_f32_e32 v38, v38
	s_and_b64 vcc, vcc, s[44:45]
	v_mul_f32_e32 v37, v109, v37
	v_add_u32_e32 v112, 10, v111
	v_cndmask_b32_e32 v37, 0, v37, vcc
	v_cmp_gt_u32_e32 vcc, s75, v112
	v_add_u32_e32 v112, 0xfffffef0, v110
	v_fma_f32 v39, v39, s28, -v89
	v_cmp_le_u32_e64 s[44:45], v112, v108
	v_exp_f32_e32 v39, v39
	s_and_b64 vcc, vcc, s[44:45]
	v_mul_f32_e32 v38, v109, v38
	v_add_u32_e32 v112, 11, v111
	v_cndmask_b32_e32 v38, 0, v38, vcc
	v_cmp_gt_u32_e32 vcc, s75, v112
	v_add_u32_e32 v112, 0xffffff00, v110
	v_fma_f32 v40, v40, s28, -v89
	v_cmp_le_u32_e64 s[44:45], v112, v108
	v_exp_f32_e32 v40, v40
	s_and_b64 vcc, vcc, s[44:45]
	v_mul_f32_e32 v39, v109, v39
	v_add_u32_e32 v112, 16, v111
	v_cndmask_b32_e32 v39, 0, v39, vcc
	v_cmp_gt_u32_e32 vcc, s75, v112
	v_add_u32_e32 v112, 0xffffff50, v110
	v_fma_f32 v41, v41, s28, -v89
	v_cmp_le_u32_e64 s[44:45], v112, v108
	v_exp_f32_e32 v41, v41
	s_and_b64 vcc, vcc, s[44:45]
	v_mul_f32_e32 v40, v109, v40
	v_add_u32_e32 v112, 17, v111
	v_cndmask_b32_e32 v40, 0, v40, vcc
	v_cmp_gt_u32_e32 vcc, s75, v112
	v_add_u32_e32 v112, 0xffffff60, v110
	v_fma_f32 v42, v42, s28, -v89
	v_cmp_le_u32_e64 s[44:45], v112, v108
	v_exp_f32_e32 v42, v42
	s_and_b64 vcc, vcc, s[44:45]
	v_mul_f32_e32 v41, v109, v41
	v_add_u32_e32 v112, 18, v111
	v_cndmask_b32_e32 v41, 0, v41, vcc
	v_cmp_gt_u32_e32 vcc, s75, v112
	v_add_u32_e32 v112, 0xffffff70, v110
	v_cmp_le_u32_e64 s[44:45], v112, v108
	s_and_b64 vcc, vcc, s[44:45]
	v_mul_f32_e32 v42, v109, v42
	v_cndmask_b32_e32 v112, 0, v42, vcc
	v_add_u32_e32 v42, 19, v111
	v_cmp_gt_u32_e32 vcc, s75, v42
	v_add_u32_e32 v42, 0xffffff80, v110
	v_cmp_le_u32_e64 s[44:45], v42, v108
	v_fma_f32 v42, v43, s28, -v89
	v_exp_f32_e32 v42, v42
	s_and_b64 vcc, vcc, s[44:45]
	v_fma_f32 v43, 0.5, v35, v34
	v_add_f32_e32 v117, v36, v37
	v_mul_f32_e32 v42, v109, v42
	v_cndmask_b32_e32 v113, 0, v42, vcc
	v_add_u32_e32 v42, 24, v111
	v_cmp_gt_u32_e32 vcc, s75, v42
	v_subrev_u32_e32 v42, 48, v110
	v_cmp_le_u32_e64 s[44:45], v42, v108
	v_fma_f32 v42, v44, s28, -v89
	v_exp_f32_e32 v42, v42
	s_and_b64 vcc, vcc, s[44:45]
	v_fma_f32 v118, 0.5, v39, v38
	v_add_f32_e32 v117, v117, v118
	v_mul_f32_e32 v42, v109, v42
	v_cndmask_b32_e32 v114, 0, v42, vcc
	v_add_u32_e32 v42, 25, v111
	v_cmp_gt_u32_e32 vcc, s75, v42
	v_subrev_u32_e32 v42, 32, v110
	v_cmp_le_u32_e64 s[44:45], v42, v108
	v_fma_f32 v42, v45, s28, -v89
	v_exp_f32_e32 v42, v42
	s_and_b64 vcc, vcc, s[44:45]
	v_mul_f32_e32 v42, v109, v42
	v_cndmask_b32_e32 v115, 0, v42, vcc
	v_add_u32_e32 v42, 26, v111
	v_cmp_gt_u32_e32 vcc, s75, v42
	v_add_u32_e32 v42, -16, v110
	v_cmp_le_u32_e64 s[44:45], v42, v108
	v_fma_f32 v42, v46, s28, -v89
	v_exp_f32_e32 v42, v42
	s_and_b64 vcc, vcc, s[44:45]
	v_cmp_le_u32_e64 s[44:45], v110, v108
	v_mul_f32_e32 v42, v109, v42
	v_cndmask_b32_e32 v46, 0, v42, vcc
	v_add_u32_e32 v42, 27, v111
	v_cmp_gt_u32_e32 vcc, s75, v42
	v_fma_f32 v42, v47, s28, -v89
	v_exp_f32_e32 v42, v42
	s_and_b64 vcc, vcc, s[44:45]
	v_add_u32_e32 v111, s6, v107
	v_add_u32_e32 v116, 0x1000, v111
	v_mul_f32_e32 v42, v109, v42
	v_cndmask_b32_e32 v47, 0, v42, vcc
	v_add_f32_e32 v42, v32, v33
	v_add_f32_e32 v44, v42, v43
	ds_read2_b32 v[42:43], v111 offset1:2
	v_cvt_pk_bf16_f32 v32, v32, v33
	v_cvt_pk_bf16_f32 v33, v34, v35
	v_cvt_pk_bf16_f32 v34, v36, v37
	v_cvt_pk_bf16_f32 v36, v40, v41
	s_waitcnt lgkmcnt(0)
	v_add_f32_e32 v42, v42, v44
	ds_read2_b32 v[44:45], v116 offset0:32 offset1:34
	v_add_f32_e32 v43, v43, v117
	ds_write2_b32 v111, v42, v43 offset1:2
	v_add_f32_e32 v42, v40, v41
	v_fma_f32 v43, 0.5, v113, v112
	s_waitcnt lgkmcnt(1)
	v_fma_f32 v44, 0.5, v35, v44
	v_cvt_pk_bf16_f32 v35, v38, v39
	v_fmac_f32_e32 v45, 0.5, v39
	ds_write2_b32 v116, v44, v45 offset0:32 offset1:34
	v_mfma_f32_32x32x16_bf16 v[0:15], v[76:79], v[32:35], v[0:15]
	v_add_f32_e32 v44, v42, v43
	ds_read2_b32 v[42:43], v111 offset0:4 offset1:6
	v_cvt_pk_bf16_f32 v37, v112, v113
	v_cvt_pk_bf16_f32 v38, v114, v115
	v_cvt_pk_bf16_f32 v39, v46, v47
	v_add_f32_e32 v117, v114, v115
	s_waitcnt lgkmcnt(0)
	v_add_f32_e32 v42, v44, v42
	v_mfma_f32_32x32x16_bf16 v[16:31], v[68:71], v[32:35], v[16:31]
	ds_read2_b32 v[44:45], v116 offset0:36 offset1:38
	v_fma_f32 v118, 0.5, v47, v46
	v_add_f32_e32 v117, v117, v118
	v_add_f32_e32 v43, v117, v43
	ds_write2_b32 v111, v42, v43 offset0:4 offset1:6
	s_waitcnt lgkmcnt(1)
	v_fma_f32 v44, 0.5, v113, v44
	v_fmac_f32_e32 v45, 0.5, v47
	v_mfma_f32_32x32x16_bf16 v[0:15], v[72:75], v[36:39], v[0:15]
	ds_write2_b32 v116, v44, v45 offset0:36 offset1:38
	v_mfma_f32_32x32x16_bf16 v[16:31], v[64:67], v[36:39], v[16:31]
	s_add_i32 s6, s6, 32
	v_add_u32_e32 v110, 0x200, v110
	v_lshl_add_u64 v[100:101], v[100:101], 0, s[24:25]
	s_cmp_eq_u32 s15, s6
	v_lshl_add_u64 v[98:99], v[98:99], 0, 64
	s_cbranch_scc0 .LBB0_253
	s_mul_i32 s6, s18, 3
	v_lshl_add_u64 v[32:33], s[6:7], 1, v[94:95]
	global_load_ushort v32, v[32:33], off
	s_lshl_b32 s6, s17, 1
	s_waitcnt vmcnt(0) lgkmcnt(0)
	v_lshlrev_b32_e32 v32, 16, v32
	v_mul_f32_e32 v32, 0xbfb8aa3b, v32
	v_exp_f32_e32 v32, v32
	s_nop 0
	v_add_f32_e32 v32, 1.0, v32
	v_rcp_f32_e32 v32, v32
	s_nop 0
	v_pk_mul_f32 v[0:1], v[0:1], v[32:33] op_sel_hi:[1,0]
	v_pk_mul_f32 v[2:3], v[2:3], v[32:33] op_sel_hi:[1,0]
	v_pk_mul_f32 v[16:17], v[16:17], v[32:33] op_sel_hi:[1,0]
	v_pk_mul_f32 v[18:19], v[18:19], v[32:33] op_sel_hi:[1,0]
	v_pk_mul_f32 v[4:5], v[4:5], v[32:33] op_sel_hi:[1,0]
	v_pk_mul_f32 v[20:21], v[20:21], v[32:33] op_sel_hi:[1,0]
	v_pk_mul_f32 v[6:7], v[6:7], v[32:33] op_sel_hi:[1,0]
	v_pk_mul_f32 v[22:23], v[22:23], v[32:33] op_sel_hi:[1,0]
	v_pk_mul_f32 v[8:9], v[8:9], v[32:33] op_sel_hi:[1,0]
	v_pk_mul_f32 v[24:25], v[24:25], v[32:33] op_sel_hi:[1,0]
	v_pk_mul_f32 v[10:11], v[10:11], v[32:33] op_sel_hi:[1,0]
	v_pk_mul_f32 v[26:27], v[26:27], v[32:33] op_sel_hi:[1,0]
	v_pk_mul_f32 v[12:13], v[12:13], v[32:33] op_sel_hi:[1,0]
	v_pk_mul_f32 v[28:29], v[28:29], v[32:33] op_sel_hi:[1,0]
	v_pk_mul_f32 v[14:15], v[14:15], v[32:33] op_sel_hi:[1,0]
	v_pk_mul_f32 v[30:31], v[30:31], v[32:33] op_sel_hi:[1,0]
	v_lshl_add_u64 v[32:33], v[96:97], 0, s[6:7]
	v_cvt_pk_bf16_f32 v0, v0, v1
	v_cvt_pk_bf16_f32 v1, v2, v3
	flat_store_dwordx2 v[32:33], v[0:1]
	v_cvt_pk_bf16_f32 v0, v4, v5
	v_cvt_pk_bf16_f32 v1, v6, v7
	flat_store_dwordx2 v[32:33], v[0:1] offset:16
	v_cvt_pk_bf16_f32 v0, v8, v9
	v_cvt_pk_bf16_f32 v1, v10, v11
	flat_store_dwordx2 v[32:33], v[0:1] offset:32
	v_cvt_pk_bf16_f32 v0, v12, v13
	v_cvt_pk_bf16_f32 v1, v14, v15
	flat_store_dwordx2 v[32:33], v[0:1] offset:48
	v_cvt_pk_bf16_f32 v0, v16, v17
	v_cvt_pk_bf16_f32 v1, v18, v19
	flat_store_dwordx2 v[32:33], v[0:1] offset:64
	v_cvt_pk_bf16_f32 v0, v20, v21
	v_cvt_pk_bf16_f32 v1, v22, v23
	flat_store_dwordx2 v[32:33], v[0:1] offset:80
	v_cvt_pk_bf16_f32 v0, v24, v25
	v_cvt_pk_bf16_f32 v1, v26, v27
	flat_store_dwordx2 v[32:33], v[0:1] offset:96
	v_cvt_pk_bf16_f32 v0, v28, v29
	v_cvt_pk_bf16_f32 v1, v30, v31
	flat_store_dwordx2 v[32:33], v[0:1] offset:112
	s_add_i32 s16, s16, 1
	s_cmp_eq_u32 s16, 4
	s_cbranch_scc0 .LBB0_250
	v_add_u32_e32 v0, 0x1080, v102
	ds_read2_b32 v[0:1], v0 offset1:1
	v_add_u32_e32 v10, 0x1088, v102
	v_add_u32_e32 v12, 0x1090, v102
	ds_read2_b32 v[2:3], v102 offset0:1 offset1:2
	ds_read2_b32 v[4:5], v102 offset0:3 offset1:4
	ds_read2_b32 v[6:7], v102 offset0:5 offset1:6
	ds_read2_b32 v[8:9], v102 offset0:7 offset1:8
	ds_read2_b32 v[10:11], v10 offset1:1
	ds_read2_b32 v[12:13], v12 offset1:1
	ds_read_b32 v28, v102 offset:4344
	s_lshr_b32 s8, s13, 6
	s_waitcnt lgkmcnt(0)
	v_add_f32_e32 v1, v3, v1
	v_add_u32_e32 v3, 0x1098, v102
	v_add_u32_e32 v16, 0x10a0, v102
	v_add_u32_e32 v18, 0x10a8, v102
	v_add_u32_e32 v20, 0x10b0, v102
	s_cmpk_gt_u32 s13, 0x7f
	ds_read2_b32 v[14:15], v3 offset1:1
	ds_read2_b32 v[16:17], v16 offset1:1
	ds_read2_b32 v[18:19], v18 offset1:1
	ds_read2_b32 v[46:47], v20 offset1:1
	ds_read2_b32 v[48:49], v102 offset0:9 offset1:10
	ds_read2_b32 v[50:51], v102 offset0:11 offset1:12
	ds_read2_b32 v[52:53], v102 offset0:13 offset1:14
	ds_read2_b32 v[54:55], v102 offset0:15 offset1:16
	v_add_u32_e32 v3, 0x10b8, v102
	v_add_u32_e32 v20, 0x10c0, v102
	v_add_u32_e32 v21, 0x10c8, v102
	v_add_u32_e32 v22, 0x10d0, v102
	s_cselect_b64 vcc, -1, 0
	s_and_b32 s9, s14, 0x7fffffc
	ds_read2_b32 v[56:57], v3 offset1:1
	ds_read2_b32 v[58:59], v20 offset1:1
	ds_read2_b32 v[60:61], v21 offset1:1
	ds_read2_b32 v[20:21], v22 offset1:1
	ds_read2_b32 v[62:63], v102 offset0:17 offset1:18
	ds_read2_b32 v[64:65], v102 offset0:19 offset1:20
	ds_read2_b32 v[42:43], v102 offset0:21 offset1:22
	ds_read2_b32 v[22:23], v102 offset0:23 offset1:24
	v_add_u32_e32 v3, 0x10d8, v102
	v_add_u32_e32 v24, 0x10e0, v102
	v_add_u32_e32 v26, 0x10e8, v102
	s_cmp_lg_u32 s9, 4
	v_add_u32_e32 v29, 0x10f0, v102
	ds_read2_b32 v[40:41], v3 offset1:1
	ds_read2_b32 v[24:25], v24 offset1:1
	ds_read2_b32 v[26:27], v26 offset1:1
	ds_read2_b32 v[30:31], v29 offset1:1
	ds_read2_b32 v[38:39], v102 offset0:25 offset1:26
	ds_read2_b32 v[36:37], v102 offset0:27 offset1:28
	ds_read2_b32 v[34:35], v102 offset0:29 offset1:30
	ds_read_b32 v32, v102 offset:124
	v_cndmask_b32_e32 v1, v212, v1, vcc
	v_mov_b32_e32 v44, 0x7f800000
	s_cselect_b64 vcc, -1, 0
	v_mov_b32_e32 v66, v4
	v_mov_b32_e32 v67, v2
	v_mov_b32_e32 v2, v10
	v_mov_b32_e32 v3, v0
	s_cmpk_gt_u32 s13, 0xbf
	v_cndmask_b32_e32 v45, v44, v1, vcc
	v_pk_add_f32 v[0:1], v[66:67], v[2:3]
	s_cselect_b64 vcc, -1, 0
	s_cmp_gt_u32 s13, 63
	v_cndmask_b32_e32 v0, v212, v0, vcc
	s_cselect_b64 vcc, -1, 0
	s_add_i32 s6, s8, -3
	s_add_i32 s14, s8, -1
	s_cmp_gt_u32 s14, 1
	v_cndmask_b32_e32 v1, v212, v1, vcc
	s_cselect_b64 vcc, -1, 0
	s_cmp_gt_u32 s6, 1
	v_cndmask_b32_e32 v1, v44, v1, vcc
	s_cselect_b64 vcc, -1, 0
	v_mov_b32_e32 v4, v7
	v_mov_b32_e32 v10, v13
	s_cmpk_gt_u32 s13, 0x17f
	v_cndmask_b32_e32 v0, v44, v0, vcc
	v_pk_add_f32 v[2:3], v[4:5], v[10:11]
	s_cselect_b64 vcc, -1, 0
	s_cmpk_gt_u32 s13, 0xff
	v_cndmask_b32_e32 v2, v212, v2, vcc
	s_cselect_b64 vcc, -1, 0
	s_cmp_lg_u32 s9, 8
	v_cndmask_b32_e32 v3, v212, v3, vcc
	s_cselect_b64 vcc, -1, 0
	s_cmp_lg_u32 s9, 12
	v_cndmask_b32_e32 v3, v44, v3, vcc
	s_cselect_b64 vcc, -1, 0
	v_mov_b32_e32 v4, v8
	v_mov_b32_e32 v5, v6
	s_waitcnt lgkmcnt(0)
	v_mov_b32_e32 v6, v14
	v_mov_b32_e32 v7, v12
	s_cmpk_gt_u32 s13, 0x1bf
	v_cndmask_b32_e32 v2, v44, v2, vcc
	v_pk_add_f32 v[4:5], v[4:5], v[6:7]
	s_cselect_b64 vcc, -1, 0
	s_cmpk_gt_u32 s13, 0x13f
	v_cndmask_b32_e32 v4, v212, v4, vcc
	s_cselect_b64 vcc, -1, 0
	s_add_i32 s14, s8, -7
	s_add_i32 s15, s8, -5
	s_cmp_gt_u32 s15, 1
	v_cndmask_b32_e32 v5, v212, v5, vcc
	s_cselect_b64 vcc, -1, 0
	s_cmp_gt_u32 s14, 1
	v_cndmask_b32_e32 v5, v44, v5, vcc
	s_cselect_b64 vcc, -1, 0
	v_mov_b32_e32 v8, v49
	v_mov_b32_e32 v14, v17
	s_cmpk_gt_u32 s13, 0x27f
	v_cndmask_b32_e32 v4, v44, v4, vcc
	v_pk_add_f32 v[6:7], v[8:9], v[14:15]
	s_cselect_b64 vcc, -1, 0
	s_cmpk_gt_u32 s13, 0x1ff
	v_cndmask_b32_e32 v6, v212, v6, vcc
	s_cselect_b64 vcc, -1, 0
	s_cmp_lg_u32 s9, 16
	v_cndmask_b32_e32 v7, v212, v7, vcc
	s_cselect_b64 vcc, -1, 0
	s_cmp_lg_u32 s9, 20
	v_cndmask_b32_e32 v7, v44, v7, vcc
	s_cselect_b64 vcc, -1, 0
	v_mov_b32_e32 v8, v50
	v_mov_b32_e32 v9, v48
	v_mov_b32_e32 v10, v18
	v_mov_b32_e32 v11, v16
	s_cmpk_gt_u32 s13, 0x2bf
	v_cndmask_b32_e32 v6, v44, v6, vcc
	v_pk_add_f32 v[8:9], v[8:9], v[10:11]
	s_cselect_b64 vcc, -1, 0
	s_cmpk_gt_u32 s13, 0x23f
	v_cndmask_b32_e32 v8, v212, v8, vcc
	s_cselect_b64 vcc, -1, 0
	s_add_i32 s14, s8, -11
	s_add_i32 s15, s8, -9
	s_cmp_gt_u32 s15, 1
	v_cndmask_b32_e32 v9, v212, v9, vcc
	s_cselect_b64 vcc, -1, 0
	s_cmp_gt_u32 s14, 1
	v_cndmask_b32_e32 v9, v44, v9, vcc
	s_cselect_b64 vcc, -1, 0
	v_mov_b32_e32 v50, v53
	v_mov_b32_e32 v18, v47
	s_cmpk_gt_u32 s13, 0x37f
	v_cndmask_b32_e32 v8, v44, v8, vcc
	v_pk_add_f32 v[10:11], v[50:51], v[18:19]
	s_cselect_b64 vcc, -1, 0
	s_cmpk_gt_u32 s13, 0x2ff
	v_cndmask_b32_e32 v10, v212, v10, vcc
	s_cselect_b64 vcc, -1, 0
	s_cmp_lg_u32 s9, 24
	v_cndmask_b32_e32 v11, v212, v11, vcc
	s_cselect_b64 vcc, -1, 0
	s_cmp_lg_u32 s9, 28
	v_cndmask_b32_e32 v11, v44, v11, vcc
	s_cselect_b64 vcc, -1, 0
	v_mov_b32_e32 v12, v54
	v_mov_b32_e32 v13, v52
	v_mov_b32_e32 v14, v56
	v_mov_b32_e32 v15, v46
	s_cmpk_gt_u32 s13, 0x3bf
	v_cndmask_b32_e32 v10, v44, v10, vcc
	v_pk_add_f32 v[12:13], v[12:13], v[14:15]
	s_cselect_b64 vcc, -1, 0
	s_cmpk_gt_u32 s13, 0x33f
	v_cndmask_b32_e32 v12, v212, v12, vcc
	s_cselect_b64 vcc, -1, 0
	s_add_i32 s14, s8, -15
	s_add_i32 s15, s8, -13
	s_cmp_gt_u32 s15, 1
	v_cndmask_b32_e32 v13, v212, v13, vcc
	s_cselect_b64 vcc, -1, 0
	s_cmp_gt_u32 s14, 1
	v_cndmask_b32_e32 v13, v44, v13, vcc
	s_cselect_b64 vcc, -1, 0
	v_mov_b32_e32 v54, v63
	v_mov_b32_e32 v56, v59
	s_cmpk_gt_u32 s13, 0x47f
	v_cndmask_b32_e32 v12, v44, v12, vcc
	v_pk_add_f32 v[14:15], v[54:55], v[56:57]
	s_cselect_b64 vcc, -1, 0
	s_cmpk_gt_u32 s13, 0x3ff
	v_cndmask_b32_e32 v14, v212, v14, vcc
	s_cselect_b64 vcc, -1, 0
	s_cmp_lg_u32 s9, 32
	v_cndmask_b32_e32 v15, v212, v15, vcc
	s_cselect_b64 vcc, -1, 0
	s_cmp_lg_u32 s9, 36
	v_cndmask_b32_e32 v15, v44, v15, vcc
	s_cselect_b64 vcc, -1, 0
	v_mov_b32_e32 v16, v64
	v_mov_b32_e32 v17, v62
	v_mov_b32_e32 v18, v60
	v_mov_b32_e32 v19, v58
	s_cmpk_gt_u32 s13, 0x4bf
	v_cndmask_b32_e32 v14, v44, v14, vcc
	v_pk_add_f32 v[16:17], v[16:17], v[18:19]
	s_cselect_b64 vcc, -1, 0
	s_cmpk_gt_u32 s13, 0x43f
	v_cndmask_b32_e32 v16, v212, v16, vcc
	s_cselect_b64 vcc, -1, 0
	s_sub_i32 s14, s8, 19
	s_sub_i32 s15, s8, 17
	s_cmp_gt_u32 s15, 1
	v_cndmask_b32_e32 v17, v212, v17, vcc
	s_cselect_b64 vcc, -1, 0
	s_cmp_gt_u32 s14, 1
	v_cndmask_b32_e32 v17, v44, v17, vcc
	s_cselect_b64 vcc, -1, 0
	v_mov_b32_e32 v64, v43
	v_mov_b32_e32 v60, v21
	s_cmpk_gt_u32 s13, 0x57f
	v_cndmask_b32_e32 v16, v44, v16, vcc
	v_pk_add_f32 v[18:19], v[64:65], v[60:61]
	s_cselect_b64 vcc, -1, 0
	s_cmpk_gt_u32 s13, 0x4ff
	v_cndmask_b32_e32 v18, v212, v18, vcc
	s_cselect_b64 vcc, -1, 0
	s_cmp_lg_u32 s9, 40
	v_cndmask_b32_e32 v19, v212, v19, vcc
	s_cselect_b64 vcc, -1, 0
	s_cmp_lg_u32 s9, 44
	v_cndmask_b32_e32 v19, v44, v19, vcc
	s_cselect_b64 vcc, -1, 0
	v_mov_b32_e32 v46, v22
	v_mov_b32_e32 v47, v42
	v_mov_b32_e32 v42, v40
	v_mov_b32_e32 v43, v20
	s_cmpk_gt_u32 s13, 0x5bf
	v_cndmask_b32_e32 v18, v44, v18, vcc
	v_pk_add_f32 v[20:21], v[46:47], v[42:43]
	s_cselect_b64 vcc, -1, 0
	s_cmpk_gt_u32 s13, 0x53f
	v_cndmask_b32_e32 v20, v212, v20, vcc
	s_cselect_b64 vcc, -1, 0
	s_sub_i32 s14, s8, 23
	s_sub_i32 s15, s8, 21
	s_cmp_gt_u32 s15, 1
	v_cndmask_b32_e32 v21, v212, v21, vcc
	s_cselect_b64 vcc, -1, 0
	s_cmp_gt_u32 s14, 1
	v_cndmask_b32_e32 v21, v44, v21, vcc
	s_cselect_b64 vcc, -1, 0
	v_mov_b32_e32 v22, v39
	v_mov_b32_e32 v40, v25
	s_cmpk_gt_u32 s13, 0x67f
	v_cndmask_b32_e32 v20, v44, v20, vcc
	v_pk_add_f32 v[22:23], v[22:23], v[40:41]
	s_cselect_b64 vcc, -1, 0
	s_cmpk_gt_u32 s13, 0x5ff
	v_cndmask_b32_e32 v22, v212, v22, vcc
	s_cselect_b64 vcc, -1, 0
	s_cmp_lg_u32 s9, 48
	v_cndmask_b32_e32 v23, v212, v23, vcc
	s_cselect_b64 vcc, -1, 0
	s_cmp_lg_u32 s9, 52
	v_cndmask_b32_e32 v23, v44, v23, vcc
	s_cselect_b64 vcc, -1, 0
	v_mov_b32_e32 v40, v36
	v_mov_b32_e32 v41, v38
	v_mov_b32_e32 v38, v26
	v_mov_b32_e32 v39, v24
	s_cmpk_gt_u32 s13, 0x6bf
	v_cndmask_b32_e32 v22, v44, v22, vcc
	v_pk_add_f32 v[24:25], v[40:41], v[38:39]
	s_cselect_b64 vcc, -1, 0
	s_cmpk_gt_u32 s13, 0x63f
	v_cndmask_b32_e32 v24, v212, v24, vcc
	s_cselect_b64 vcc, -1, 0
	s_sub_i32 s14, s8, 27
	s_sub_i32 s15, s8, 25
	s_cmp_gt_u32 s15, 1
	v_cndmask_b32_e32 v25, v212, v25, vcc
	s_cselect_b64 vcc, -1, 0
	s_cmp_gt_u32 s14, 1
	v_cndmask_b32_e32 v25, v44, v25, vcc
	s_cselect_b64 vcc, -1, 0
	v_mov_b32_e32 v36, v35
	v_mov_b32_e32 v26, v31
	s_cmpk_gt_u32 s13, 0x77f
	v_cndmask_b32_e32 v24, v44, v24, vcc
	v_pk_add_f32 v[26:27], v[36:37], v[26:27]
	s_cselect_b64 vcc, -1, 0
	s_cmpk_gt_u32 s13, 0x6ff
	v_cndmask_b32_e32 v26, v212, v26, vcc
	s_cselect_b64 vcc, -1, 0
	s_cmp_lg_u32 s9, 56
	v_cndmask_b32_e32 v27, v212, v27, vcc
	s_cselect_b64 vcc, -1, 0
	s_cmp_lg_u32 s9, 60
	v_cndmask_b32_e32 v27, v44, v27, vcc
	s_cselect_b64 vcc, -1, 0
	v_mov_b32_e32 v33, v34
	v_mov_b32_e32 v29, v30
	s_cmpk_gt_u32 s13, 0x7bf
	v_cndmask_b32_e32 v26, v44, v26, vcc
	v_pk_add_f32 v[28:29], v[32:33], v[28:29]
	s_cselect_b64 vcc, -1, 0
	s_cmpk_gt_u32 s13, 0x73f
	v_cndmask_b32_e32 v28, v212, v28, vcc
	s_cselect_b64 vcc, -1, 0
	s_sub_i32 s9, s8, 31
	s_sub_i32 s8, s8, 29
	s_cmp_gt_u32 s8, 1
	v_cndmask_b32_e32 v29, v212, v29, vcc
	s_cselect_b64 vcc, -1, 0
	s_cmp_gt_u32 s9, 1
	v_cndmask_b32_e32 v29, v44, v29, vcc
	s_cselect_b64 vcc, -1, 0
	s_mov_b32 s6, 8
	v_cndmask_b32_e32 v28, v44, v28, vcc
	v_mov_b32_e32 v30, 0

.LBB0_269:
	s_andn2_b64 vcc, exec, s[12:13]
	s_cbranch_vccnz .LBB0_264
	v_lshl_add_u32 v2, s10, 10, v13
	v_ashrrev_i32_e32 v3, 31, v2
	v_lshl_add_u64 v[2:3], v[2:3], 2, s[90:91]
	global_load_dwordx2 v[2:3], v[2:3], off
	ds_bpermute_b32 v1, v12, v0
	s_lshl_b32 s12, s17, 1
	s_or_b32 s12, s12, s6
	s_ashr_i32 s13, s12, 31
	s_ashr_i32 s11, s10, 31
	s_lshl_b64 s[12:13], s[12:13], 14
	s_add_u32 s6, s48, s12
	s_addc_u32 s12, s49, s13
	s_lshl_b64 s[10:11], s[10:11], 7
	s_add_u32 s10, s6, s10
	s_addc_u32 s11, s12, s11
	s_waitcnt vmcnt(0) lgkmcnt(0)
	v_mul_f32_e32 v1, v3, v1
	v_cndmask_b32_e64 v1, v1, -v1, s[42:43]
	v_fmac_f32_e32 v1, v0, v2
	v_cvt_pk_bf16_f32 v2, v1, s0
	v_lshl_add_u64 v[0:1], s[10:11], 0, v[176:177]
	flat_store_short v[0:1], v2
	s_branch .LBB0_264

.LBB0_278:
	v_add_co_u32_e32 v36, vcc, 0xfdfff400, v22
	s_movk_i32 s10, 0xfc00
	s_nop 0
	v_addc_co_u32_e32 v37, vcc, -1, v23, vcc
	global_load_dwordx4 v[8:11], v[36:37], off
	v_add_co_u32_e32 v32, vcc, 0xfdfff800, v22
	s_mov_b64 s[46:47], vcc
	v_add_co_u32_e32 v26, vcc, 0xfdfffc00, v22
	s_mov_b64 s[42:43], vcc
	v_add_co_u32_e32 v24, vcc, 0xfe000000, v22
	s_mov_b64 s[44:45], vcc
	v_add_co_u32_e32 v34, vcc, 0xfffff400, v22
	s_add_i32 s6, s6, s36
	s_nop 0
	v_addc_co_u32_e32 v35, vcc, -1, v23, vcc
	global_load_dwordx4 v[12:15], v[34:35], off
	v_addc_co_u32_e64 v33, vcc, -1, v23, s[46:47]
	v_add_co_u32_e32 v30, vcc, 0xfffff800, v22
	global_load_dwordx4 v[4:7], v[32:33], off
	s_nop 0
	v_addc_co_u32_e32 v31, vcc, -1, v23, vcc
	global_load_dwordx4 v[0:3], v[30:31], off
	s_cmpk_gt_i32 s6, 0x1fff
	s_waitcnt vmcnt(0) lgkmcnt(0)
	v_and_b32_e32 v53, 0xffff0000, v8
	v_lshlrev_b32_e32 v52, 16, v8
	v_and_b32_e32 v51, 0xffff0000, v9
	v_lshlrev_b32_e32 v50, 16, v9
	v_pk_mul_f32 v[38:39], v[52:53], v[52:53]
	v_pk_mul_f32 v[28:29], v[50:51], v[50:51]
	v_add_f32_e32 v25, v38, v39
	v_and_b32_e32 v49, 0xffff0000, v10
	v_lshlrev_b32_e32 v48, 16, v10
	v_add_f32_e32 v25, v25, v28
	v_and_b32_e32 v47, 0xffff0000, v11
	v_lshlrev_b32_e32 v46, 16, v11
	v_pk_mul_f32 v[10:11], v[48:49], v[48:49]
	v_add_f32_e32 v25, v25, v29
	v_add_f32_e32 v10, v25, v10
	v_and_b32_e32 v45, 0xffff0000, v12
	v_lshlrev_b32_e32 v44, 16, v12
	v_pk_mul_f32 v[8:9], v[46:47], v[46:47]
	v_and_b32_e32 v43, 0xffff0000, v13
	v_lshlrev_b32_e32 v42, 16, v13
	v_pk_mul_f32 v[60:61], v[44:45], v[44:45]
	v_add_f32_e32 v10, v10, v11
	v_pk_mul_f32 v[28:29], v[42:43], v[42:43]
	v_add_f32_e32 v11, v60, v61
	v_add_f32_e32 v8, v10, v8
	v_add_f32_e32 v10, v11, v28
	v_add_f32_e32 v8, v8, v9
	v_and_b32_e32 v41, 0xffff0000, v14
	v_lshlrev_b32_e32 v40, 16, v14
	v_add_f32_e32 v9, v10, v29
	ds_bpermute_b32 v10, v54, v8
	v_and_b32_e32 v39, 0xffff0000, v15
	v_lshlrev_b32_e32 v38, 16, v15
	v_pk_mul_f32 v[14:15], v[40:41], v[40:41]
	v_pk_mul_f32 v[12:13], v[38:39], v[38:39]
	v_add_f32_e32 v9, v9, v14
	v_add_f32_e32 v9, v9, v15
	v_add_f32_e32 v9, v9, v12
	v_add_f32_e32 v9, v9, v13
	s_waitcnt lgkmcnt(0)
	v_add_f32_e32 v8, v8, v10
	ds_bpermute_b32 v11, v54, v9
	ds_bpermute_b32 v10, v55, v8
	s_waitcnt lgkmcnt(1)
	v_add_f32_e32 v25, v9, v11
	s_waitcnt lgkmcnt(0)
	v_add_f32_e32 v28, v8, v10
	global_load_dwordx4 v[12:15], v[16:17], off
	global_load_dwordx4 v[8:11], v[16:17], off offset:16
	ds_bpermute_b32 v27, v55, v25
	ds_bpermute_b32 v29, v56, v28
	s_waitcnt lgkmcnt(1)
	v_add_f32_e32 v25, v25, v27
	ds_bpermute_b32 v27, v56, v25
	s_waitcnt lgkmcnt(1)
	v_add_f32_e32 v28, v28, v29
	ds_bpermute_b32 v29, v57, v28
	s_waitcnt lgkmcnt(1)
	v_add_f32_e32 v25, v25, v27
	ds_bpermute_b32 v27, v57, v25
	s_waitcnt lgkmcnt(1)
	v_add_f32_e32 v28, v28, v29
	ds_bpermute_b32 v29, v58, v28
	s_waitcnt lgkmcnt(1)
	v_add_f32_e32 v25, v25, v27
	ds_bpermute_b32 v27, v58, v25
	s_waitcnt lgkmcnt(1)
	v_add_f32_e32 v29, v28, v29
	ds_bpermute_b32 v60, v59, v29
	v_add_co_u32_e32 v28, vcc, s10, v22
	s_waitcnt lgkmcnt(1)
	v_add_f32_e32 v25, v25, v27
	ds_bpermute_b32 v27, v59, v25
	s_waitcnt lgkmcnt(1)
	v_add_f32_e32 v29, v29, v60
	v_fmamk_f32 v29, v29, 0x3b000000, v204
	s_mov_b64 s[46:47], vcc
	v_mul_f32_e32 v60, 0x4f800000, v29
	v_cmp_gt_f32_e32 vcc, s48, v29
	s_waitcnt lgkmcnt(0)
	v_add_f32_e32 v25, v25, v27
	v_fmamk_f32 v25, v25, 0x3b000000, v204
	v_cndmask_b32_e32 v29, v29, v60, vcc
	v_sqrt_f32_e32 v60, v29
	s_mov_b32 s10, 0xf800000
	v_mul_f32_e32 v27, 0x4f800000, v25
	v_cmp_gt_f32_e64 s[48:49], s10, v25
	v_add_u32_e32 v61, 1, v60
	v_fma_f32 v64, -v61, v60, v29
	v_cndmask_b32_e64 v25, v25, v27, s[48:49]
	v_add_u32_e32 v27, -1, v60
	v_fma_f32 v63, -v27, v60, v29
	v_sqrt_f32_e32 v62, v25
	v_cmp_ge_f32_e64 s[50:51], 0, v63
	v_add_u32_e32 v63, 1, v62
	s_nop 0
	v_cndmask_b32_e64 v27, v60, v27, s[50:51]
	v_cmp_lt_f32_e64 s[50:51], 0, v64
	v_fma_f32 v64, -v63, v62, v25
	s_nop 0
	v_cndmask_b32_e64 v27, v27, v61, s[50:51]
	v_mul_f32_e32 v60, 0x37800000, v27
	v_add_u32_e32 v61, -1, v62
	v_cndmask_b32_e32 v27, v27, v60, vcc
	v_cmp_class_f32_e32 vcc, v29, v205
	v_fma_f32 v60, -v61, v62, v25
	v_cmp_lt_f32_e64 s[50:51], 0, v64
	v_cndmask_b32_e32 v27, v27, v29, vcc
	v_cmp_ge_f32_e32 vcc, 0, v60
	v_div_scale_f32 v60, s[10:11], v27, v27, 1.0
	s_nop 0
	v_cndmask_b32_e32 v29, v62, v61, vcc
	v_rcp_f32_e32 v62, v60
	v_cndmask_b32_e64 v29, v29, v63, s[50:51]
	v_mul_f32_e32 v63, 0x37800000, v29
	v_cndmask_b32_e64 v29, v29, v63, s[48:49]
	v_fma_f32 v63, -v60, v62, 1.0
	v_div_scale_f32 v61, vcc, 1.0, v27, 1.0
	v_fmac_f32_e32 v62, v63, v62
	v_mul_f32_e32 v63, v61, v62
	v_fma_f32 v64, -v60, v63, v61
	v_fmac_f32_e32 v63, v64, v62
	v_fma_f32 v60, -v60, v63, v61
	v_div_fmas_f32 v60, v60, v62, v63
	v_div_fixup_f32 v60, v60, v27, 1.0
	v_cmp_class_f32_e64 s[48:49], v25, v205
	v_pk_mul_f32 v[52:53], v[60:61], v[52:53] op_sel_hi:[0,1]
	v_pk_mul_f32 v[50:51], v[60:61], v[50:51] op_sel_hi:[0,1]
	v_cndmask_b32_e64 v25, v29, v25, s[48:49]
	v_pk_mul_f32 v[48:49], v[60:61], v[48:49] op_sel_hi:[0,1]
	v_pk_mul_f32 v[60:61], v[60:61], v[46:47] op_sel_hi:[0,1]
	s_waitcnt vmcnt(1)
	v_pk_mul_f32 v[46:47], v[12:13], v[52:53]
	v_pk_mul_f32 v[50:51], v[14:15], v[50:51]
	v_div_scale_f32 v29, s[10:11], v25, v25, 1.0
	s_waitcnt vmcnt(0)
	v_pk_mul_f32 v[48:49], v[8:9], v[48:49]
	v_cvt_pk_bf16_f32 v46, v46, v47
	v_cvt_pk_bf16_f32 v47, v50, v51
	v_pk_mul_f32 v[50:51], v[10:11], v[60:61]
	v_and_b32_e32 v61, 0xffff0000, v4
	v_lshlrev_b32_e32 v60, 16, v4
	v_cvt_pk_bf16_f32 v48, v48, v49
	v_rcp_f32_e32 v27, v29
	v_cvt_pk_bf16_f32 v49, v50, v51
	v_and_b32_e32 v51, 0xffff0000, v5
	v_lshlrev_b32_e32 v50, 16, v5
	v_pk_mul_f32 v[4:5], v[60:61], v[60:61]
	v_pk_mul_f32 v[52:53], v[50:51], v[50:51]
	v_add_f32_e32 v4, v4, v5
	flat_store_dwordx4 v[36:37], v[46:49]
	v_add_f32_e32 v4, v4, v52
	v_add_f32_e32 v4, v4, v53
	v_and_b32_e32 v49, 0xffff0000, v6
	v_lshlrev_b32_e32 v48, 16, v6
	v_and_b32_e32 v47, 0xffff0000, v7
	v_lshlrev_b32_e32 v46, 16, v7
	v_pk_mul_f32 v[6:7], v[48:49], v[48:49]
	v_fma_f32 v36, -v29, v27, 1.0
	v_add_f32_e32 v4, v4, v6
	v_fmac_f32_e32 v27, v36, v27
	v_pk_mul_f32 v[36:37], v[46:47], v[46:47]
	v_add_f32_e32 v4, v4, v7
	v_add_f32_e32 v4, v4, v36
	v_add_f32_e32 v4, v4, v37
	ds_bpermute_b32 v5, v54, v4
	v_div_scale_f32 v62, vcc, 1.0, v25, 1.0
	v_mul_f32_e32 v6, v62, v27
	v_fma_f32 v7, -v29, v6, v62
	v_fmac_f32_e32 v6, v7, v27
	s_waitcnt lgkmcnt(0)
	v_add_f32_e32 v5, v4, v5
	v_fma_f32 v7, -v29, v6, v62
	ds_bpermute_b32 v29, v55, v5
	v_div_fmas_f32 v4, v7, v27, v6
	v_div_fixup_f32 v4, v4, v25, 1.0
	v_pk_mul_f32 v[6:7], v[4:5], v[44:45] op_sel_hi:[0,1]
	v_pk_mul_f32 v[36:37], v[4:5], v[42:43] op_sel_hi:[0,1]
	s_waitcnt lgkmcnt(0)
	v_add_f32_e32 v25, v5, v29
	ds_bpermute_b32 v27, v56, v25
	v_pk_mul_f32 v[40:41], v[4:5], v[40:41] op_sel_hi:[0,1]
	v_pk_mul_f32 v[38:39], v[4:5], v[38:39] op_sel_hi:[0,1]
	v_pk_mul_f32 v[4:5], v[12:13], v[6:7]
	v_pk_mul_f32 v[6:7], v[14:15], v[36:37]
	s_waitcnt lgkmcnt(0)
	v_add_f32_e32 v12, v25, v27
	v_cvt_pk_bf16_f32 v4, v4, v5
	ds_bpermute_b32 v13, v57, v12
	v_cvt_pk_bf16_f32 v5, v6, v7
	v_pk_mul_f32 v[6:7], v[8:9], v[40:41]
	v_pk_mul_f32 v[8:9], v[10:11], v[38:39]
	v_cvt_pk_bf16_f32 v6, v6, v7
	v_cvt_pk_bf16_f32 v7, v8, v9
	flat_store_dwordx4 v[34:35], v[4:7]
	global_load_dwordx4 v[8:11], v[16:17], off offset:2048
	s_waitcnt lgkmcnt(0)
	v_add_f32_e32 v12, v12, v13
	ds_bpermute_b32 v13, v58, v12
	s_mov_b32 s48, 0xf800000
	v_addc_co_u32_e64 v27, vcc, -1, v23, s[42:43]
	v_addc_co_u32_e64 v25, s[42:43], -1, v23, s[44:45]
	s_waitcnt lgkmcnt(0)
	v_add_f32_e32 v4, v12, v13
	global_load_dwordx4 v[12:15], v[16:17], off offset:2064
	ds_bpermute_b32 v5, v59, v4
	v_and_b32_e32 v63, 0xffff0000, v0
	v_lshlrev_b32_e32 v62, 16, v0
	v_and_b32_e32 v53, 0xffff0000, v1
	v_lshlrev_b32_e32 v52, 16, v1
	s_waitcnt lgkmcnt(0)
	v_add_f32_e32 v4, v4, v5
	v_fmamk_f32 v4, v4, 0x3b000000, v204
	v_mul_f32_e32 v5, 0x4f800000, v4
	v_cmp_gt_f32_e32 vcc, s48, v4
	v_pk_mul_f32 v[0:1], v[62:63], v[62:63]
	v_and_b32_e32 v45, 0xffff0000, v2
	v_cndmask_b32_e32 v29, v4, v5, vcc
	global_load_dwordx4 v[34:37], v[26:27], off
	global_load_dwordx4 v[4:7], v[24:25], off
	v_sqrt_f32_e32 v38, v29
	v_add_f32_e32 v0, v0, v1
	v_lshlrev_b32_e32 v44, 16, v2
	v_and_b32_e32 v43, 0xffff0000, v3
	v_add_u32_e32 v39, -1, v38
	v_fma_f32 v40, -v39, v38, v29
	v_cmp_ge_f32_e64 s[42:43], 0, v40
	v_add_u32_e32 v40, 1, v38
	v_lshlrev_b32_e32 v42, 16, v3
	v_cndmask_b32_e64 v39, v38, v39, s[42:43]
	v_fma_f32 v38, -v40, v38, v29
	v_cmp_lt_f32_e64 s[42:43], 0, v38
	v_pk_mul_f32 v[2:3], v[44:45], v[44:45]
	s_nop 0
	v_cndmask_b32_e64 v38, v39, v40, s[42:43]
	v_pk_mul_f32 v[40:41], v[52:53], v[52:53]
	v_mul_f32_e32 v39, 0x37800000, v38
	v_add_f32_e32 v0, v0, v40
	v_add_f32_e32 v0, v0, v41
	v_add_f32_e32 v0, v0, v2
	v_cndmask_b32_e32 v64, v38, v39, vcc
	v_pk_mul_f32 v[38:39], v[42:43], v[42:43]
	v_add_f32_e32 v0, v0, v3
	v_add_f32_e32 v0, v0, v38
	v_add_f32_e32 v0, v0, v39
	ds_bpermute_b32 v1, v54, v0
	v_cmp_class_f32_e32 vcc, v29, v205
	s_waitcnt lgkmcnt(0)
	v_add_f32_e32 v0, v0, v1
	ds_bpermute_b32 v1, v55, v0
	v_cndmask_b32_e32 v2, v64, v29, vcc
	v_div_scale_f32 v3, s[10:11], v2, v2, 1.0
	v_rcp_f32_e32 v64, v3
	s_waitcnt lgkmcnt(0)
	v_add_f32_e32 v0, v0, v1
	ds_bpermute_b32 v1, v56, v0
	v_addc_co_u32_e64 v29, vcc, -1, v23, s[46:47]
	v_fma_f32 v65, -v3, v64, 1.0
	v_fmac_f32_e32 v64, v65, v64
	s_waitcnt lgkmcnt(0)
	v_add_f32_e32 v0, v0, v1
	ds_bpermute_b32 v1, v57, v0
	v_div_scale_f32 v65, vcc, 1.0, v2, 1.0
	v_mul_f32_e32 v66, v65, v64
	v_fma_f32 v67, -v3, v66, v65
	v_fmac_f32_e32 v66, v67, v64
	v_fma_f32 v3, -v3, v66, v65
	s_waitcnt lgkmcnt(0)
	v_add_f32_e32 v1, v0, v1
	v_div_fmas_f32 v3, v3, v64, v66
	ds_bpermute_b32 v64, v58, v1
	v_div_fixup_f32 v0, v3, v2, 1.0
	v_pk_mul_f32 v[2:3], v[0:1], v[60:61] op_sel_hi:[0,1]
	v_pk_mul_f32 v[50:51], v[0:1], v[50:51] op_sel_hi:[0,1]
	v_pk_mul_f32 v[48:49], v[0:1], v[48:49] op_sel_hi:[0,1]
	s_waitcnt lgkmcnt(0)
	v_add_f32_e32 v60, v1, v64
	ds_bpermute_b32 v61, v59, v60
	v_pk_mul_f32 v[46:47], v[0:1], v[46:47] op_sel_hi:[0,1]
	s_waitcnt vmcnt(0)
	v_pk_mul_f32 v[0:1], v[8:9], v[2:3]
	v_pk_mul_f32 v[2:3], v[10:11], v[50:51]
	v_cvt_pk_bf16_f32 v0, v0, v1
	s_waitcnt lgkmcnt(0)
	v_add_f32_e32 v1, v60, v61
	v_fmamk_f32 v1, v1, 0x3b000000, v204
	v_mul_f32_e32 v50, 0x4f800000, v1
	v_cmp_gt_f32_e32 vcc, s48, v1
	global_load_dwordx4 v[38:41], v[28:29], off
	v_pk_mul_f32 v[46:47], v[14:15], v[46:47]
	v_cndmask_b32_e32 v50, v1, v50, vcc
	v_sqrt_f32_e32 v51, v50
	v_cvt_pk_bf16_f32 v1, v2, v3
	v_pk_mul_f32 v[2:3], v[12:13], v[48:49]
	s_nop 0
	v_cvt_pk_bf16_f32 v2, v2, v3
	v_add_u32_e32 v3, -1, v51
	v_fma_f32 v48, -v3, v51, v50
	v_cmp_ge_f32_e64 s[42:43], 0, v48
	v_add_u32_e32 v48, 1, v51
	v_fma_f32 v49, -v48, v51, v50
	v_cndmask_b32_e64 v3, v51, v3, s[42:43]
	v_cmp_lt_f32_e64 s[42:43], 0, v49
	s_nop 1
	v_cndmask_b32_e64 v3, v3, v48, s[42:43]
	v_mul_f32_e32 v48, 0x37800000, v3
	v_cndmask_b32_e32 v3, v3, v48, vcc
	v_cmp_class_f32_e32 vcc, v50, v205
	s_nop 1
	v_cndmask_b32_e32 v60, v3, v50, vcc
	v_div_scale_f32 v61, s[10:11], v60, v60, 1.0
	v_rcp_f32_e32 v64, v61
	v_cvt_pk_bf16_f32 v3, v46, v47
	v_and_b32_e32 v47, 0xffff0000, v35
	v_lshlrev_b32_e32 v46, 16, v35
	v_and_b32_e32 v35, 0xffff0000, v34
	v_lshlrev_b32_e32 v34, 16, v34
	v_pk_mul_f32 v[50:51], v[34:35], v[34:35]
	flat_store_dwordx4 v[32:33], v[0:3]
	v_pk_mul_f32 v[48:49], v[46:47], v[46:47]
	v_add_f32_e32 v50, v50, v51
	v_fma_f32 v0, -v61, v64, 1.0
	v_fmac_f32_e32 v64, v0, v64
	v_div_scale_f32 v65, vcc, 1.0, v60, 1.0
	v_and_b32_e32 v33, 0xffff0000, v37
	v_lshlrev_b32_e32 v32, 16, v37
	v_and_b32_e32 v37, 0xffff0000, v36
	v_lshlrev_b32_e32 v36, 16, v36
	v_add_f32_e32 v48, v50, v48
	v_mul_f32_e32 v66, v65, v64
	v_pk_mul_f32 v[2:3], v[36:37], v[36:37]
	v_add_f32_e32 v48, v48, v49
	v_fma_f32 v0, -v61, v66, v65
	v_add_f32_e32 v2, v48, v2
	v_fmac_f32_e32 v66, v0, v64
	v_pk_mul_f32 v[0:1], v[32:33], v[32:33]
	v_add_f32_e32 v2, v2, v3
	v_add_f32_e32 v0, v2, v0
	v_add_f32_e32 v1, v0, v1
	ds_bpermute_b32 v2, v54, v1
	v_fma_f32 v0, -v61, v66, v65
	v_div_fmas_f32 v0, v0, v64, v66
	v_div_fixup_f32 v0, v0, v60, 1.0
	s_waitcnt lgkmcnt(0)
	v_add_f32_e32 v1, v1, v2
	ds_bpermute_b32 v50, v55, v1
	v_pk_mul_f32 v[2:3], v[0:1], v[62:63] op_sel_hi:[0,1]
	v_pk_mul_f32 v[48:49], v[0:1], v[52:53] op_sel_hi:[0,1]
	v_pk_mul_f32 v[44:45], v[0:1], v[44:45] op_sel_hi:[0,1]
	v_pk_mul_f32 v[42:43], v[0:1], v[42:43] op_sel_hi:[0,1]
	s_waitcnt lgkmcnt(0)
	v_add_f32_e32 v50, v1, v50
	ds_bpermute_b32 v51, v56, v50
	v_pk_mul_f32 v[0:1], v[8:9], v[2:3]
	v_pk_mul_f32 v[2:3], v[10:11], v[48:49]
	v_cvt_pk_bf16_f32 v0, v0, v1
	v_cvt_pk_bf16_f32 v1, v2, v3
	s_waitcnt lgkmcnt(0)
	v_add_f32_e32 v10, v50, v51
	ds_bpermute_b32 v11, v57, v10
	v_pk_mul_f32 v[2:3], v[12:13], v[44:45]
	v_pk_mul_f32 v[8:9], v[14:15], v[42:43]
	v_cvt_pk_bf16_f32 v2, v2, v3
	v_cvt_pk_bf16_f32 v3, v8, v9
	flat_store_dwordx4 v[30:31], v[0:3]
	s_waitcnt lgkmcnt(0)
	v_add_f32_e32 v12, v10, v11
	global_load_dwordx4 v[8:11], v[18:19], off
	ds_bpermute_b32 v13, v58, v12
	s_waitcnt lgkmcnt(0)
	v_add_f32_e32 v0, v12, v13
	global_load_dwordx4 v[12:15], v[18:19], off offset:16
	ds_bpermute_b32 v1, v59, v0
	s_waitcnt lgkmcnt(0)
	v_add_f32_e32 v0, v0, v1
	v_fmamk_f32 v0, v0, 0x3b000000, v204
	v_mul_f32_e32 v1, 0x4f800000, v0
	v_cmp_gt_f32_e32 vcc, s48, v0
	s_nop 1
	v_cndmask_b32_e32 v60, v0, v1, vcc
	v_sqrt_f32_e32 v30, v60
	global_load_dwordx4 v[0:3], v[22:23], off
	s_waitcnt vmcnt(0)
	v_and_b32_e32 v49, 0xffff0000, v39
	v_lshlrev_b32_e32 v48, 16, v39
	v_add_u32_e32 v31, -1, v30
	v_fma_f32 v42, -v31, v30, v60
	v_cmp_ge_f32_e64 s[42:43], 0, v42
	v_add_u32_e32 v42, 1, v30
	v_and_b32_e32 v39, 0xffff0000, v38
	v_lshlrev_b32_e32 v38, 16, v38
	v_cndmask_b32_e64 v31, v30, v31, s[42:43]
	v_fma_f32 v30, -v42, v30, v60
	v_pk_mul_f32 v[52:53], v[38:39], v[38:39]
	v_cmp_lt_f32_e64 s[42:43], 0, v30
	v_pk_mul_f32 v[50:51], v[48:49], v[48:49]
	v_add_f32_e32 v52, v52, v53
	v_cndmask_b32_e64 v30, v31, v42, s[42:43]
	v_and_b32_e32 v43, 0xffff0000, v41
	v_lshlrev_b32_e32 v42, 16, v41
	v_and_b32_e32 v41, 0xffff0000, v40
	v_lshlrev_b32_e32 v40, 16, v40
	v_add_f32_e32 v50, v52, v50
	v_pk_mul_f32 v[44:45], v[40:41], v[40:41]
	v_add_f32_e32 v50, v50, v51
	v_mul_f32_e32 v31, 0x37800000, v30
	v_add_f32_e32 v44, v50, v44
	v_cndmask_b32_e32 v61, v30, v31, vcc
	v_pk_mul_f32 v[30:31], v[42:43], v[42:43]
	v_add_f32_e32 v44, v44, v45
	v_add_f32_e32 v30, v44, v30
	v_add_f32_e32 v30, v30, v31
	ds_bpermute_b32 v31, v54, v30
	v_cmp_class_f32_e32 vcc, v60, v205
	s_waitcnt lgkmcnt(0)
	v_add_f32_e32 v30, v30, v31
	ds_bpermute_b32 v31, v55, v30
	v_cndmask_b32_e32 v44, v61, v60, vcc
	v_div_scale_f32 v45, s[10:11], v44, v44, 1.0
	v_rcp_f32_e32 v50, v45
	s_waitcnt lgkmcnt(0)
	v_add_f32_e32 v30, v30, v31
	ds_bpermute_b32 v31, v56, v30
	v_fma_f32 v51, -v45, v50, 1.0
	v_fmac_f32_e32 v50, v51, v50
	v_div_scale_f32 v51, vcc, 1.0, v44, 1.0
	s_waitcnt lgkmcnt(0)
	v_add_f32_e32 v30, v30, v31
	ds_bpermute_b32 v31, v57, v30
	v_mul_f32_e32 v52, v51, v50
	v_fma_f32 v53, -v45, v52, v51
	v_fmac_f32_e32 v52, v53, v50
	v_fma_f32 v45, -v45, v52, v51
	s_waitcnt lgkmcnt(0)
	v_add_f32_e32 v31, v30, v31
	v_div_fmas_f32 v45, v45, v50, v52
	ds_bpermute_b32 v50, v58, v31
	v_div_fixup_f32 v30, v45, v44, 1.0
	v_pk_mul_f32 v[34:35], v[30:31], v[34:35] op_sel_hi:[0,1]
	v_pk_mul_f32 v[44:45], v[30:31], v[46:47] op_sel_hi:[0,1]
	v_pk_mul_f32 v[36:37], v[30:31], v[36:37] op_sel_hi:[0,1]
	s_waitcnt lgkmcnt(0)
	v_add_f32_e32 v50, v31, v50
	ds_bpermute_b32 v51, v59, v50
	v_pk_mul_f32 v[46:47], v[30:31], v[32:33] op_sel_hi:[0,1]
	v_pk_mul_f32 v[30:31], v[8:9], v[34:35]
	v_pk_mul_f32 v[32:33], v[10:11], v[44:45]
	v_cvt_pk_bf16_f32 v30, v30, v31
	s_waitcnt lgkmcnt(0)
	v_add_f32_e32 v31, v50, v51
	v_fmamk_f32 v31, v31, 0x3b000000, v204
	v_mul_f32_e32 v34, 0x4f800000, v31
	v_cmp_gt_f32_e32 vcc, s48, v31
	v_and_b32_e32 v45, 0xffff0000, v4
	v_lshlrev_b32_e32 v44, 16, v4
	v_cndmask_b32_e32 v34, v31, v34, vcc
	v_sqrt_f32_e32 v35, v34
	v_cvt_pk_bf16_f32 v31, v32, v33
	v_pk_mul_f32 v[32:33], v[12:13], v[36:37]
	s_nop 0
	v_cvt_pk_bf16_f32 v32, v32, v33
	v_add_u32_e32 v33, -1, v35
	v_fma_f32 v36, -v33, v35, v34
	v_cmp_ge_f32_e64 s[42:43], 0, v36
	v_add_u32_e32 v36, 1, v35
	s_nop 0
	v_cndmask_b32_e64 v33, v35, v33, s[42:43]
	v_fma_f32 v35, -v36, v35, v34
	v_cmp_lt_f32_e64 s[42:43], 0, v35
	s_nop 1
	v_cndmask_b32_e64 v33, v33, v36, s[42:43]
	v_mul_f32_e32 v35, 0x37800000, v33
	v_cndmask_b32_e32 v33, v33, v35, vcc
	v_cmp_class_f32_e32 vcc, v34, v205
	s_nop 1
	v_cndmask_b32_e32 v50, v33, v34, vcc
	v_div_scale_f32 v51, s[10:11], v50, v50, 1.0
	v_rcp_f32_e32 v52, v51
	v_pk_mul_f32 v[34:35], v[14:15], v[46:47]
	v_div_scale_f32 v46, vcc, 1.0, v50, 1.0
	v_cvt_pk_bf16_f32 v33, v34, v35
	flat_store_dwordx4 v[26:27], v[30:33]
	v_fma_f32 v26, -v51, v52, 1.0
	v_fmac_f32_e32 v52, v26, v52
	v_and_b32_e32 v35, 0xffff0000, v5
	v_lshlrev_b32_e32 v34, 16, v5
	v_pk_mul_f32 v[4:5], v[44:45], v[44:45]
	v_mul_f32_e32 v47, v46, v52
	v_pk_mul_f32 v[36:37], v[34:35], v[34:35]
	v_add_f32_e32 v4, v4, v5
	v_fma_f32 v26, -v51, v47, v46
	v_and_b32_e32 v33, 0xffff0000, v6
	v_lshlrev_b32_e32 v32, 16, v6
	v_add_f32_e32 v4, v4, v36
	v_fmac_f32_e32 v47, v26, v52
	v_and_b32_e32 v27, 0xffff0000, v7
	v_lshlrev_b32_e32 v26, 16, v7
	v_pk_mul_f32 v[6:7], v[32:33], v[32:33]
	v_add_f32_e32 v4, v4, v37
	v_add_f32_e32 v4, v4, v6
	v_pk_mul_f32 v[30:31], v[26:27], v[26:27]
	v_add_f32_e32 v4, v4, v7
	v_add_f32_e32 v4, v4, v30
	v_add_f32_e32 v5, v4, v31
	ds_bpermute_b32 v6, v54, v5
	v_fma_f32 v4, -v51, v47, v46
	v_div_fmas_f32 v4, v4, v52, v47
	v_div_fixup_f32 v4, v4, v50, 1.0
	s_waitcnt lgkmcnt(0)
	v_add_f32_e32 v5, v5, v6
	ds_bpermute_b32 v46, v55, v5
	v_pk_mul_f32 v[36:37], v[4:5], v[40:41] op_sel_hi:[0,1]
	v_pk_mul_f32 v[6:7], v[4:5], v[38:39] op_sel_hi:[0,1]
	v_pk_mul_f32 v[30:31], v[4:5], v[48:49] op_sel_hi:[0,1]
	v_pk_mul_f32 v[38:39], v[4:5], v[42:43] op_sel_hi:[0,1]
	s_waitcnt lgkmcnt(0)
	v_add_f32_e32 v40, v5, v46
	ds_bpermute_b32 v41, v56, v40
	v_pk_mul_f32 v[4:5], v[8:9], v[6:7]
	v_pk_mul_f32 v[6:7], v[10:11], v[30:31]
	v_cvt_pk_bf16_f32 v4, v4, v5
	v_cvt_pk_bf16_f32 v5, v6, v7
	s_waitcnt lgkmcnt(0)
	v_add_f32_e32 v10, v40, v41
	ds_bpermute_b32 v11, v57, v10
	v_pk_mul_f32 v[6:7], v[12:13], v[36:37]
	v_pk_mul_f32 v[8:9], v[14:15], v[38:39]
	v_cvt_pk_bf16_f32 v6, v6, v7
	v_cvt_pk_bf16_f32 v7, v8, v9
	flat_store_dwordx4 v[28:29], v[4:7]
	global_load_dwordx4 v[4:7], v[20:21], off
	s_waitcnt lgkmcnt(0)
	v_add_f32_e32 v8, v10, v11
	ds_bpermute_b32 v9, v58, v8
	v_and_b32_e32 v39, 0xffff0000, v0
	v_lshlrev_b32_e32 v38, 16, v0
	v_and_b32_e32 v31, 0xffff0000, v1
	v_lshlrev_b32_e32 v30, 16, v1
	s_waitcnt lgkmcnt(0)
	v_add_f32_e32 v12, v8, v9
	global_load_dwordx4 v[8:11], v[20:21], off offset:16
	ds_bpermute_b32 v13, v59, v12
	v_pk_mul_f32 v[0:1], v[38:39], v[38:39]
	v_pk_mul_f32 v[36:37], v[30:31], v[30:31]
	v_add_f32_e32 v0, v0, v1
	v_and_b32_e32 v29, 0xffff0000, v2
	s_waitcnt lgkmcnt(0)
	v_add_f32_e32 v12, v12, v13
	v_fmamk_f32 v12, v12, 0x3b000000, v204
	v_mul_f32_e32 v13, 0x4f800000, v12
	v_cmp_gt_f32_e32 vcc, s48, v12
	v_lshlrev_b32_e32 v28, 16, v2
	v_add_f32_e32 v0, v0, v36
	v_cndmask_b32_e32 v40, v12, v13, vcc
	v_sqrt_f32_e32 v12, v40
	v_add_f32_e32 v0, v0, v37
	v_add_u32_e32 v13, -1, v12
	v_fma_f32 v14, -v13, v12, v40
	v_cmp_ge_f32_e64 s[42:43], 0, v14
	v_add_u32_e32 v14, 1, v12
	s_nop 0
	v_cndmask_b32_e64 v13, v12, v13, s[42:43]
	v_fma_f32 v12, -v14, v12, v40
	v_cmp_lt_f32_e64 s[42:43], 0, v12
	s_nop 1
	v_cndmask_b32_e64 v12, v13, v14, s[42:43]
	v_mul_f32_e32 v13, 0x37800000, v12
	v_cndmask_b32_e32 v41, v12, v13, vcc
	v_and_b32_e32 v13, 0xffff0000, v3
	v_lshlrev_b32_e32 v12, 16, v3
	v_pk_mul_f32 v[2:3], v[28:29], v[28:29]
	v_pk_mul_f32 v[14:15], v[12:13], v[12:13]
	v_add_f32_e32 v0, v0, v2
	v_add_f32_e32 v0, v0, v3
	v_add_f32_e32 v0, v0, v14
	v_add_f32_e32 v0, v0, v15
	ds_bpermute_b32 v1, v54, v0
	v_cmp_class_f32_e32 vcc, v40, v205
	s_waitcnt lgkmcnt(0)
	v_add_f32_e32 v0, v0, v1
	ds_bpermute_b32 v1, v55, v0
	v_cndmask_b32_e32 v2, v41, v40, vcc
	v_div_scale_f32 v3, s[10:11], v2, v2, 1.0
	v_rcp_f32_e32 v14, v3
	s_waitcnt lgkmcnt(0)
	v_add_f32_e32 v0, v0, v1
	ds_bpermute_b32 v1, v56, v0
	v_fma_f32 v15, -v3, v14, 1.0
	v_fmac_f32_e32 v14, v15, v14
	v_div_scale_f32 v15, vcc, 1.0, v2, 1.0
	s_waitcnt lgkmcnt(0)
	v_add_f32_e32 v0, v0, v1
	ds_bpermute_b32 v1, v57, v0
	v_mul_f32_e32 v36, v15, v14
	v_fma_f32 v37, -v3, v36, v15
	v_fmac_f32_e32 v36, v37, v14
	v_fma_f32 v3, -v3, v36, v15
	s_waitcnt lgkmcnt(0)
	v_add_f32_e32 v1, v0, v1
	v_div_fmas_f32 v3, v3, v14, v36
	ds_bpermute_b32 v36, v58, v1
	v_div_fixup_f32 v0, v3, v2, 1.0
	v_pk_mul_f32 v[14:15], v[0:1], v[34:35] op_sel_hi:[0,1]
	v_pk_mul_f32 v[2:3], v[0:1], v[44:45] op_sel_hi:[0,1]
	v_pk_mul_f32 v[32:33], v[0:1], v[32:33] op_sel_hi:[0,1]
	s_waitcnt lgkmcnt(0)
	v_add_f32_e32 v34, v1, v36
	ds_bpermute_b32 v35, v59, v34
	v_pk_mul_f32 v[26:27], v[0:1], v[26:27] op_sel_hi:[0,1]
	s_waitcnt vmcnt(0)
	v_pk_mul_f32 v[0:1], v[4:5], v[2:3]
	v_pk_mul_f32 v[2:3], v[6:7], v[14:15]
	v_cvt_pk_bf16_f32 v0, v0, v1
	s_waitcnt lgkmcnt(0)
	v_add_f32_e32 v1, v34, v35
	v_fmamk_f32 v1, v1, 0x3b000000, v204
	v_mul_f32_e32 v14, 0x4f800000, v1
	v_cmp_gt_f32_e32 vcc, s48, v1
	s_nop 1
	v_cndmask_b32_e32 v14, v1, v14, vcc
	v_sqrt_f32_e32 v15, v14
	v_cvt_pk_bf16_f32 v1, v2, v3
	v_pk_mul_f32 v[2:3], v[8:9], v[32:33]
	s_nop 0
	v_cvt_pk_bf16_f32 v2, v2, v3
	v_add_u32_e32 v3, -1, v15
	v_fma_f32 v32, -v3, v15, v14
	v_cmp_ge_f32_e64 s[42:43], 0, v32
	v_add_u32_e32 v32, 1, v15
	s_nop 0
	v_cndmask_b32_e64 v3, v15, v3, s[42:43]
	v_fma_f32 v15, -v32, v15, v14
	v_cmp_lt_f32_e64 s[42:43], 0, v15
	s_nop 1
	v_cndmask_b32_e64 v3, v3, v32, s[42:43]
	v_mul_f32_e32 v15, 0x37800000, v3
	v_cndmask_b32_e32 v3, v3, v15, vcc
	v_cmp_class_f32_e32 vcc, v14, v205
	s_nop 1
	v_cndmask_b32_e32 v32, v3, v14, vcc
	v_div_scale_f32 v33, s[10:11], v32, v32, 1.0
	v_rcp_f32_e32 v34, v33
	v_pk_mul_f32 v[14:15], v[10:11], v[26:27]
	s_nop 0
	v_cvt_pk_bf16_f32 v3, v14, v15
	flat_store_dwordx4 v[24:25], v[0:3]
	s_nop 1
	v_fma_f32 v0, -v33, v34, 1.0
	v_fmac_f32_e32 v34, v0, v34
	v_div_scale_f32 v0, vcc, 1.0, v32, 1.0
	v_mul_f32_e32 v1, v0, v34
	v_fma_f32 v2, -v33, v1, v0
	v_fmac_f32_e32 v1, v2, v34
	v_fma_f32 v0, -v33, v1, v0
	v_div_fmas_f32 v0, v0, v34, v1
	v_div_fixup_f32 v0, v0, v32, 1.0
	v_pk_mul_f32 v[2:3], v[0:1], v[38:39] op_sel_hi:[0,1]
	v_pk_mul_f32 v[14:15], v[0:1], v[30:31] op_sel_hi:[0,1]
	v_pk_mul_f32 v[24:25], v[0:1], v[28:29] op_sel_hi:[0,1]
	v_pk_mul_f32 v[12:13], v[0:1], v[12:13] op_sel_hi:[0,1]
	v_pk_mul_f32 v[0:1], v[4:5], v[2:3]
	v_pk_mul_f32 v[2:3], v[6:7], v[14:15]
	v_cvt_pk_bf16_f32 v0, v0, v1
	v_cvt_pk_bf16_f32 v1, v2, v3
	v_pk_mul_f32 v[2:3], v[8:9], v[24:25]
	v_pk_mul_f32 v[4:5], v[10:11], v[12:13]
	v_cvt_pk_bf16_f32 v2, v2, v3
	v_cvt_pk_bf16_f32 v3, v4, v5
	flat_store_dwordx4 v[22:23], v[0:3]
	v_lshl_add_u64 v[22:23], v[22:23], 0, s[20:21]
	s_cbranch_scc0 .LBB0_278

.LBB0_299:
	s_bfe_u32 s33, s18, 0x20007
	s_bfe_u32 s41, s19, 0x30002
	v_lshl_add_u32 v0, s33, 7, v135
	s_lshl_b32 s6, s41, 9
	v_ashrrev_i32_e32 v1, 31, v0
	s_add_u32 s20, s90, s6
	v_lshlrev_b64 v[0:1], 12, v[0:1]
	s_addc_u32 s21, s91, 0
	v_lshl_add_u64 v[144:145], s[20:21], 0, v[0:1]
	s_lshl_b32 s20, s41, 19
	s_lshl_b32 s21, s33, 8
	s_or_b32 s20, s20, s21
	s_mov_b32 s21, s7
	v_lshl_add_u64 v[146:147], v[138:139], 0, s[20:21]
	s_lshl_b32 s20, s19, 3
	s_and_b32 s20, s20, 0xffffff00
	v_add_u32_e32 v0, s20, v131
	v_ashrrev_i32_e32 v1, 31, v0
	s_lshl_b32 s20, s41, 20
	v_lshlrev_b64 v[0:1], 9, v[0:1]
	v_lshl_add_u64 v[142:143], v[0:1], 0, s[20:21]
	s_lshl_b32 s20, s19, 7
	s_and_b32 s20, s20, 0x180
	v_lshl_add_u64 v[0:1], v[142:143], 1, s[0:1]
	s_lshl_b32 s38, s20, 1
	s_mov_b32 s39, s7
	v_lshl_add_u64 v[0:1], v[0:1], 0, s[38:39]
	v_lshlrev_b32_e32 v176, 1, v130
	v_lshl_add_u64 v[0:1], v[0:1], 0, v[176:177]
	s_lshl_b32 s42, s41, 8
	s_mov_b32 s43, s7
	v_add_u32_e32 v2, s20, v135
	s_waitcnt vmcnt(0)
	global_load_dwordx4 v[80:83], v[0:1], off
	global_load_dwordx4 v[84:87], v[0:1], off offset:32
	global_load_dwordx4 v[88:91], v[0:1], off offset:64
	global_load_dwordx4 v[92:95], v[0:1], off offset:96
	global_load_dwordx4 v[96:99], v[0:1], off offset:128
	global_load_dwordx4 v[100:103], v[0:1], off offset:160
	global_load_dwordx4 v[104:107], v[0:1], off offset:192
	global_load_dwordx4 v[108:111], v[0:1], off offset:224
	v_lshl_add_u64 v[0:1], s[42:43], 0, v[132:133]
	v_ashrrev_i32_e32 v3, 31, v2
	v_lshlrev_b64 v[0:1], 11, v[0:1]
	v_lshlrev_b64 v[2:3], 12, v[2:3]
	v_lshl_add_u64 v[0:1], s[14:15], 0, v[0:1]
	v_lshl_add_u64 v[2:3], s[16:17], 0, v[2:3]
	v_lshl_add_u64 v[0:1], v[0:1], 0, s[38:39]
	v_lshlrev_b32_e32 v176, 1, v134
	v_lshl_add_u64 v[2:3], v[2:3], 0, s[6:7]
	v_lshl_add_u64 v[0:1], v[0:1], 0, v[176:177]
	v_lshl_add_u64 v[2:3], v[2:3], 0, v[176:177]
	s_mov_b32 s6, 0x40000
	global_load_dwordx4 v[112:115], v[0:1], off
	global_load_dwordx4 v[116:119], v[0:1], off offset:128
	global_load_dwordx4 v[120:123], v[2:3], off
	v_add_co_u32_e32 v0, vcc, s6, v2
	v_mov_b32_e32 v14, v177
	s_nop 0
	v_addc_co_u32_e32 v1, vcc, 0, v3, vcc
	global_load_dwordx4 v[124:127], v[0:1], off
	v_mov_b32_e32 v15, v177
	v_mov_b32_e32 v0, v177
	v_mov_b32_e32 v1, v177
	v_mov_b32_e32 v2, v177
	v_mov_b32_e32 v3, v177
	v_mov_b32_e32 v4, v177
	v_mov_b32_e32 v5, v177
	v_mov_b32_e32 v6, v177
	v_mov_b32_e32 v7, v177
	v_mov_b32_e32 v8, v177
	v_mov_b32_e32 v9, v177
	v_mov_b32_e32 v10, v177
	v_mov_b32_e32 v11, v177
	v_mov_b32_e32 v12, v177
	v_mov_b32_e32 v13, v177
	v_mov_b64_e32 v[30:31], v[14:15]
	v_mov_b64_e32 v[46:47], v[14:15]
	v_mov_b64_e32 v[62:63], v[14:15]
	s_mov_b32 s6, 0
	v_mov_b32_e32 v141, 0
	v_mov_b32_e32 v154, 0xff800000
	v_mov_b64_e32 v[28:29], v[12:13]
	v_mov_b64_e32 v[26:27], v[10:11]
	v_mov_b64_e32 v[24:25], v[8:9]
	v_mov_b64_e32 v[22:23], v[6:7]
	v_mov_b64_e32 v[20:21], v[4:5]
	v_mov_b64_e32 v[18:19], v[2:3]
	v_mov_b64_e32 v[16:17], v[0:1]
	v_mov_b64_e32 v[44:45], v[12:13]
	v_mov_b64_e32 v[42:43], v[10:11]
	v_mov_b64_e32 v[40:41], v[8:9]
	v_mov_b64_e32 v[38:39], v[6:7]
	v_mov_b64_e32 v[36:37], v[4:5]
	v_mov_b64_e32 v[34:35], v[2:3]
	v_mov_b64_e32 v[32:33], v[0:1]
	v_mov_b64_e32 v[60:61], v[12:13]
	v_mov_b64_e32 v[58:59], v[10:11]
	v_mov_b64_e32 v[56:57], v[8:9]
	v_mov_b64_e32 v[54:55], v[6:7]
	v_mov_b64_e32 v[52:53], v[4:5]
	v_mov_b64_e32 v[50:51], v[2:3]
	v_mov_b64_e32 v[48:49], v[0:1]
	s_branch .LBB0_301

.LBB0_301:
	s_bitcmp1_b32 s6, 0
	s_cselect_b32 s21, 0x8800, 0
	s_add_i32 s21, s21, 0
	s_waitcnt lgkmcnt(0)
	v_add3_u32 v64, s21, v149, v176
	s_waitcnt vmcnt(0) lgkmcnt(0)
	ds_write_b128 v64, v[112:115]
	ds_write_b128 v64, v[116:119] offset:128
	v_add3_u32 v64, s21, v151, v176
	v_add_u32_e32 v65, 0x4400, v64
	v_add_u32_e32 v64, 0x6600, v64
	s_cmp_eq_u32 s6, 3
	ds_write2_b64 v65, v[120:121], v[122:123] offset1:1
	ds_write2_b64 v64, v[124:125], v[126:127] offset1:1
	s_waitcnt lgkmcnt(0)
	s_barrier
	s_cbranch_scc1 .LBB0_303
	v_lshl_add_u64 v[64:65], v[146:147], 0, v[136:137]
	v_add_co_u32_e32 v64, vcc, 0x1de20000, v64
	v_lshl_add_u64 v[66:67], v[144:145], 0, v[136:137]
	s_nop 0
	v_addc_co_u32_e32 v65, vcc, 0, v65, vcc
	global_load_dwordx4 v[112:115], v[64:65], off
	global_load_dwordx4 v[116:119], v[64:65], off offset:128
	v_add_co_u32_e32 v64, vcc, 0x1e200000, v66
	s_nop 1
	v_addc_co_u32_e32 v65, vcc, 0, v67, vcc
	v_add_co_u32_e32 v66, vcc, 0x1e240000, v66
	s_nop 1
	v_addc_co_u32_e32 v67, vcc, 0, v67, vcc
	global_load_dwordx4 v[120:123], v[64:65], off offset:128
	global_load_dwordx4 v[124:127], v[66:67], off offset:128

.LBB0_316:
	v_lshl_add_u64 v[16:17], s[12:13], 0, v[66:67]
	v_add_co_u32_e32 v0, vcc, 0xf8000000, v16
	s_and_b64 s[14:15], s[8:9], exec
	s_nop 0
	v_addc_co_u32_e32 v1, vcc, -1, v17, vcc
	v_add_co_u32_e32 v4, vcc, 0xf8000400, v16
	global_load_dwordx4 v[0:3], v[0:1], off
	s_nop 0
	v_addc_co_u32_e32 v5, vcc, -1, v17, vcc
	global_load_dwordx4 v[68:71], v[4:5], off
	v_add_co_u32_e32 v4, vcc, 0xf8000800, v16
	s_cselect_b32 s15, s18, 0
	s_nop 0
	v_addc_co_u32_e32 v5, vcc, -1, v17, vcc
	global_load_dwordx4 v[72:75], v[4:5], off
	v_add_co_u32_e32 v4, vcc, 0xf8000c00, v16
	s_cselect_b32 s14, s6, 0
	s_nop 0
	v_addc_co_u32_e32 v5, vcc, -1, v17, vcc
	global_load_dwordx4 v[76:79], v[4:5], off
	v_add_co_u32_e32 v4, vcc, 0xf9000000, v16
	v_lshlrev_b32_e32 v176, 2, v52
	s_nop 0
	v_addc_co_u32_e32 v5, vcc, -1, v17, vcc
	global_load_dwordx4 v[36:39], v[4:5], off
	v_add_co_u32_e32 v4, vcc, 0xf9000400, v16
	s_cmp_lg_u64 s[14:15], 0
	s_nop 0
	v_addc_co_u32_e32 v5, vcc, -1, v17, vcc
	global_load_dwordx4 v[40:43], v[4:5], off
	v_add_co_u32_e32 v4, vcc, 0xf9000800, v16
	s_cselect_b64 s[16:17], -1, 0
	s_nop 0
	v_addc_co_u32_e32 v5, vcc, -1, v17, vcc
	global_load_dwordx4 v[44:47], v[4:5], off
	v_add_co_u32_e32 v4, vcc, 0xf9000c00, v16
	s_cmp_eq_u64 s[14:15], 0
	s_nop 0
	v_addc_co_u32_e32 v5, vcc, -1, v17, vcc
	global_load_dwordx4 v[48:51], v[4:5], off
	v_add_co_u32_e32 v4, vcc, 0xfa000000, v16
	s_waitcnt vmcnt(0) lgkmcnt(0)
	v_and_b32_e32 v107, 0xffff0000, v71
	v_lshlrev_b32_e32 v106, 16, v71
	v_and_b32_e32 v111, 0xffff0000, v70
	v_lshlrev_b32_e32 v110, 16, v70
	v_and_b32_e32 v113, 0xffff0000, v69
	v_lshlrev_b32_e32 v112, 16, v69
	v_and_b32_e32 v103, 0xffff0000, v73
	v_lshlrev_b32_e32 v102, 16, v73
	v_and_b32_e32 v105, 0xffff0000, v72
	v_lshlrev_b32_e32 v104, 16, v72
	v_and_b32_e32 v101, 0xffff0000, v74
	v_lshlrev_b32_e32 v100, 16, v74
	v_and_b32_e32 v131, 0xffff0000, v68
	v_lshlrev_b32_e32 v130, 16, v68
	v_addc_co_u32_e32 v5, vcc, -1, v17, vcc
	v_and_b32_e32 v91, 0xffff0000, v79
	v_lshlrev_b32_e32 v90, 16, v79
	v_and_b32_e32 v73, 0xffff0000, v37
	v_lshlrev_b32_e32 v72, 16, v37
	v_and_b32_e32 v37, 0xffff0000, v36
	v_lshlrev_b32_e32 v36, 16, v36
	v_add_f32_e32 v74, 0, v36
	v_add_f32_e32 v74, v74, v37
	v_add_f32_e32 v74, v74, v72
	v_and_b32_e32 v71, 0xffff0000, v39
	v_lshlrev_b32_e32 v70, 16, v39
	v_and_b32_e32 v39, 0xffff0000, v38
	v_lshlrev_b32_e32 v38, 16, v38
	v_add_f32_e32 v74, v74, v73
	v_add_f32_e32 v74, v74, v38
	v_add_f32_e32 v74, v74, v39
	v_add_f32_e32 v74, v74, v70
	v_and_b32_e32 v69, 0xffff0000, v41
	v_lshlrev_b32_e32 v68, 16, v41
	v_and_b32_e32 v41, 0xffff0000, v40
	v_lshlrev_b32_e32 v40, 16, v40
	v_add_f32_e32 v74, v74, v71
	v_add_f32_e32 v74, v74, v40
	v_add_f32_e32 v74, v74, v41
	v_add_f32_e32 v74, v74, v68
	v_and_b32_e32 v93, 0xffff0000, v78
	v_lshlrev_b32_e32 v92, 16, v78
	v_and_b32_e32 v79, 0xffff0000, v49
	v_lshlrev_b32_e32 v78, 16, v49
	v_and_b32_e32 v83, 0xffff0000, v48
	v_lshlrev_b32_e32 v82, 16, v48
	v_and_b32_e32 v49, 0xffff0000, v47
	v_lshlrev_b32_e32 v48, 16, v47
	v_and_b32_e32 v85, 0xffff0000, v46
	v_lshlrev_b32_e32 v84, 16, v46
	v_and_b32_e32 v47, 0xffff0000, v43
	v_lshlrev_b32_e32 v46, 16, v43
	v_and_b32_e32 v43, 0xffff0000, v42
	v_lshlrev_b32_e32 v42, 16, v42
	v_add_f32_e32 v74, v74, v69
	global_load_dwordx4 v[20:23], v[4:5], off
	v_add_f32_e32 v74, v74, v42
	v_add_f32_e32 v74, v74, v43
	v_add_f32_e32 v74, v74, v46
	v_and_b32_e32 v95, 0xffff0000, v77
	v_lshlrev_b32_e32 v94, 16, v77
	v_and_b32_e32 v97, 0xffff0000, v76
	v_lshlrev_b32_e32 v96, 16, v76
	v_and_b32_e32 v77, 0xffff0000, v51
	v_lshlrev_b32_e32 v76, 16, v51
	v_and_b32_e32 v81, 0xffff0000, v50
	v_lshlrev_b32_e32 v80, 16, v50
	v_and_b32_e32 v51, 0xffff0000, v45
	v_lshlrev_b32_e32 v50, 16, v45
	v_and_b32_e32 v45, 0xffff0000, v44
	v_lshlrev_b32_e32 v44, 16, v44
	v_add_f32_e32 v74, v74, v47
	v_add_f32_e32 v74, v74, v44
	v_add_f32_e32 v74, v74, v45
	v_add_co_u32_e32 v4, vcc, 0xfa000400, v16
	v_add_f32_e32 v74, v74, v50
	s_nop 0
	v_addc_co_u32_e32 v5, vcc, -1, v17, vcc
	v_add_f32_e32 v74, v74, v51
	global_load_dwordx4 v[24:27], v[4:5], off
	v_add_co_u32_e32 v4, vcc, 0xfa000800, v16
	v_add_f32_e32 v74, v74, v84
	s_nop 0
	v_addc_co_u32_e32 v5, vcc, -1, v17, vcc
	v_add_f32_e32 v74, v74, v85
	global_load_dwordx4 v[28:31], v[4:5], off
	v_add_co_u32_e32 v4, vcc, 0xfa000c00, v16
	v_add_f32_e32 v74, v74, v48
	s_nop 0
	v_addc_co_u32_e32 v5, vcc, -1, v17, vcc
	v_add_f32_e32 v74, v74, v49
	global_load_dwordx4 v[32:35], v[4:5], off
	v_add_f32_e32 v74, v74, v82
	v_add_f32_e32 v74, v74, v83
	v_add_f32_e32 v74, v74, v78
	v_add_f32_e32 v74, v74, v79
	v_add_f32_e32 v74, v74, v80
	v_add_f32_e32 v74, v74, v81
	v_add_f32_e32 v74, v74, v76
	v_add_f32_e32 v74, v74, v77
	v_and_b32_e32 v99, 0xffff0000, v75
	v_lshlrev_b32_e32 v98, 16, v75
	ds_bpermute_b32 v75, v53, v74
	v_add_co_u32_e32 v4, vcc, 0xfb000000, v16
	s_waitcnt lgkmcnt(0)
	v_add_f32_e32 v74, v74, v75
	ds_bpermute_b32 v75, v171, v74
	v_addc_co_u32_e32 v5, vcc, -1, v17, vcc
	global_load_dwordx4 v[4:7], v[4:5], off
	v_add_co_u32_e32 v8, vcc, 0xfb000400, v16
	s_waitcnt lgkmcnt(0)
	v_add_f32_e32 v74, v74, v75
	ds_bpermute_b32 v75, v172, v74
	v_addc_co_u32_e32 v9, vcc, -1, v17, vcc
	global_load_dwordx4 v[8:11], v[8:9], off
	v_add_co_u32_e32 v12, vcc, 0xfb000800, v16
	s_waitcnt lgkmcnt(0)
	v_add_f32_e32 v74, v74, v75
	ds_bpermute_b32 v75, v173, v74
	v_addc_co_u32_e32 v13, vcc, -1, v17, vcc
	global_load_dwordx4 v[12:15], v[12:13], off
	v_add_co_u32_e32 v16, vcc, 0xfb000c00, v16
	s_waitcnt lgkmcnt(0)
	v_add_f32_e32 v74, v74, v75
	ds_bpermute_b32 v75, v174, v74
	v_addc_co_u32_e32 v17, vcc, -1, v17, vcc
	global_load_dwordx4 v[16:19], v[16:17], off
	s_waitcnt lgkmcnt(0)
	v_add_f32_e32 v74, v74, v75
	ds_bpermute_b32 v75, v175, v74
	s_waitcnt lgkmcnt(0)
	v_add_f32_e32 v74, v74, v75
	v_mul_f32_e32 v86, 0x3a000000, v74
	v_pk_add_f32 v[114:115], v[36:37], v[86:87] op_sel_hi:[1,0] neg_lo:[0,1] neg_hi:[0,1]
	v_pk_add_f32 v[108:109], v[72:73], v[86:87] op_sel_hi:[1,0] neg_lo:[0,1] neg_hi:[0,1]
	v_pk_mul_f32 v[88:89], v[114:115], v[114:115]
	v_pk_mul_f32 v[118:119], v[108:109], v[108:109]
	v_pk_add_f32 v[120:121], v[38:39], v[86:87] op_sel_hi:[1,0] neg_lo:[0,1] neg_hi:[0,1]
	v_pk_add_f32 v[116:117], v[70:71], v[86:87] op_sel_hi:[1,0] neg_lo:[0,1] neg_hi:[0,1]
	v_pk_add_f32 v[70:71], v[40:41], v[86:87] op_sel_hi:[1,0] neg_lo:[0,1] neg_hi:[0,1]
	v_pk_add_f32 v[68:69], v[68:69], v[86:87] op_sel_hi:[1,0] neg_lo:[0,1] neg_hi:[0,1]
	v_pk_add_f32 v[74:75], v[42:43], v[86:87] op_sel_hi:[1,0] neg_lo:[0,1] neg_hi:[0,1]
	v_pk_add_f32 v[72:73], v[46:47], v[86:87] op_sel_hi:[1,0] neg_lo:[0,1] neg_hi:[0,1]
	v_pk_add_f32 v[46:47], v[44:45], v[86:87] op_sel_hi:[1,0] neg_lo:[0,1] neg_hi:[0,1]
	v_pk_add_f32 v[44:45], v[50:51], v[86:87] op_sel_hi:[1,0] neg_lo:[0,1] neg_hi:[0,1]
	v_pk_add_f32 v[50:51], v[84:85], v[86:87] op_sel_hi:[1,0] neg_lo:[0,1] neg_hi:[0,1]
	v_pk_add_f32 v[48:49], v[48:49], v[86:87] op_sel_hi:[1,0] neg_lo:[0,1] neg_hi:[0,1]
	v_pk_add_f32 v[38:39], v[82:83], v[86:87] op_sel_hi:[1,0] neg_lo:[0,1] neg_hi:[0,1]
	v_pk_add_f32 v[36:37], v[78:79], v[86:87] op_sel_hi:[1,0] neg_lo:[0,1] neg_hi:[0,1]
	v_pk_add_f32 v[42:43], v[80:81], v[86:87] op_sel_hi:[1,0] neg_lo:[0,1] neg_hi:[0,1]
	v_pk_add_f32 v[40:41], v[76:77], v[86:87] op_sel_hi:[1,0] neg_lo:[0,1] neg_hi:[0,1]
	v_add_f32_e32 v86, v88, v89
	v_add_f32_e32 v86, v118, v86
	v_pk_mul_f32 v[122:123], v[120:121], v[120:121]
	v_add_f32_e32 v86, v119, v86
	v_add_f32_e32 v86, v122, v86
	v_pk_mul_f32 v[124:125], v[116:117], v[116:117]
	v_add_f32_e32 v86, v123, v86
	v_add_f32_e32 v86, v124, v86
	v_pk_mul_f32 v[126:127], v[70:71], v[70:71]
	v_add_f32_e32 v86, v125, v86
	v_add_f32_e32 v86, v126, v86
	v_pk_mul_f32 v[132:133], v[68:69], v[68:69]
	v_add_f32_e32 v86, v127, v86
	v_add_f32_e32 v86, v132, v86
	v_pk_mul_f32 v[134:135], v[74:75], v[74:75]
	v_add_f32_e32 v86, v133, v86
	v_add_f32_e32 v86, v134, v86
	v_pk_mul_f32 v[136:137], v[72:73], v[72:73]
	v_add_f32_e32 v86, v135, v86
	v_add_f32_e32 v86, v136, v86
	v_pk_mul_f32 v[138:139], v[46:47], v[46:47]
	v_add_f32_e32 v86, v137, v86
	v_add_f32_e32 v86, v138, v86
	v_pk_mul_f32 v[140:141], v[44:45], v[44:45]
	v_add_f32_e32 v86, v139, v86
	v_add_f32_e32 v86, v140, v86
	v_pk_mul_f32 v[84:85], v[50:51], v[50:51]
	v_add_f32_e32 v86, v141, v86
	v_add_f32_e32 v84, v84, v86
	v_pk_mul_f32 v[142:143], v[48:49], v[48:49]
	v_add_f32_e32 v84, v85, v84
	v_add_f32_e32 v84, v142, v84
	s_waitcnt vmcnt(0)
	v_and_b32_e32 v123, 0xffff0000, v21
	v_lshlrev_b32_e32 v122, 16, v21
	v_and_b32_e32 v21, 0xffff0000, v20
	v_lshlrev_b32_e32 v20, 16, v20
	v_pk_mul_f32 v[82:83], v[38:39], v[38:39]
	v_add_f32_e32 v84, v143, v84
	v_add_f32_e32 v89, 0, v20
	v_add_f32_e32 v82, v82, v84
	v_add_f32_e32 v89, v89, v21
	v_pk_mul_f32 v[78:79], v[36:37], v[36:37]
	v_add_f32_e32 v82, v83, v82
	v_add_f32_e32 v89, v89, v122
	v_add_f32_e32 v78, v78, v82
	v_and_b32_e32 v119, 0xffff0000, v23
	v_lshlrev_b32_e32 v118, 16, v23
	v_and_b32_e32 v23, 0xffff0000, v22
	v_lshlrev_b32_e32 v22, 16, v22
	v_add_f32_e32 v89, v89, v123
	v_pk_mul_f32 v[80:81], v[42:43], v[42:43]
	v_add_f32_e32 v78, v79, v78
	v_add_f32_e32 v89, v89, v22
	v_add_f32_e32 v78, v80, v78
	v_add_f32_e32 v89, v89, v23
	v_pk_mul_f32 v[76:77], v[40:41], v[40:41]
	v_add_f32_e32 v78, v81, v78
	v_add_f32_e32 v89, v89, v118
	v_add_f32_e32 v76, v76, v78
	v_and_b32_e32 v79, 0xffff0000, v25
	v_lshlrev_b32_e32 v78, 16, v25
	v_and_b32_e32 v25, 0xffff0000, v24
	v_lshlrev_b32_e32 v24, 16, v24
	v_add_f32_e32 v89, v89, v119
	v_add_f32_e32 v89, v89, v24
	v_add_f32_e32 v89, v89, v25
	v_add_f32_e32 v89, v89, v78
	v_and_b32_e32 v81, 0xffff0000, v35
	v_lshlrev_b32_e32 v80, 16, v35
	v_and_b32_e32 v85, 0xffff0000, v34
	v_lshlrev_b32_e32 v84, 16, v34
	v_and_b32_e32 v35, 0xffff0000, v27
	v_lshlrev_b32_e32 v34, 16, v27
	v_and_b32_e32 v27, 0xffff0000, v26
	v_lshlrev_b32_e32 v26, 16, v26
	v_add_f32_e32 v89, v89, v79
	v_add_f32_e32 v89, v89, v26
	v_add_f32_e32 v89, v89, v27
	v_add_f32_e32 v89, v89, v34
	v_and_b32_e32 v83, 0xffff0000, v33
	v_lshlrev_b32_e32 v82, 16, v33
	v_and_b32_e32 v87, 0xffff0000, v32
	v_lshlrev_b32_e32 v86, 16, v32
	v_and_b32_e32 v33, 0xffff0000, v29
	v_lshlrev_b32_e32 v32, 16, v29
	v_and_b32_e32 v29, 0xffff0000, v28
	v_lshlrev_b32_e32 v28, 16, v28
	v_add_f32_e32 v89, v89, v35
	v_add_f32_e32 v89, v89, v28
	v_add_f32_e32 v89, v89, v29
	v_add_f32_e32 v89, v89, v32
	v_add_f32_e32 v88, v77, v76
	v_and_b32_e32 v77, 0xffff0000, v31
	v_lshlrev_b32_e32 v76, 16, v31
	v_and_b32_e32 v31, 0xffff0000, v30
	v_lshlrev_b32_e32 v30, 16, v30
	v_add_f32_e32 v89, v89, v33
	v_add_f32_e32 v89, v89, v30
	v_add_f32_e32 v89, v89, v31
	v_add_f32_e32 v89, v89, v76
	v_add_f32_e32 v89, v89, v77
	v_add_f32_e32 v89, v89, v86
	v_add_f32_e32 v89, v89, v87
	v_add_f32_e32 v89, v89, v82
	v_add_f32_e32 v89, v89, v83
	v_add_f32_e32 v89, v89, v84
	v_add_f32_e32 v89, v89, v85
	v_add_f32_e32 v89, v89, v80
	v_add_f32_e32 v89, v89, v81
	ds_bpermute_b32 v124, v53, v89
	s_waitcnt lgkmcnt(0)
	v_add_f32_e32 v89, v89, v124
	ds_bpermute_b32 v124, v171, v89
	s_waitcnt lgkmcnt(0)
	v_add_f32_e32 v89, v89, v124
	ds_bpermute_b32 v124, v172, v89
	s_waitcnt lgkmcnt(0)
	v_add_f32_e32 v89, v89, v124
	ds_bpermute_b32 v124, v173, v89
	s_waitcnt lgkmcnt(0)
	v_add_f32_e32 v89, v89, v124
	ds_bpermute_b32 v124, v174, v89
	s_waitcnt lgkmcnt(0)
	v_add_f32_e32 v89, v89, v124
	ds_bpermute_b32 v124, v175, v89
	s_waitcnt lgkmcnt(0)
	v_add_f32_e32 v89, v89, v124
	v_mul_f32_e32 v132, 0x3a000000, v89
	v_pk_add_f32 v[142:143], v[20:21], v[132:133] op_sel_hi:[1,0] neg_lo:[0,1] neg_hi:[0,1]
	v_pk_add_f32 v[140:141], v[122:123], v[132:133] op_sel_hi:[1,0] neg_lo:[0,1] neg_hi:[0,1]
	v_pk_mul_f32 v[20:21], v[142:143], v[142:143]
	v_pk_mul_f32 v[134:135], v[140:141], v[140:141]
	v_add_f32_e32 v20, v20, v21
	v_pk_add_f32 v[146:147], v[22:23], v[132:133] op_sel_hi:[1,0] neg_lo:[0,1] neg_hi:[0,1]
	v_add_f32_e32 v20, v134, v20
	v_pk_mul_f32 v[22:23], v[146:147], v[146:147]
	v_add_f32_e32 v20, v135, v20
	v_pk_add_f32 v[144:145], v[118:119], v[132:133] op_sel_hi:[1,0] neg_lo:[0,1] neg_hi:[0,1]
	v_add_f32_e32 v20, v22, v20
	v_pk_mul_f32 v[136:137], v[144:145], v[144:145]
	v_add_f32_e32 v20, v23, v20
	v_pk_add_f32 v[122:123], v[24:25], v[132:133] op_sel_hi:[1,0] neg_lo:[0,1] neg_hi:[0,1]
	v_add_f32_e32 v20, v136, v20
	v_pk_mul_f32 v[138:139], v[122:123], v[122:123]
	v_add_f32_e32 v20, v137, v20
	v_pk_add_f32 v[118:119], v[78:79], v[132:133] op_sel_hi:[1,0] neg_lo:[0,1] neg_hi:[0,1]
	v_add_f32_e32 v20, v138, v20
	v_pk_mul_f32 v[148:149], v[118:119], v[118:119]
	v_add_f32_e32 v20, v139, v20
	v_pk_add_f32 v[126:127], v[26:27], v[132:133] op_sel_hi:[1,0] neg_lo:[0,1] neg_hi:[0,1]
	v_add_f32_e32 v20, v148, v20
	v_pk_mul_f32 v[150:151], v[126:127], v[126:127]
	v_add_f32_e32 v20, v149, v20
	v_pk_add_f32 v[124:125], v[34:35], v[132:133] op_sel_hi:[1,0] neg_lo:[0,1] neg_hi:[0,1]
	v_add_f32_e32 v20, v150, v20
	v_pk_mul_f32 v[152:153], v[124:125], v[124:125]
	v_add_f32_e32 v20, v151, v20
	v_pk_add_f32 v[34:35], v[28:29], v[132:133] op_sel_hi:[1,0] neg_lo:[0,1] neg_hi:[0,1]
	v_add_f32_e32 v20, v152, v20
	v_pk_mul_f32 v[154:155], v[34:35], v[34:35]
	v_add_f32_e32 v20, v153, v20
	v_pk_add_f32 v[32:33], v[32:33], v[132:133] op_sel_hi:[1,0] neg_lo:[0,1] neg_hi:[0,1]
	v_add_f32_e32 v20, v154, v20
	v_pk_mul_f32 v[156:157], v[32:33], v[32:33]
	v_add_f32_e32 v20, v155, v20
	v_and_b32_e32 v135, 0xffff0000, v5
	v_lshlrev_b32_e32 v134, 16, v5
	v_and_b32_e32 v5, 0xffff0000, v4
	v_lshlrev_b32_e32 v4, 16, v4
	v_pk_add_f32 v[78:79], v[30:31], v[132:133] op_sel_hi:[1,0] neg_lo:[0,1] neg_hi:[0,1]
	v_add_f32_e32 v20, v156, v20
	v_add_f32_e32 v136, 0, v4
	v_pk_mul_f32 v[158:159], v[78:79], v[78:79]
	v_add_f32_e32 v20, v157, v20
	v_add_f32_e32 v136, v136, v5
	v_pk_add_f32 v[76:77], v[76:77], v[132:133] op_sel_hi:[1,0] neg_lo:[0,1] neg_hi:[0,1]
	v_add_f32_e32 v20, v158, v20
	v_add_f32_e32 v136, v136, v134
	v_pk_mul_f32 v[160:161], v[76:77], v[76:77]
	v_pk_add_f32 v[26:27], v[86:87], v[132:133] op_sel_hi:[1,0] neg_lo:[0,1] neg_hi:[0,1]
	v_pk_add_f32 v[24:25], v[82:83], v[132:133] op_sel_hi:[1,0] neg_lo:[0,1] neg_hi:[0,1]
	v_pk_add_f32 v[30:31], v[84:85], v[132:133] op_sel_hi:[1,0] neg_lo:[0,1] neg_hi:[0,1]
	v_pk_add_f32 v[28:29], v[80:81], v[132:133] op_sel_hi:[1,0] neg_lo:[0,1] neg_hi:[0,1]
	v_add_f32_e32 v20, v159, v20
	v_and_b32_e32 v133, 0xffff0000, v7
	v_lshlrev_b32_e32 v132, 16, v7
	v_and_b32_e32 v7, 0xffff0000, v6
	v_lshlrev_b32_e32 v6, 16, v6
	v_add_f32_e32 v136, v136, v135
	v_add_f32_e32 v20, v160, v20
	v_add_f32_e32 v136, v136, v6
	v_pk_mul_f32 v[86:87], v[26:27], v[26:27]
	v_add_f32_e32 v20, v161, v20
	v_add_f32_e32 v136, v136, v7
	v_add_f32_e32 v20, v86, v20
	v_add_f32_e32 v136, v136, v132
	v_pk_mul_f32 v[82:83], v[24:25], v[24:25]
	v_add_f32_e32 v20, v87, v20
	v_and_b32_e32 v87, 0xffff0000, v9
	v_lshlrev_b32_e32 v86, 16, v9
	v_and_b32_e32 v9, 0xffff0000, v8
	v_lshlrev_b32_e32 v8, 16, v8
	v_add_f32_e32 v136, v136, v133
	v_add_f32_e32 v20, v82, v20
	v_add_f32_e32 v136, v136, v8
	v_pk_mul_f32 v[84:85], v[30:31], v[30:31]
	v_add_f32_e32 v20, v83, v20
	v_add_f32_e32 v136, v136, v9
	v_add_f32_e32 v20, v84, v20
	v_add_f32_e32 v136, v136, v86
	v_add_f32_e32 v20, v85, v20
	v_and_b32_e32 v85, 0xffff0000, v11
	v_lshlrev_b32_e32 v84, 16, v11
	v_and_b32_e32 v11, 0xffff0000, v10
	v_lshlrev_b32_e32 v10, 16, v10
	v_add_f32_e32 v136, v136, v87
	v_add_f32_e32 v136, v136, v10
	v_add_f32_e32 v136, v136, v11
	v_add_f32_e32 v136, v136, v84
	v_and_b32_e32 v83, 0xffff0000, v13
	v_lshlrev_b32_e32 v82, 16, v13
	v_and_b32_e32 v13, 0xffff0000, v12
	v_lshlrev_b32_e32 v12, 16, v12
	v_add_f32_e32 v136, v136, v85
	v_add_f32_e32 v136, v136, v12
	v_pk_mul_f32 v[80:81], v[28:29], v[28:29]
	v_add_f32_e32 v136, v136, v13
	v_add_f32_e32 v20, v80, v20
	v_add_f32_e32 v136, v136, v82
	v_add_f32_e32 v89, v81, v20
	v_and_b32_e32 v81, 0xffff0000, v15
	v_lshlrev_b32_e32 v80, 16, v15
	v_and_b32_e32 v15, 0xffff0000, v14
	v_lshlrev_b32_e32 v14, 16, v14
	v_add_f32_e32 v136, v136, v83
	v_add_f32_e32 v136, v136, v14
	v_add_f32_e32 v136, v136, v15
	v_add_f32_e32 v136, v136, v80
	v_and_b32_e32 v23, 0xffff0000, v17
	v_lshlrev_b32_e32 v22, 16, v17
	v_and_b32_e32 v17, 0xffff0000, v16
	v_lshlrev_b32_e32 v16, 16, v16
	v_add_f32_e32 v136, v136, v81
	v_add_f32_e32 v136, v136, v16
	v_add_f32_e32 v136, v136, v17
	v_add_f32_e32 v136, v136, v22
	v_and_b32_e32 v21, 0xffff0000, v19
	v_lshlrev_b32_e32 v20, 16, v19
	v_and_b32_e32 v19, 0xffff0000, v18
	v_lshlrev_b32_e32 v18, 16, v18
	v_add_f32_e32 v136, v136, v23
	v_add_f32_e32 v136, v136, v18
	v_add_f32_e32 v136, v136, v19
	v_add_f32_e32 v136, v136, v20
	v_add_f32_e32 v136, v136, v21
	ds_bpermute_b32 v137, v53, v136
	s_waitcnt lgkmcnt(0)
	v_add_f32_e32 v136, v136, v137
	ds_bpermute_b32 v137, v171, v136
	s_waitcnt lgkmcnt(0)
	v_add_f32_e32 v136, v136, v137
	ds_bpermute_b32 v137, v172, v136
	s_waitcnt lgkmcnt(0)
	v_add_f32_e32 v136, v136, v137
	ds_bpermute_b32 v137, v173, v136
	s_waitcnt lgkmcnt(0)
	v_add_f32_e32 v136, v136, v137
	ds_bpermute_b32 v137, v174, v136
	s_waitcnt lgkmcnt(0)
	v_add_f32_e32 v136, v136, v137
	ds_bpermute_b32 v137, v175, v136
	s_waitcnt lgkmcnt(0)
	v_add_f32_e32 v136, v136, v137
	v_mul_f32_e32 v164, 0x3a000000, v136
	v_pk_add_f32 v[158:159], v[4:5], v[164:165] op_sel_hi:[1,0] neg_lo:[0,1] neg_hi:[0,1]
	v_pk_add_f32 v[156:157], v[134:135], v[164:165] op_sel_hi:[1,0] neg_lo:[0,1] neg_hi:[0,1]
	v_pk_mul_f32 v[4:5], v[158:159], v[158:159]
	v_pk_mul_f32 v[166:167], v[156:157], v[156:157]
	v_add_f32_e32 v4, v4, v5
	v_pk_add_f32 v[162:163], v[6:7], v[164:165] op_sel_hi:[1,0] neg_lo:[0,1] neg_hi:[0,1]
	v_add_f32_e32 v4, v166, v4
	v_pk_mul_f32 v[6:7], v[162:163], v[162:163]
	v_add_f32_e32 v4, v167, v4
	v_pk_add_f32 v[160:161], v[132:133], v[164:165] op_sel_hi:[1,0] neg_lo:[0,1] neg_hi:[0,1]
	v_add_f32_e32 v4, v6, v4
	v_pk_mul_f32 v[168:169], v[160:161], v[160:161]
	v_add_f32_e32 v4, v7, v4
	v_pk_add_f32 v[150:151], v[8:9], v[164:165] op_sel_hi:[1,0] neg_lo:[0,1] neg_hi:[0,1]
	v_add_f32_e32 v4, v168, v4
	v_pk_mul_f32 v[8:9], v[150:151], v[150:151]
	v_add_f32_e32 v4, v169, v4
	v_pk_add_f32 v[148:149], v[86:87], v[164:165] op_sel_hi:[1,0] neg_lo:[0,1] neg_hi:[0,1]
	v_add_f32_e32 v4, v8, v4
	v_pk_mul_f32 v[180:181], v[148:149], v[148:149]
	v_add_f32_e32 v4, v9, v4
	v_pk_add_f32 v[154:155], v[10:11], v[164:165] op_sel_hi:[1,0] neg_lo:[0,1] neg_hi:[0,1]
	v_add_f32_e32 v4, v180, v4
	v_pk_mul_f32 v[10:11], v[154:155], v[154:155]
	v_add_f32_e32 v4, v181, v4
	v_pk_add_f32 v[152:153], v[84:85], v[164:165] op_sel_hi:[1,0] neg_lo:[0,1] neg_hi:[0,1]
	v_add_f32_e32 v4, v10, v4
	v_pk_mul_f32 v[182:183], v[152:153], v[152:153]
	v_add_f32_e32 v4, v11, v4
	v_pk_add_f32 v[134:135], v[12:13], v[164:165] op_sel_hi:[1,0] neg_lo:[0,1] neg_hi:[0,1]
	v_add_f32_e32 v4, v182, v4
	v_pk_mul_f32 v[12:13], v[134:135], v[134:135]
	v_add_f32_e32 v4, v183, v4
	v_pk_add_f32 v[132:133], v[82:83], v[164:165] op_sel_hi:[1,0] neg_lo:[0,1] neg_hi:[0,1]
	v_add_f32_e32 v4, v12, v4
	v_pk_mul_f32 v[184:185], v[132:133], v[132:133]
	v_add_f32_e32 v4, v13, v4
	v_pk_add_f32 v[138:139], v[14:15], v[164:165] op_sel_hi:[1,0] neg_lo:[0,1] neg_hi:[0,1]
	v_add_f32_e32 v4, v184, v4
	v_pk_mul_f32 v[14:15], v[138:139], v[138:139]
	v_add_f32_e32 v4, v185, v4
	v_pk_add_f32 v[136:137], v[80:81], v[164:165] op_sel_hi:[1,0] neg_lo:[0,1] neg_hi:[0,1]
	v_add_f32_e32 v4, v14, v4
	v_pk_mul_f32 v[186:187], v[136:137], v[136:137]
	v_add_f32_e32 v4, v15, v4
	v_pk_add_f32 v[82:83], v[16:17], v[164:165] op_sel_hi:[1,0] neg_lo:[0,1] neg_hi:[0,1]
	v_add_f32_e32 v4, v186, v4
	v_pk_mul_f32 v[16:17], v[82:83], v[82:83]
	v_add_f32_e32 v4, v187, v4
	v_pk_add_f32 v[80:81], v[22:23], v[164:165] op_sel_hi:[1,0] neg_lo:[0,1] neg_hi:[0,1]
	v_add_f32_e32 v4, v16, v4
	v_pk_mul_f32 v[22:23], v[80:81], v[80:81]
	v_add_f32_e32 v4, v17, v4
	v_pk_add_f32 v[86:87], v[18:19], v[164:165] op_sel_hi:[1,0] neg_lo:[0,1] neg_hi:[0,1]
	v_add_f32_e32 v4, v22, v4
	v_pk_mul_f32 v[18:19], v[86:87], v[86:87]
	v_add_f32_e32 v4, v23, v4
	v_and_b32_e32 v23, 0xffff0000, v1
	v_lshlrev_b32_e32 v22, 16, v1
	v_and_b32_e32 v1, 0xffff0000, v0
	v_lshlrev_b32_e32 v0, 16, v0
	v_pk_add_f32 v[84:85], v[20:21], v[164:165] op_sel_hi:[1,0] neg_lo:[0,1] neg_hi:[0,1]
	v_add_f32_e32 v4, v18, v4
	v_add_f32_e32 v164, 0, v0
	v_pk_mul_f32 v[20:21], v[84:85], v[84:85]
	v_add_f32_e32 v4, v19, v4
	v_add_f32_e32 v164, v164, v1
	v_add_f32_e32 v4, v20, v4
	v_add_f32_e32 v164, v164, v22
	v_add_f32_e32 v4, v21, v4
	v_and_b32_e32 v21, 0xffff0000, v3
	v_lshlrev_b32_e32 v20, 16, v3
	v_and_b32_e32 v3, 0xffff0000, v2
	v_lshlrev_b32_e32 v2, 16, v2
	v_add_f32_e32 v164, v164, v23
	v_add_f32_e32 v164, v164, v2
	v_add_f32_e32 v164, v164, v3
	v_add_f32_e32 v164, v164, v20
	v_add_f32_e32 v164, v164, v21
	v_add_f32_e32 v164, v164, v130
	v_add_f32_e32 v164, v164, v131
	v_add_f32_e32 v164, v164, v112
	v_add_f32_e32 v164, v164, v113
	v_add_f32_e32 v164, v164, v110
	v_add_f32_e32 v164, v164, v111
	v_add_f32_e32 v164, v164, v106
	v_add_f32_e32 v164, v164, v107
	v_add_f32_e32 v164, v164, v104
	v_add_f32_e32 v164, v164, v105
	v_add_f32_e32 v164, v164, v102
	v_add_f32_e32 v164, v164, v103
	v_add_f32_e32 v164, v164, v100
	v_add_f32_e32 v164, v164, v101
	v_add_f32_e32 v164, v164, v98
	ds_bpermute_b32 v5, v53, v88
	v_add_f32_e32 v164, v164, v99
	ds_bpermute_b32 v7, v53, v4
	v_add_f32_e32 v164, v164, v96
	v_add_f32_e32 v164, v164, v97
	v_add_f32_e32 v164, v164, v94
	v_add_f32_e32 v164, v164, v95
	s_waitcnt lgkmcnt(1)
	v_add_f32_e32 v5, v88, v5
	ds_bpermute_b32 v6, v53, v89
	v_add_f32_e32 v164, v164, v92
	s_waitcnt lgkmcnt(1)
	v_add_f32_e32 v4, v4, v7
	ds_bpermute_b32 v7, v171, v5
	v_add_f32_e32 v164, v164, v93
	v_add_f32_e32 v164, v164, v90
	v_add_f32_e32 v164, v164, v91
	ds_bpermute_b32 v165, v53, v164
	s_waitcnt lgkmcnt(2)
	v_add_f32_e32 v6, v89, v6
	s_waitcnt lgkmcnt(1)
	v_add_f32_e32 v5, v5, v7
	ds_bpermute_b32 v7, v171, v6
	v_lshl_add_u64 v[88:89], s[14:15], 0, v[176:177]
	s_waitcnt lgkmcnt(1)
	v_add_f32_e32 v164, v164, v165
	ds_bpermute_b32 v165, v171, v164
	s_waitcnt lgkmcnt(1)
	v_add_f32_e32 v6, v6, v7
	ds_bpermute_b32 v7, v171, v4
	s_waitcnt lgkmcnt(1)
	v_add_f32_e32 v164, v164, v165
	ds_bpermute_b32 v165, v172, v164
	s_waitcnt lgkmcnt(1)
	v_add_f32_e32 v4, v4, v7
	ds_bpermute_b32 v7, v172, v5
	s_waitcnt lgkmcnt(1)
	v_add_f32_e32 v164, v164, v165
	ds_bpermute_b32 v165, v173, v164
	s_waitcnt lgkmcnt(1)
	v_add_f32_e32 v5, v5, v7
	ds_bpermute_b32 v7, v172, v6
	s_waitcnt lgkmcnt(1)
	v_add_f32_e32 v164, v164, v165
	ds_bpermute_b32 v165, v174, v164
	s_waitcnt lgkmcnt(1)
	v_add_f32_e32 v6, v6, v7
	ds_bpermute_b32 v7, v172, v4
	s_waitcnt lgkmcnt(1)
	v_add_f32_e32 v164, v164, v165
	ds_bpermute_b32 v165, v175, v164
	s_waitcnt lgkmcnt(1)
	v_add_f32_e32 v4, v4, v7
	ds_bpermute_b32 v7, v173, v5
	s_waitcnt lgkmcnt(1)
	v_add_f32_e32 v164, v164, v165
	v_mul_f32_e32 v176, 0x3a000000, v164
	v_pk_add_f32 v[0:1], v[0:1], v[176:177] op_sel_hi:[1,0] neg_lo:[0,1] neg_hi:[0,1]
	s_waitcnt lgkmcnt(0)
	v_add_f32_e32 v5, v5, v7
	ds_bpermute_b32 v7, v173, v6
	v_pk_mul_f32 v[186:187], v[0:1], v[0:1]
	v_pk_add_f32 v[22:23], v[22:23], v[176:177] op_sel_hi:[1,0] neg_lo:[0,1] neg_hi:[0,1]
	v_pk_add_f32 v[2:3], v[2:3], v[176:177] op_sel_hi:[1,0] neg_lo:[0,1] neg_hi:[0,1]
	v_pk_mul_f32 v[188:189], v[22:23], v[22:23]
	s_waitcnt lgkmcnt(0)
	v_add_f32_e32 v6, v6, v7
	ds_bpermute_b32 v7, v173, v4
	v_pk_add_f32 v[192:193], v[20:21], v[176:177] op_sel_hi:[1,0] neg_lo:[0,1] neg_hi:[0,1]
	v_pk_add_f32 v[130:131], v[130:131], v[176:177] op_sel_hi:[1,0] neg_lo:[0,1] neg_hi:[0,1]
	v_pk_add_f32 v[164:165], v[112:113], v[176:177] op_sel_hi:[1,0] neg_lo:[0,1] neg_hi:[0,1]
	v_pk_add_f32 v[166:167], v[110:111], v[176:177] op_sel_hi:[1,0] neg_lo:[0,1] neg_hi:[0,1]
	v_pk_add_f32 v[168:169], v[106:107], v[176:177] op_sel_hi:[1,0] neg_lo:[0,1] neg_hi:[0,1]
	v_pk_add_f32 v[104:105], v[104:105], v[176:177] op_sel_hi:[1,0] neg_lo:[0,1] neg_hi:[0,1]
	v_pk_add_f32 v[102:103], v[102:103], v[176:177] op_sel_hi:[1,0] neg_lo:[0,1] neg_hi:[0,1]
	v_pk_add_f32 v[110:111], v[100:101], v[176:177] op_sel_hi:[1,0] neg_lo:[0,1] neg_hi:[0,1]
	v_pk_add_f32 v[106:107], v[98:99], v[176:177] op_sel_hi:[1,0] neg_lo:[0,1] neg_hi:[0,1]
	v_pk_add_f32 v[96:97], v[96:97], v[176:177] op_sel_hi:[1,0] neg_lo:[0,1] neg_hi:[0,1]
	v_pk_add_f32 v[94:95], v[94:95], v[176:177] op_sel_hi:[1,0] neg_lo:[0,1] neg_hi:[0,1]
	v_pk_add_f32 v[92:93], v[92:93], v[176:177] op_sel_hi:[1,0] neg_lo:[0,1] neg_hi:[0,1]
	v_pk_add_f32 v[90:91], v[90:91], v[176:177] op_sel_hi:[1,0] neg_lo:[0,1] neg_hi:[0,1]
	v_add_f32_e32 v176, v186, v187
	v_add_f32_e32 v176, v188, v176
	v_pk_mul_f32 v[190:191], v[2:3], v[2:3]
	v_add_f32_e32 v176, v189, v176
	s_waitcnt lgkmcnt(0)
	v_add_f32_e32 v4, v4, v7
	ds_bpermute_b32 v7, v174, v5
	v_add_f32_e32 v176, v190, v176
	v_pk_mul_f32 v[20:21], v[192:193], v[192:193]
	v_add_f32_e32 v176, v191, v176
	v_add_f32_e32 v20, v20, v176
	v_pk_mul_f32 v[194:195], v[130:131], v[130:131]
	v_add_f32_e32 v20, v21, v20
	v_add_f32_e32 v20, v194, v20
	s_waitcnt lgkmcnt(0)
	v_add_f32_e32 v184, v5, v7
	ds_bpermute_b32 v5, v174, v6
	v_pk_mul_f32 v[112:113], v[164:165], v[164:165]
	v_add_f32_e32 v20, v195, v20
	v_add_f32_e32 v20, v112, v20
	v_pk_mul_f32 v[196:197], v[166:167], v[166:167]
	v_add_f32_e32 v20, v113, v20
	v_add_f32_e32 v20, v196, v20
	v_pk_mul_f32 v[198:199], v[168:169], v[168:169]
	v_add_f32_e32 v20, v197, v20
	s_waitcnt lgkmcnt(0)
	v_add_f32_e32 v182, v6, v5
	ds_bpermute_b32 v5, v174, v4
	v_add_f32_e32 v20, v198, v20
	v_pk_mul_f32 v[200:201], v[104:105], v[104:105]
	v_add_f32_e32 v20, v199, v20
	v_add_f32_e32 v20, v200, v20
	v_pk_mul_f32 v[202:203], v[102:103], v[102:103]
	v_add_f32_e32 v20, v201, v20
	v_add_f32_e32 v20, v202, v20
	s_waitcnt lgkmcnt(0)
	v_add_f32_e32 v180, v4, v5
	global_load_dwordx4 v[12:15], v[54:55], off
	global_load_dwordx4 v[4:7], v[54:55], off offset:16
	global_load_dwordx4 v[16:19], v[56:57], off
	global_load_dwordx4 v[8:11], v[56:57], off offset:16
	v_pk_mul_f32 v[100:101], v[110:111], v[110:111]
	v_add_f32_e32 v20, v203, v20
	v_add_f32_e32 v20, v100, v20
	v_pk_mul_f32 v[98:99], v[106:107], v[106:107]
	v_add_f32_e32 v20, v101, v20
	v_add_f32_e32 v20, v98, v20
	v_pk_mul_f32 v[218:219], v[96:97], v[96:97]
	v_add_f32_e32 v20, v99, v20
	v_add_f32_e32 v20, v218, v20
	v_pk_mul_f32 v[220:221], v[94:95], v[94:95]
	v_add_f32_e32 v20, v219, v20
	v_add_f32_e32 v20, v220, v20
	v_pk_mul_f32 v[222:223], v[92:93], v[92:93]
	v_add_f32_e32 v20, v221, v20
	v_add_f32_e32 v20, v222, v20
	v_pk_mul_f32 v[224:225], v[90:91], v[90:91]
	v_add_f32_e32 v20, v223, v20
	v_add_f32_e32 v20, v224, v20
	v_add_f32_e32 v20, v225, v20
	ds_bpermute_b32 v21, v53, v20
	ds_bpermute_b32 v185, v175, v184
	ds_bpermute_b32 v183, v175, v182
	ds_bpermute_b32 v181, v175, v180
	s_waitcnt lgkmcnt(3)
	v_add_f32_e32 v20, v20, v21
	ds_bpermute_b32 v21, v171, v20
	s_waitcnt lgkmcnt(0)
	v_add_f32_e32 v20, v20, v21
	ds_bpermute_b32 v21, v172, v20
	s_waitcnt lgkmcnt(0)
	v_add_f32_e32 v20, v20, v21
	ds_bpermute_b32 v21, v173, v20
	s_waitcnt lgkmcnt(0)
	v_add_f32_e32 v20, v20, v21
	ds_bpermute_b32 v21, v174, v20
	s_waitcnt lgkmcnt(0)
	v_add_f32_e32 v20, v20, v21
	ds_bpermute_b32 v21, v175, v20
	s_waitcnt lgkmcnt(0)
	v_add_f32_e32 v20, v20, v21
	v_fmamk_f32 v20, v20, 0x3a000000, v206
	v_cmp_gt_f32_e32 vcc, s48, v20
	v_mul_f32_e32 v21, 0x4f800000, v20
	s_nop 0
	v_cndmask_b32_e32 v20, v20, v21, vcc
	v_sqrt_f32_e32 v21, v20
	s_nop 0
	v_add_u32_e32 v98, -1, v21
	v_fma_f32 v99, -v98, v21, v20
	v_cmp_ge_f32_e64 s[42:43], 0, v99
	v_add_u32_e32 v99, 1, v21
	s_nop 0
	v_cndmask_b32_e64 v98, v21, v98, s[42:43]
	v_fma_f32 v21, -v99, v21, v20
	v_cmp_lt_f32_e64 s[42:43], 0, v21
	s_nop 1
	v_cndmask_b32_e64 v21, v98, v99, s[42:43]
	v_mul_f32_e32 v98, 0x37800000, v21
	v_cndmask_b32_e32 v21, v21, v98, vcc
	v_cmp_class_f32_e32 vcc, v20, v205
	s_nop 1
	v_cndmask_b32_e32 v20, v21, v20, vcc
	v_div_scale_f32 v21, s[14:15], v20, v20, 1.0
	v_rcp_f32_e32 v98, v21
	s_nop 0
	v_fma_f32 v99, -v21, v98, 1.0
	v_fmac_f32_e32 v98, v99, v98
	v_div_scale_f32 v99, vcc, 1.0, v20, 1.0
	v_mul_f32_e32 v100, v99, v98
	v_fma_f32 v101, -v21, v100, v99
	v_fmac_f32_e32 v100, v101, v98
	v_fma_f32 v21, -v21, v100, v99
	v_div_fmas_f32 v21, v21, v98, v100
	v_div_fixup_f32 v100, v21, v20, 1.0
	v_pk_mul_f32 v[0:1], v[0:1], v[100:101] op_sel_hi:[1,0]
	s_waitcnt vmcnt(1)
	v_pk_fma_f32 v[20:21], v[12:13], v[0:1], v[16:17]
	v_pk_mul_f32 v[0:1], v[2:3], v[100:101] op_sel_hi:[1,0]
	v_pk_mul_f32 v[2:3], v[22:23], v[100:101] op_sel_hi:[1,0]
	s_waitcnt vmcnt(0)
	v_pk_fma_f32 v[0:1], v[4:5], v[0:1], v[8:9]
	v_pk_fma_f32 v[22:23], v[14:15], v[2:3], v[18:19]
	v_pk_mul_f32 v[2:3], v[192:193], v[100:101] op_sel_hi:[1,0]
	s_nop 0
	v_pk_fma_f32 v[2:3], v[6:7], v[2:3], v[10:11]
	s_cbranch_scc1 .LBB0_318
	global_store_dwordx4 v[88:89], v[20:23], off nt
	global_store_dwordx4 v[88:89], v[0:3], off offset:16 nt

.LBB0_700:
	v_lshlrev_b32_e32 v64, 16, v145
	v_mul_f32_e32 v64, 0xbfb8aa3b, v64
	v_exp_f32_e32 v64, v64
	v_and_b32_e32 v65, 0xffff0000, v145
	v_mul_f32_e32 v65, 0xbfb8aa3b, v65
	v_exp_f32_e32 v65, v65
	v_add_f32_e32 v64, 1.0, v64
	v_rcp_f32_e32 v64, v64
	s_lshl_b32 s6, s16, 1
	v_add_f32_e32 v75, 1.0, v65
	v_add_f32_e32 v65, v144, v146
	v_div_scale_f32 v66, s[8:9], v65, v65, v64
	v_rcp_f32_e32 v67, v66
	v_cmp_lt_f32_e64 s[44:45], 0, v65
	v_lshlrev_b32_e32 v176, 1, v110
	s_waitcnt lgkmcnt(0)
	v_fma_f32 v68, -v66, v67, 1.0
	v_fmac_f32_e32 v67, v68, v67
	v_div_scale_f32 v68, vcc, v64, v65, v64
	v_mul_f32_e32 v69, v68, v67
	v_fma_f32 v70, -v66, v69, v68
	v_fmac_f32_e32 v69, v70, v67
	v_fma_f32 v66, -v66, v69, v68
	v_div_fmas_f32 v66, v66, v67, v69
	v_div_fixup_f32 v64, v66, v65, v64
	v_cndmask_b32_e64 v74, 0, v64, s[44:45]
	v_pk_mul_f32 v[66:67], v[74:75], v[4:5] op_sel_hi:[0,1]
	ds_bpermute_b32 v5, v140, v149
	v_rcp_f32_e32 v4, v75
	v_pk_mul_f32 v[64:65], v[74:75], v[6:7] op_sel_hi:[0,1]
	v_pk_mul_f32 v[72:73], v[74:75], v[24:25] op_sel_hi:[0,1]
	v_pk_mul_f32 v[24:25], v[74:75], v[8:9] op_sel_hi:[0,1]
	s_waitcnt lgkmcnt(0)
	v_add_f32_e32 v5, v149, v5
	v_div_scale_f32 v6, s[8:9], v5, v5, v4
	v_rcp_f32_e32 v7, v6
	v_pk_mul_f32 v[76:77], v[74:75], v[22:23] op_sel_hi:[0,1]
	v_pk_mul_f32 v[22:23], v[74:75], v[10:11] op_sel_hi:[0,1]
	v_readlane_b32 s8, v248, 7
	v_fma_f32 v8, -v6, v7, 1.0
	v_fmac_f32_e32 v7, v8, v7
	v_div_scale_f32 v8, vcc, v4, v5, v4
	v_mul_f32_e32 v9, v8, v7
	v_fma_f32 v10, -v6, v9, v8
	v_fmac_f32_e32 v9, v10, v7
	v_fma_f32 v6, -v6, v9, v8
	v_div_fmas_f32 v6, v6, v7, v9
	v_div_fixup_f32 v4, v6, v5, v4
	v_lshlrev_b64 v[6:7], 10, v[114:115]
	v_readlane_b32 s9, v248, 8
	v_pk_mul_f32 v[82:83], v[74:75], v[16:17] op_sel_hi:[0,1]
	v_pk_mul_f32 v[70:71], v[74:75], v[0:1] op_sel_hi:[0,1]
	v_lshl_add_u64 v[6:7], s[8:9], 0, v[6:7]
	v_lshl_add_u64 v[6:7], v[6:7], 0, s[6:7]
	v_pk_mul_f32 v[80:81], v[74:75], v[18:19] op_sel_hi:[0,1]
	v_pk_mul_f32 v[68:69], v[74:75], v[2:3] op_sel_hi:[0,1]
	v_pk_mul_f32 v[78:79], v[74:75], v[20:21] op_sel_hi:[0,1]
	v_pk_mul_f32 v[16:17], v[74:75], v[26:27] op_sel_hi:[0,1]
	v_pk_mul_f32 v[18:19], v[74:75], v[28:29] op_sel_hi:[0,1]
	v_pk_mul_f32 v[2:3], v[74:75], v[12:13] op_sel_hi:[0,1]
	v_pk_mul_f32 v[20:21], v[74:75], v[30:31] op_sel_hi:[0,1]
	v_pk_mul_f32 v[0:1], v[74:75], v[14:15] op_sel_hi:[0,1]
	v_lshl_add_u64 v[74:75], v[6:7], 0, v[176:177]
	s_barrier
	global_load_dwordx2 v[8:9], v[74:75], off
	v_cmp_lt_f32_e64 s[44:45], 0, v5
	s_add_i32 s15, s15, s40
	s_cmpk_gt_i32 s15, 0x1ff
	v_cndmask_b32_e64 v4, 0, v4, s[44:45]
	v_pk_fma_f32 v[6:7], v[4:5], v[48:49], v[82:83] op_sel_hi:[0,1,1]
	v_pk_fma_f32 v[16:17], v[4:5], v[58:59], v[16:17] op_sel_hi:[0,1,1]
	v_pk_fma_f32 v[18:19], v[4:5], v[60:61], v[18:19] op_sel_hi:[0,1,1]
	v_pk_fma_f32 v[20:21], v[4:5], v[62:63], v[20:21] op_sel_hi:[0,1,1]
	v_pk_fma_f32 v[24:25], v[4:5], v[40:41], v[24:25] op_sel_hi:[0,1,1]
	v_pk_fma_f32 v[22:23], v[4:5], v[42:43], v[22:23] op_sel_hi:[0,1,1]
	v_pk_fma_f32 v[2:3], v[4:5], v[44:45], v[2:3] op_sel_hi:[0,1,1]
	v_pk_fma_f32 v[0:1], v[4:5], v[46:47], v[0:1] op_sel_hi:[0,1,1]
	s_waitcnt vmcnt(0) lgkmcnt(0)
	v_and_b32_e32 v11, 0xffff0000, v8
	v_lshlrev_b32_e32 v10, 16, v8
	v_pk_add_f32 v[6:7], v[6:7], v[10:11]
	v_pk_fma_f32 v[10:11], v[4:5], v[50:51], v[80:81] op_sel_hi:[0,1,1]
	v_and_b32_e32 v13, 0xffff0000, v9
	v_lshlrev_b32_e32 v12, 16, v9
	v_pk_add_f32 v[8:9], v[10:11], v[12:13]
	global_load_dwordx2 v[12:13], v[74:75], off offset:16
	v_pk_fma_f32 v[10:11], v[4:5], v[52:53], v[78:79] op_sel_hi:[0,1,1]
	v_cvt_pk_bf16_f32 v6, v6, v7
	v_cvt_pk_bf16_f32 v7, v8, v9
	s_waitcnt vmcnt(0) lgkmcnt(0)
	v_and_b32_e32 v15, 0xffff0000, v12
	v_lshlrev_b32_e32 v14, 16, v12
	v_pk_add_f32 v[10:11], v[10:11], v[14:15]
	v_pk_fma_f32 v[14:15], v[4:5], v[54:55], v[76:77] op_sel_hi:[0,1,1]
	v_and_b32_e32 v27, 0xffff0000, v13
	v_lshlrev_b32_e32 v26, 16, v13
	v_pk_add_f32 v[12:13], v[14:15], v[26:27]
	global_load_dwordx2 v[26:27], v[74:75], off offset:32
	v_pk_fma_f32 v[14:15], v[4:5], v[56:57], v[72:73] op_sel_hi:[0,1,1]
	s_waitcnt vmcnt(0) lgkmcnt(0)
	v_and_b32_e32 v29, 0xffff0000, v26
	v_lshlrev_b32_e32 v28, 16, v26
	v_pk_add_f32 v[14:15], v[14:15], v[28:29]
	v_and_b32_e32 v29, 0xffff0000, v27
	v_lshlrev_b32_e32 v28, 16, v27
	global_load_dwordx2 v[26:27], v[74:75], off offset:48
	v_pk_add_f32 v[16:17], v[16:17], v[28:29]
	s_waitcnt vmcnt(0) lgkmcnt(0)
	v_and_b32_e32 v29, 0xffff0000, v26
	v_lshlrev_b32_e32 v28, 16, v26
	v_pk_add_f32 v[18:19], v[18:19], v[28:29]
	v_and_b32_e32 v29, 0xffff0000, v27
	v_lshlrev_b32_e32 v28, 16, v27
	v_pk_add_f32 v[20:21], v[20:21], v[28:29]
	global_load_dwordx2 v[28:29], v[74:75], off offset:64
	v_pk_fma_f32 v[26:27], v[4:5], v[32:33], v[70:71] op_sel_hi:[0,1,1]
	s_waitcnt vmcnt(0) lgkmcnt(0)
	v_and_b32_e32 v31, 0xffff0000, v28
	v_lshlrev_b32_e32 v30, 16, v28
	v_pk_add_f32 v[26:27], v[26:27], v[30:31]
	v_pk_fma_f32 v[30:31], v[4:5], v[34:35], v[68:69] op_sel_hi:[0,1,1]
	v_and_b32_e32 v33, 0xffff0000, v29
	v_lshlrev_b32_e32 v32, 16, v29
	v_pk_add_f32 v[28:29], v[30:31], v[32:33]
	global_load_dwordx2 v[32:33], v[74:75], off offset:80
	v_pk_fma_f32 v[30:31], v[4:5], v[36:37], v[66:67] op_sel_hi:[0,1,1]
	s_waitcnt vmcnt(0) lgkmcnt(0)
	v_and_b32_e32 v35, 0xffff0000, v32
	v_lshlrev_b32_e32 v34, 16, v32
	v_pk_add_f32 v[30:31], v[30:31], v[34:35]
	v_pk_fma_f32 v[34:35], v[4:5], v[38:39], v[64:65] op_sel_hi:[0,1,1]
	v_and_b32_e32 v37, 0xffff0000, v33
	v_lshlrev_b32_e32 v36, 16, v33
	v_pk_add_f32 v[32:33], v[34:35], v[36:37]
	global_load_dwordx2 v[34:35], v[74:75], off offset:96
	s_waitcnt vmcnt(0) lgkmcnt(0)
	v_and_b32_e32 v37, 0xffff0000, v34
	v_lshlrev_b32_e32 v36, 16, v34
	v_pk_add_f32 v[24:25], v[24:25], v[36:37]
	v_and_b32_e32 v37, 0xffff0000, v35
	v_lshlrev_b32_e32 v36, 16, v35
	global_load_dwordx2 v[34:35], v[74:75], off offset:112
	v_pk_add_f32 v[22:23], v[22:23], v[36:37]
	s_waitcnt vmcnt(0) lgkmcnt(0)
	v_and_b32_e32 v5, 0xffff0000, v35
	v_lshlrev_b32_e32 v4, 16, v35
	v_pk_add_f32 v[0:1], v[0:1], v[4:5]
	v_lshlrev_b64 v[4:5], 12, v[114:115]
	v_lshl_add_u64 v[4:5], s[0:1], 0, v[4:5]
	v_lshl_add_u64 v[4:5], v[4:5], 0, s[6:7]
	v_lshl_add_u64 v[4:5], v[4:5], 0, v[176:177]
	flat_store_dwordx2 v[4:5], v[6:7] offset:1024
	v_cvt_pk_bf16_f32 v6, v10, v11
	v_cvt_pk_bf16_f32 v7, v12, v13
	flat_store_dwordx2 v[4:5], v[6:7] offset:1040
	v_cvt_pk_bf16_f32 v6, v14, v15
	v_cvt_pk_bf16_f32 v7, v16, v17
	flat_store_dwordx2 v[4:5], v[6:7] offset:1056
	v_cvt_pk_bf16_f32 v6, v18, v19
	v_cvt_pk_bf16_f32 v7, v20, v21
	v_and_b32_e32 v37, 0xffff0000, v34
	v_lshlrev_b32_e32 v36, 16, v34
	flat_store_dwordx2 v[4:5], v[6:7] offset:1072
	v_cvt_pk_bf16_f32 v6, v26, v27
	v_cvt_pk_bf16_f32 v7, v28, v29
	v_pk_add_f32 v[2:3], v[2:3], v[36:37]
	flat_store_dwordx2 v[4:5], v[6:7] offset:1088
	v_cvt_pk_bf16_f32 v6, v30, v31
	v_cvt_pk_bf16_f32 v7, v32, v33
	flat_store_dwordx2 v[4:5], v[6:7] offset:1104
	v_cvt_pk_bf16_f32 v6, v24, v25
	v_cvt_pk_bf16_f32 v7, v22, v23
	v_cvt_pk_bf16_f32 v2, v2, v3
	v_cvt_pk_bf16_f32 v3, v0, v1
	flat_store_dwordx2 v[4:5], v[6:7] offset:1120
	flat_store_dwordx2 v[4:5], v[2:3] offset:1136
	s_cbranch_scc1 .LBB0_738
.LBB0_701:
	s_ashr_i32 s6, s15, 6
	s_lshr_b32 s8, s15, 6
	s_sub_i32 s6, 7, s6
	s_add_i32 s8, s8, -4
	s_cmpk_lt_i32 s15, 0x100
	s_cselect_b32 s20, s6, s8
	s_lshl_b32 s18, s20, 8
	s_add_i32 s19, s18, s14
	v_or_b32_e32 v58, s19, v129
	s_lshl_b32 s6, s15, 8
	s_and_b32 s8, s6, 0x3800
	s_mov_b32 s9, s7
	v_ashrrev_i32_e32 v59, 31, v58
	v_lshl_add_u64 v[114:115], v[58:59], 0, s[8:9]
	v_mov_b64_e32 v[0:1], s[26:27]
	s_movk_i32 s6, 0x1e00
	s_and_b32 s21, s15, 7
	v_mad_u64_u32 v[56:57], s[10:11], v114, s6, v[0:1]
	v_mad_i32_i24 v57, v115, s6, v57
	s_lshl_b32 s6, s21, 7
	v_lshl_add_u64 v[0:1], v[56:57], 0, s[6:7]
	v_mov_b32_e32 v113, v177
	v_lshl_add_u64 v[0:1], v[0:1], 0, v[112:113]
	global_load_dwordx4 v[80:83], v[0:1], off offset:1024
	global_load_dwordx4 v[84:87], v[0:1], off offset:1056
	global_load_dwordx4 v[88:91], v[0:1], off offset:1088
	global_load_dwordx4 v[92:95], v[0:1], off offset:1120
	s_and_b32 s6, s15, 4
	v_lshl_add_u64 v[0:1], v[114:115], 3, s[96:97]
	v_lshl_add_u64 v[0:1], v[0:1], 0, s[6:7]
	global_load_dword v59, v[0:1], off
	s_lshl_b32 s9, s20, 2
	s_bfe_u32 s38, s15, 0x10002
	s_lshl_b32 s16, s21, 6
	s_add_i32 s10, s9, 4
	s_mov_b32 s6, 0
	s_mov_b32 s11, 0

.LBB0_705:
	s_or_b64 exec, exec, s[10:11]
	s_mul_i32 s6, s8, 0x1e00
	s_add_u32 s6, s26, s6
	s_addc_u32 s11, s27, 0
	s_lshl_b32 s10, s38, 7
	s_add_u32 s10, s6, s10
	s_addc_u32 s11, s11, 0
	s_add_i32 s6, 0, 0x8c20
	s_cmp_lg_u32 s6, -1
	v_lshl_add_u64 v[0:1], s[10:11], 0, v[104:105]
	v_lshlrev_b32_e32 v176, 1, v106
	s_cselect_b32 s6, s6, 0
	v_lshl_add_u64 v[116:117], v[0:1], 0, v[176:177]
	s_cselect_b32 s10, s35, 0
	v_mov_b32_e32 v0, s6
	s_add_i32 s6, 0, 0x8c24
	s_cmp_lg_u32 s6, -1
	v_mov_b32_e32 v1, s10
	s_cselect_b32 s6, s6, 0
	s_cselect_b32 s10, s35, 0
	s_waitcnt lgkmcnt(0)
	s_barrier
	flat_load_dword v2, v[0:1] sc0 sc1
	s_waitcnt vmcnt(0)
	v_mov_b32_e32 v0, s6
	v_mov_b32_e32 v1, s10
	flat_load_dword v0, v[0:1] sc0 sc1
	s_waitcnt vmcnt(0)
	s_add_i32 s6, 0, 0x8c28
	s_cmp_lg_u32 s6, -1
	s_cselect_b32 s6, s6, 0
	s_cselect_b32 s10, s35, 0
	v_mov_b32_e32 v1, s10
	v_sub_u32_e32 v62, v110, v58
	s_waitcnt lgkmcnt(0)
	v_or_b32_e32 v2, v0, v2
	v_mov_b32_e32 v0, s6
	s_add_i32 s6, 0, 0x8c2c
	s_cmp_lg_u32 s6, -1
	s_cselect_b32 s6, s6, 0
	s_cselect_b32 s10, s35, 0
	flat_load_dword v3, v[0:1] sc0 sc1
	s_waitcnt vmcnt(0)
	v_mov_b32_e32 v0, s6
	v_mov_b32_e32 v1, s10
	flat_load_dword v0, v[0:1] sc0 sc1
	s_waitcnt vmcnt(0)
	s_add_i32 s6, 0, 0x8c30
	s_cmp_lg_u32 s6, -1
	s_cselect_b32 s6, s6, 0
	s_cselect_b32 s10, s35, 0
	v_mov_b32_e32 v1, s10
	s_waitcnt lgkmcnt(0)
	v_or3_b32 v2, v2, v3, v0
	v_mov_b32_e32 v0, s6
	s_add_i32 s6, 0, 0x8c34
	s_cmp_lg_u32 s6, -1
	s_cselect_b32 s6, s6, 0
	s_cselect_b32 s10, s35, 0
	flat_load_dword v3, v[0:1] sc0 sc1
	s_waitcnt vmcnt(0)
	v_mov_b32_e32 v0, s6
	v_mov_b32_e32 v1, s10
	flat_load_dword v0, v[0:1] sc0 sc1
	s_waitcnt vmcnt(0)
	s_add_i32 s6, 0, 0x8c38
	s_cmp_lg_u32 s6, -1
	s_cselect_b32 s6, s6, 0
	s_cselect_b32 s10, s35, 0
	v_mov_b32_e32 v1, s10
	s_waitcnt lgkmcnt(0)
	v_or3_b32 v2, v2, v3, v0
	v_mov_b32_e32 v0, s6
	s_add_i32 s6, 0, 0x8c3c
	s_cmp_lg_u32 s6, -1
	s_cselect_b32 s6, s6, 0
	s_cselect_b32 s10, s35, 0
	flat_load_dword v3, v[0:1] sc0 sc1
	s_waitcnt vmcnt(0)
	v_mov_b32_e32 v0, s6
	v_mov_b32_e32 v1, s10
	flat_load_dword v0, v[0:1] sc0 sc1
	s_waitcnt vmcnt(0) lgkmcnt(0)
	v_or3_b32 v0, v2, v3, v0
	s_nop 0
	v_readfirstlane_b32 s10, v0
	s_cmp_lg_u32 s10, 0
	s_cbranch_scc0 .LBB0_737
	s_lshl_b32 s6, s38, 6
	s_lshl_b32 s6, s6, 15
	s_add_u32 s6, s23, s6
	s_addc_u32 s11, s77, 0
	s_lshl_b32 s12, s8, 1
	s_add_u32 s12, s6, s12
	s_addc_u32 s13, s11, 0
	s_ff1_i32_b32 s33, s10
	v_lshl_add_u64 v[0:1], s[12:13], 0, v[108:109]
	s_mul_i32 s6, s33, 0x78000
	v_lshl_add_u64 v[60:61], v[0:1], 0, v[176:177]
	v_lshl_add_u64 v[0:1], v[116:117], 0, s[6:7]
	s_lshl_b32 s6, s33, 7
	v_lshl_add_u64 v[2:3], v[60:61], 0, s[6:7]
	global_load_dwordx4 v[48:51], v[0:1], off offset:2560
	global_load_dwordx4 v[52:55], v[2:3], off
	s_add_i32 s6, s10, -1
	v_mov_b32_e32 v144, 0
	s_and_b32 s39, s6, s10
	s_or_b32 s17, s19, 31
	v_add_u32_e32 v63, v58, v124
	v_add_u32_e32 v64, v58, v125
	v_add_u32_e32 v65, v58, v126
	v_add_u32_e32 v66, v58, v127
	v_add_u32_e32 v67, v58, v130
	v_add_u32_e32 v68, v58, v131
	v_add_u32_e32 v69, v58, v132
	v_add_u32_e32 v70, v58, v133
	v_add_u32_e32 v71, v58, v134
	v_add_u32_e32 v72, v58, v135
	v_add_u32_e32 v73, v58, v136
	v_add_u32_e32 v74, v58, v137
	v_add_u32_e32 v75, v58, v138
	v_add_u32_e32 v76, v58, v139
	v_sub_u32_e32 v113, v110, v58
	s_mov_b64 s[10:11], 0
	v_mov_b32_e32 v78, 0xff800000
	v_mov_b32_e32 v16, 0
	v_mov_b32_e32 v17, v144
	v_mov_b32_e32 v18, v144
	v_mov_b32_e32 v19, v144
	v_mov_b32_e32 v20, v144
	v_mov_b32_e32 v21, v144
	v_mov_b32_e32 v22, v144
	v_mov_b32_e32 v23, v144
	v_mov_b32_e32 v24, v144
	v_mov_b32_e32 v25, v144
	v_mov_b32_e32 v26, v144
	v_mov_b32_e32 v27, v144
	v_mov_b32_e32 v28, v144
	v_mov_b32_e32 v29, v144
	v_mov_b32_e32 v30, v144
	v_mov_b32_e32 v31, v144
	v_mov_b32_e32 v0, v144
	v_mov_b32_e32 v1, v144
	v_mov_b32_e32 v2, v144
	v_mov_b32_e32 v3, v144
	v_mov_b32_e32 v4, v144
	v_mov_b32_e32 v5, v144
	v_mov_b32_e32 v6, v144
	v_mov_b32_e32 v7, v144
	v_mov_b32_e32 v8, v144
	v_mov_b32_e32 v9, v144
	v_mov_b32_e32 v10, v144
	v_mov_b32_e32 v11, v144
	v_mov_b32_e32 v12, v144
	v_mov_b32_e32 v13, v144
	v_mov_b32_e32 v14, v144
	v_mov_b32_e32 v15, v144
.LBB0_707:
	s_and_b64 s[12:13], s[10:11], exec
	s_cselect_b32 s6, 0x4600, 0
	s_add_i32 s44, s6, 0
	v_add3_u32 v32, s44, v107, v176
	s_waitcnt vmcnt(0) lgkmcnt(0)
	ds_write_b128 v32, v[48:51]
	v_add_u32_e32 v32, s44, v111
	v_add3_u32 v32, v32, v176, s78
	ds_write2_b64 v32, v[52:53], v[54:55] offset1:1
	v_sub_co_u32_e64 v32, s[12:13], s39, 1
	s_nop 0
	v_readfirstlane_b32 s48, v32
	s_ff1_i32_b32 s41, s39
	s_and_b64 vcc, exec, s[12:13]
	s_waitcnt lgkmcnt(0)
	s_barrier
	s_cbranch_vccnz .LBB0_709
	s_mul_i32 s6, s41, 0x78000
	v_lshl_add_u64 v[32:33], v[116:117], 0, s[6:7]
	s_lshl_b32 s6, s41, 7
	v_lshl_add_u64 v[34:35], v[60:61], 0, s[6:7]
	global_load_dwordx4 v[48:51], v[32:33], off offset:2560
	global_load_dwordx4 v[52:55], v[34:35], off

.LBB0_723:
	s_mul_i32 s6, s21, 6
	v_lshl_add_u64 v[32:33], v[56:57], 0, s[6:7]
	s_movk_i32 s6, 0x1000
	s_or_b32 s12, s9, 3
	v_add_co_u32_e32 v32, vcc, s6, v32
	s_lshl_b32 s6, s38, 21
	s_add_u32 s6, s23, s6
	s_addc_u32 s11, s77, 0
	s_lshl_b32 s8, s8, 1
	s_add_u32 s10, s6, s8
	s_addc_u32 s11, s11, 0
	s_add_i32 s9, s9, -8
	v_lshl_add_u64 v[34:35], s[10:11], 0, v[108:109]
	s_cmp_gt_u32 s20, 2
	v_lshl_add_u64 v[34:35], v[34:35], 0, v[176:177]
	s_mov_b64 s[10:11], 0x400000
	s_cselect_b32 s13, s9, 0
	v_addc_co_u32_e32 v33, vcc, 0, v33, vcc
	v_lshl_add_u64 v[118:119], v[34:35], 0, s[10:11]
	s_lshl_b32 s6, s13, 6
	s_waitcnt lgkmcnt(0)
	s_barrier
	v_lshl_add_u64 v[34:35], s[6:7], 1, v[118:119]
	global_load_dword v145, v[32:33], off offset:3074
	global_load_dwordx4 v[96:99], v[34:35], off
	v_mad_u64_u32 v[32:33], s[8:9], s6, v210, v[116:117]
	global_load_dwordx4 v[100:103], v[32:33], off offset:2816
	ds_bpermute_b32 v146, v140, v144
	v_add_u32_e32 v32, s18, v142
	s_addk_i32 s19, 0xfe01
	v_subrev_u32_e32 v147, s6, v32
	v_subrev_u32_e32 v148, s18, v143
	s_waitcnt vmcnt(0)
	v_mov_b32_e32 v48, v177
	v_mov_b32_e32 v49, v177
	v_mov_b32_e32 v50, v177
	v_mov_b32_e32 v51, v177
	v_mov_b32_e32 v52, v177
	v_mov_b32_e32 v53, v177
	v_mov_b32_e32 v54, v177
	v_mov_b32_e32 v55, v177
	v_mov_b32_e32 v56, v177
	v_mov_b32_e32 v57, v177
	v_mov_b32_e32 v58, v177
	v_mov_b32_e32 v59, v177
	v_mov_b32_e32 v60, v177
	v_mov_b32_e32 v61, v177
	v_mov_b32_e32 v62, v177
	v_mov_b32_e32 v63, v177
	v_mov_b32_e32 v32, v177
	v_mov_b32_e32 v33, v177
	v_mov_b32_e32 v34, v177
	v_mov_b32_e32 v35, v177
	v_mov_b32_e32 v36, v177
	v_mov_b32_e32 v37, v177
	v_mov_b32_e32 v38, v177
	v_mov_b32_e32 v39, v177
	v_mov_b32_e32 v40, v177
	v_mov_b32_e32 v41, v177
	v_mov_b32_e32 v42, v177
	v_mov_b32_e32 v43, v177
	v_mov_b32_e32 v44, v177
	v_mov_b32_e32 v45, v177
	v_mov_b32_e32 v46, v177
	v_mov_b32_e32 v47, v177
	s_mov_b64 s[8:9], 0
	v_mov_b32_e32 v149, 0
	v_mov_b32_e32 v151, 0xff800000
	s_branch .LBB0_726

.LBB0_726:
	s_and_b64 s[10:11], s[8:9], exec
	s_cselect_b32 s10, 0x4600, 0
	s_add_i32 s18, s10, 0
	v_add3_u32 v64, s18, v107, v176
	s_cmp_ge_i32 s13, s12
	s_waitcnt vmcnt(0) lgkmcnt(0)
	ds_write_b128 v64, v[100:103]
	v_add_u32_e32 v64, s18, v111
	s_cselect_b64 s[10:11], -1, 0
	v_add3_u32 v64, v64, v176, s78
	s_and_b64 vcc, exec, s[10:11]
	ds_write2_b64 v64, v[96:97], v[98:99] offset1:1
	s_waitcnt lgkmcnt(0)
	s_barrier
	s_cbranch_vccnz .LBB0_728
	s_add_i32 s20, s6, 64
	s_ashr_i32 s21, s20, 31
	v_mad_i64_i32 v[64:65], s[38:39], s20, v210, v[116:117]
	v_lshl_add_u64 v[66:67], s[20:21], 1, v[118:119]
	global_load_dwordx4 v[100:103], v[64:65], off offset:2816
	global_load_dwordx4 v[96:99], v[66:67], off

.LBB0_744:
	s_ashr_i32 s6, s39, 6
	s_lshr_b32 s12, s39, 6
	s_sub_i32 s6, 7, s6
	s_add_i32 s12, s12, -4
	s_cmpk_lt_i32 s39, 0x100
	s_cselect_b32 s6, s6, s12
	s_lshl_b32 s41, s6, 8
	s_add_i32 s72, s41, s20
	v_or_b32_e32 v102, s72, v129
	s_lshl_b32 s12, s39, 8
	s_and_b32 s14, s12, 0x3800
	s_mov_b32 s15, s7
	v_ashrrev_i32_e32 v103, 31, v102
	v_lshl_add_u64 v[100:101], v[102:103], 0, s[14:15]
	v_mov_b64_e32 v[0:1], s[10:11]
	s_movk_i32 s15, 0x1e00
	v_mad_u64_u32 v[0:1], s[12:13], v100, s15, v[0:1]
	s_lshl_b32 s12, s39, 6
	v_mad_i32_i24 v1, v101, s15, v1
	s_and_b32 s15, s12, 0x1c0
	s_lshl_b32 s12, s15, 1
	s_mov_b32 s13, s7
	v_lshl_add_u64 v[0:1], v[0:1], 0, s[12:13]
	v_lshl_add_u64 v[0:1], v[0:1], 0, v[176:177]
	s_waitcnt vmcnt(0) lgkmcnt(0)
	global_load_dwordx4 v[64:67], v[0:1], off
	global_load_dwordx4 v[68:71], v[0:1], off offset:32
	global_load_dwordx4 v[72:75], v[0:1], off offset:64
	global_load_dwordx4 v[76:79], v[0:1], off offset:96
	s_mul_i32 s13, s14, 0x1e00
	s_add_u32 s76, s26, s13
	s_addc_u32 s80, s27, 0
	s_lshl_b32 s13, s15, 15
	s_add_u32 s15, s23, s13
	s_addc_u32 s73, s77, 0
	s_lshl_b32 s87, s6, 2
	s_or_b32 s13, s87, 3
	s_mov_b64 s[18:19], -1
	s_and_b64 vcc, exec, s[8:9]
	v_lshlrev_b32_e32 v104, 1, v92
	s_cbranch_vccz .LBB0_783
	s_add_u32 s16, s76, s12
	s_addc_u32 s17, s80, 0
	s_lshl_b32 s6, s14, 1
	s_add_u32 s18, s15, s6
	s_addc_u32 s19, s73, 0
	v_mov_b32_e32 v105, v177
	v_lshl_add_u64 v[2:3], s[18:19], 0, v[94:95]
	v_lshl_add_u64 v[2:3], v[2:3], 0, v[104:105]
	s_mov_b32 s6, 0x1800000
	v_lshl_add_u64 v[0:1], s[16:17], 0, v[90:91]
	v_add_co_u32_e32 v4, vcc, s6, v2
	v_lshl_add_u64 v[0:1], v[0:1], 0, v[104:105]
	s_nop 0
	v_addc_co_u32_e32 v5, vcc, 0, v3, vcc
	s_movk_i32 s6, 0x1000
	v_add_co_u32_e32 v6, vcc, s6, v0
	s_mov_b64 s[16:17], 0x1800
	s_nop 0
	v_addc_co_u32_e32 v7, vcc, 0, v1, vcc
	global_load_dwordx4 v[80:83], v[4:5], off
	global_load_dwordx4 v[84:87], v[6:7], off offset:2048
	v_lshl_add_u64 v[106:107], v[0:1], 0, s[16:17]
	s_mov_b64 s[16:17], 0x1800000
	v_mov_b32_e32 v16, v177
	v_mov_b32_e32 v17, v177
	v_lshl_add_u64 v[108:109], v[2:3], 0, s[16:17]
	v_mov_b32_e32 v18, v177
	v_mov_b32_e32 v19, v177
	v_mov_b32_e32 v20, v177
	v_mov_b32_e32 v21, v177
	v_mov_b32_e32 v22, v177
	v_mov_b32_e32 v23, v177
	v_mov_b32_e32 v24, v177
	v_mov_b32_e32 v25, v177
	v_mov_b32_e32 v26, v177
	v_mov_b32_e32 v27, v177
	v_mov_b32_e32 v28, v177
	v_mov_b32_e32 v29, v177
	v_mov_b32_e32 v30, v177
	v_mov_b32_e32 v31, v177
	v_mov_b64_e32 v[0:1], v[16:17]
	s_mov_b32 s85, 0
	s_or_b32 s86, s72, 31
	s_add_i32 s87, s87, 4
	s_add_i32 s89, s38, s41
	s_mov_b64 s[16:17], 0
	v_mov_b32_e32 v120, 0xff800000
	v_mov_b32_e32 v103, 0
	s_mov_b32 s92, 32
	v_mov_b64_e32 v[2:3], v[18:19]
	v_mov_b64_e32 v[4:5], v[20:21]
	v_mov_b64_e32 v[6:7], v[22:23]
	v_mov_b64_e32 v[8:9], v[24:25]
	v_mov_b64_e32 v[10:11], v[26:27]
	v_mov_b64_e32 v[12:13], v[28:29]
	v_mov_b64_e32 v[14:15], v[30:31]
	s_branch .LBB0_748

.LBB0_748:
	s_and_b64 s[18:19], s[16:17], exec
	s_cselect_b32 s6, 0x4600, 0
	s_add_i32 s18, s6, 0
	v_add3_u32 v32, s18, v89, v104
	s_waitcnt vmcnt(0) lgkmcnt(0)
	ds_write_b128 v32, v[84:87]
	v_add_u32_e32 v32, s18, v93
	v_add3_u32 v32, v32, v104, s78
	s_cmp_ge_u32 s85, s13
	ds_write2_b64 v32, v[80:81], v[82:83] offset1:1
	s_waitcnt lgkmcnt(0)
	s_barrier
	s_cbranch_scc1 .LBB0_750
	s_add_i32 s6, s92, 32
	v_mad_u64_u32 v[32:33], s[54:55], s6, v210, v[106:107]
	v_lshl_add_u64 v[34:35], s[6:7], 1, v[108:109]
	global_load_dwordx4 v[84:87], v[32:33], off
	global_load_dwordx4 v[80:83], v[34:35], off

.LBB0_783:
	s_mov_b64 s[16:17], 0x600
	s_and_b64 vcc, exec, s[18:19]
	s_cbranch_vccz .LBB0_743
	s_add_u32 s16, s76, s12
	s_addc_u32 s17, s80, 0
	s_lshl_b32 s6, s14, 1
	s_add_u32 s14, s15, s6
	v_lshl_add_u64 v[0:1], s[16:17], 0, v[90:91]
	v_mov_b32_e32 v105, v177
	s_addc_u32 s15, s73, 0
	v_lshl_add_u64 v[0:1], v[0:1], 0, v[104:105]
	v_lshl_add_u64 v[56:57], v[0:1], 0, s[24:25]
	v_lshl_add_u64 v[0:1], s[14:15], 0, v[94:95]
	v_lshl_add_u64 v[0:1], v[0:1], 0, v[104:105]
	s_mov_b64 s[14:15], 0x800000
	v_lshl_add_u64 v[58:59], v[0:1], 0, s[14:15]
	s_lshl_b32 s6, s13, 6
	v_lshl_add_u64 v[0:1], s[6:7], 1, v[58:59]
	v_mad_u64_u32 v[2:3], s[14:15], s6, v210, v[56:57]
	global_load_dwordx4 v[48:51], v[0:1], off
	global_load_dwordx4 v[52:55], v[2:3], off
	v_mov_b32_e32 v16, v177
	v_mov_b32_e32 v17, v177
	v_mov_b32_e32 v18, v177
	v_mov_b32_e32 v19, v177
	v_mov_b32_e32 v20, v177
	v_mov_b32_e32 v21, v177
	v_mov_b32_e32 v22, v177
	v_mov_b32_e32 v23, v177
	v_mov_b32_e32 v24, v177
	v_mov_b32_e32 v25, v177
	v_mov_b32_e32 v26, v177
	v_mov_b32_e32 v27, v177
	v_mov_b32_e32 v28, v177
	v_mov_b32_e32 v29, v177
	v_mov_b32_e32 v30, v177
	v_mov_b32_e32 v31, v177
	v_mov_b64_e32 v[0:1], v[16:17]
	s_or_b32 s18, s72, 31
	s_add_i32 s6, s41, 0x80
	s_mov_b32 s19, 0
	s_mov_b64 s[14:15], -1
	v_mov_b32_e32 v63, 0
	v_mov_b64_e32 v[2:3], v[18:19]
	v_mov_b64_e32 v[4:5], v[20:21]
	v_mov_b64_e32 v[6:7], v[22:23]
	v_mov_b64_e32 v[8:9], v[24:25]
	v_mov_b64_e32 v[10:11], v[26:27]
	v_mov_b64_e32 v[12:13], v[28:29]
	v_mov_b64_e32 v[14:15], v[30:31]
	s_branch .LBB0_786

.LBB0_788:
	s_or_b64 exec, exec, s[16:17]
	s_mulk_i32 s41, 0xba20
	s_add_i32 s16, s33, s41
	s_add_i32 s17, s16, 0x8c00
	v_mov_b32_e32 v32, s17
	v_mov_b32_e32 v33, s35
	s_add_i32 s17, s16, 0x8c04
	s_waitcnt lgkmcnt(0)
	s_barrier
	ds_read_b128 v[36:39], v32
	ds_read_b128 v[40:43], v32 offset:16
	s_waitcnt vmcnt(0) lgkmcnt(0)
	v_or3_b32 v34, v36, v37, v38
	v_or3_b32 v35, v39, v40, v41
	v_or3_b32 v34, v34, v42, v43
	v_or_b32_e32 v32, v34, v35
	s_nop 0
	v_readfirstlane_b32 s16, v32
	s_cmp_eq_u32 s16, 0
	s_cbranch_scc1 .LBB0_785
	s_cmp_lt_i32 s13, 1
	s_cbranch_scc1 .LBB0_791
	v_mad_u64_u32 v[32:33], s[16:17], s6, v210, v[56:57]
	v_lshl_add_u64 v[34:35], s[6:7], 1, v[58:59]
	global_load_dwordx4 v[52:55], v[32:33], off
	global_load_dwordx4 v[48:51], v[34:35], off
